# GEMM compute-segment edges: s_setprio 1 hoisted above the opening barrier, duplicate lgkmcnt(0) dropped, s_setprio 0 sunk below the closing barrier (3 issue slots off the last-arriving wave per barrie
# speedup vs baseline: 1.0110x; 1.0011x over previous
; #define PG8_STAGE(bufoff, gbase, voff) do { _Pragma("unroll") for (int _i = 0; _i < 2; ++_i) \
;         __builtin_amdgcn_global_load_lds((const unsigned*)((const char*)(gbase) + (voff)[_i]), (LAS unsigned*)(lds + (bufoff) + ldsw + _i * 8192), 16, 0, 0); } while (0)
; #define PG8_LDA(dst, b, h) do { _Pragma("unroll") for (int m = 0; m < 4; ++m) _Pragma("unroll") for (int k = 0; k < 2; ++k) dst[m][k] = *(const LAS bf16x8*)(lds + PG8_SA(b, h) + aoff + m * 2048 + k * 1024); } while (0)
; #define PG8_LDB(dst, b, h) do { _Pragma("unroll") for (int n = 0; n < 2; ++n) _Pragma("unroll") for (int k = 0; k < 2; ++k) dst[n][k] = *(const LAS bf16x8*)(lds + PG8_SB(b, h) + boff + n * 2048 + k * 1024); } while (0)
; #define PG8_MMA(ai, bj, At, Bt) do { __builtin_amdgcn_s_setprio(1); _Pragma("unroll") for (int m = 0; m < 4; ++m) _Pragma("unroll") for (int n = 0; n < 2; ++n) _Pragma("unroll") for (int k = 0; k < 2; ++k) \
;         acc[ai][bj][m][n] = __builtin_amdgcn_mfma_f32_16x16x32_bf16(Bt[n][k], At[m][k], acc[ai][bj][m][n], 0, 0, 0); __builtin_amdgcn_s_setprio(0); } while (0)
; #define PG8_WAIT_V(n) asm volatile("s_waitcnt vmcnt(" #n ")" ::: "memory")
; #define PG8_WAIT_L(n) asm volatile("s_waitcnt lgkmcnt(" #n ")" ::: "memory")
; #define PG8_BAR __builtin_amdgcn_s_barrier()
; #define PG8_SCHED __builtin_amdgcn_sched_barrier(0)
; template <class Epi, bool ALIGN_EPI>
; __device__ __forceinline__ void gemm_phase(LAS unsigned char* lds, const Gemm g, const StaticOrder& S, const Epi& E) {
;     ...
;         for (int t = 0; t < nt; t += 2) {
;             const bool last = (t == nt - 2);
;             const char* a1 = cA + (size_t)(t + 1) * kstep;
;             const char* a2 = last ? nA : cA + (size_t)(t + 2) * kstep; const char* b2 = last ? nB : cB + (size_t)(t + 2) * kstep;
;             const char* a3 = a2 + kstep; const char* b3 = b2 + kstep;
;             PG8_LDB(B0, 0, 0); PG8_LDB(B1, 0, 1); PG8_SCHED; PG8_LDA(At, 0, 0); PG8_STAGE(PG8_SA(1, 1), a1 + hA, voffA);
;             PG8_WAIT_V(8); PG8_WAIT_L(0); PG8_BAR; PG8_MMA(0, 0, At, B0); PG8_MMA(0, 1, At, B1); PG8_BAR; PG8_SCHED;
;             PG8_LDA(At, 0, 1); PG8_STAGE(PG8_SB(0, 0), b2, voffB); PG8_STAGE(PG8_SB(0, 1), b2 + hB, voffB); PG8_STAGE(PG8_SA(0, 0), a2, voffA);
;             PG8_WAIT_V(8); PG8_WAIT_L(0); PG8_BAR; PG8_MMA(1, 0, At, B0); PG8_MMA(1, 1, At, B1); PG8_BAR; PG8_SCHED;
.LBB0_252:
	ds_read_b128 v[168:171], v153
	ds_read_b128 v[172:175], v153 offset:1024
	ds_read_b128 v[176:179], v153 offset:2048
	ds_read_b128 v[180:183], v153 offset:3072
	ds_read_b128 v[184:187], v154
	ds_read_b128 v[188:191], v154 offset:1024
	ds_read_b128 v[194:197], v154 offset:2048
	ds_read_b128 v[198:201], v154 offset:3072
	s_add_u32 s8, s6, 0xfff80080
	s_addc_u32 s9, s7, -1
	s_cmp_eq_u32 s71, 28
	s_cselect_b32 s55, s47, s9
	s_cselect_b32 s54, s67, s8
	s_cselect_b32 s9, s45, s70
	s_cselect_b32 s8, s68, s69
	v_lshl_add_u64 v[234:235], s[6:7], 0, v[136:137]
	s_add_i32 m0, s39, 0xc000
	ds_read_b128 v[202:205], v155
	ds_read_b128 v[206:209], v155 offset:1024
	ds_read_b128 v[210:213], v155 offset:2048
	ds_read_b128 v[214:217], v155 offset:3072
	ds_read_b128 v[218:221], v155 offset:4096
	ds_read_b128 v[222:225], v155 offset:5120
	ds_read_b128 v[226:229], v155 offset:6144
	ds_read_b128 v[230:233], v155 offset:7168
	global_load_lds_dwordx4 v[234:235], off
	v_lshl_add_u64 v[234:235], s[6:7], 0, v[138:139]
	s_add_i32 m0, s39, 0xe000
	s_nop 0
	global_load_lds_dwordx4 v[234:235], off
	s_waitcnt vmcnt(8)
	s_waitcnt lgkmcnt(0)
	s_setprio 1
	s_barrier
	v_mfma_f32_16x16x32_bf16 v[124:127], v[168:171], v[202:205], v[124:127]
	v_mfma_f32_16x16x32_bf16 v[124:127], v[172:175], v[206:209], v[124:127]
	v_mfma_f32_16x16x32_bf16 v[120:123], v[176:179], v[202:205], v[120:123]
	v_mfma_f32_16x16x32_bf16 v[120:123], v[180:183], v[206:209], v[120:123]
	v_mfma_f32_16x16x32_bf16 v[108:111], v[168:171], v[210:213], v[108:111]
	v_mfma_f32_16x16x32_bf16 v[108:111], v[172:175], v[214:217], v[108:111]
	v_mfma_f32_16x16x32_bf16 v[104:107], v[176:179], v[210:213], v[104:107]
	v_mfma_f32_16x16x32_bf16 v[104:107], v[180:183], v[214:217], v[104:107]
	v_mfma_f32_16x16x32_bf16 v[92:95], v[168:171], v[218:221], v[92:95]
	v_mfma_f32_16x16x32_bf16 v[92:95], v[172:175], v[222:225], v[92:95]
	v_mfma_f32_16x16x32_bf16 v[88:91], v[176:179], v[218:221], v[88:91]
	v_mfma_f32_16x16x32_bf16 v[88:91], v[180:183], v[222:225], v[88:91]
	v_mfma_f32_16x16x32_bf16 v[76:79], v[168:171], v[226:229], v[76:79]
	v_mfma_f32_16x16x32_bf16 v[76:79], v[172:175], v[230:233], v[76:79]
	v_mfma_f32_16x16x32_bf16 v[72:75], v[176:179], v[226:229], v[72:75]
	v_mfma_f32_16x16x32_bf16 v[72:75], v[180:183], v[230:233], v[72:75]
	s_setprio 0
	s_setprio 1
	v_mfma_f32_16x16x32_bf16 v[116:119], v[184:187], v[202:205], v[116:119]
	v_mfma_f32_16x16x32_bf16 v[116:119], v[188:191], v[206:209], v[116:119]
	v_mfma_f32_16x16x32_bf16 v[112:115], v[194:197], v[202:205], v[112:115]
	v_mfma_f32_16x16x32_bf16 v[112:115], v[198:201], v[206:209], v[112:115]
	v_mfma_f32_16x16x32_bf16 v[100:103], v[184:187], v[210:213], v[100:103]
	v_mfma_f32_16x16x32_bf16 v[100:103], v[188:191], v[214:217], v[100:103]
	v_mfma_f32_16x16x32_bf16 v[96:99], v[194:197], v[210:213], v[96:99]
	v_mfma_f32_16x16x32_bf16 v[96:99], v[198:201], v[214:217], v[96:99]
	v_mfma_f32_16x16x32_bf16 v[84:87], v[184:187], v[218:221], v[84:87]
	v_mfma_f32_16x16x32_bf16 v[84:87], v[188:191], v[222:225], v[84:87]
	v_mfma_f32_16x16x32_bf16 v[80:83], v[194:197], v[218:221], v[80:83]
	v_mfma_f32_16x16x32_bf16 v[80:83], v[198:201], v[222:225], v[80:83]
	v_mfma_f32_16x16x32_bf16 v[68:71], v[184:187], v[226:229], v[68:71]
	v_mfma_f32_16x16x32_bf16 v[68:71], v[188:191], v[230:233], v[68:71]
	v_mfma_f32_16x16x32_bf16 v[64:67], v[194:197], v[226:229], v[64:67]
	v_mfma_f32_16x16x32_bf16 v[64:67], v[198:201], v[230:233], v[64:67]
	s_barrier
	s_setprio 0
	s_add_i32 s72, s63, s33
	v_lshl_add_u64 v[234:235], s[8:9], 0, v[132:133]
	s_mov_b32 m0, s72
	ds_read_b128 v[202:205], v155 offset:16384
	ds_read_b128 v[206:209], v155 offset:17408
	ds_read_b128 v[210:213], v155 offset:18432
	ds_read_b128 v[214:217], v155 offset:19456
	ds_read_b128 v[218:221], v155 offset:20480
	ds_read_b128 v[222:225], v155 offset:21504
	ds_read_b128 v[226:229], v155 offset:22528
	ds_read_b128 v[230:233], v155 offset:23552
	global_load_lds_dwordx4 v[234:235], off
	s_add_i32 m0, s72, 0x2000
	s_add_u32 s72, s8, 0x80000
	v_lshl_add_u64 v[236:237], s[8:9], 0, v[128:129]
	s_addc_u32 s73, s9, 0
	s_add_i32 s74, s64, s33
	global_load_lds_dwordx4 v[236:237], off
	v_lshl_add_u64 v[238:239], s[72:73], 0, v[132:133]
	s_mov_b32 m0, s74
	v_lshl_add_u64 v[240:241], s[54:55], 0, v[130:131]
	global_load_lds_dwordx4 v[238:239], off
	v_lshl_add_u64 v[238:239], s[72:73], 0, v[128:129]
	s_add_i32 m0, s74, 0x2000
	s_nop 0
	global_load_lds_dwordx4 v[238:239], off
	v_lshl_add_u64 v[238:239], s[54:55], 0, v[134:135]
	s_mov_b32 m0, s39
	s_nop 0
	global_load_lds_dwordx4 v[238:239], off
	s_mov_b32 m0, s53
	s_nop 0
	global_load_lds_dwordx4 v[240:241], off
	s_waitcnt vmcnt(8)
	s_waitcnt lgkmcnt(0)
	s_setprio 1
	s_barrier
; #define PG8_STAGE(bufoff, gbase, voff) do { _Pragma("unroll") for (int _i = 0; _i < 2; ++_i) \
;         __builtin_amdgcn_global_load_lds((const unsigned*)((const char*)(gbase) + (voff)[_i]), (LAS unsigned*)(lds + (bufoff) + ldsw + _i * 8192), 16, 0, 0); } while (0)
; #define PG8_LDA(dst, b, h) do { _Pragma("unroll") for (int m = 0; m < 4; ++m) _Pragma("unroll") for (int k = 0; k < 2; ++k) dst[m][k] = *(const LAS bf16x8*)(lds + PG8_SA(b, h) + aoff + m * 2048 + k * 1024); } while (0)
; #define PG8_LDB(dst, b, h) do { _Pragma("unroll") for (int n = 0; n < 2; ++n) _Pragma("unroll") for (int k = 0; k < 2; ++k) dst[n][k] = *(const LAS bf16x8*)(lds + PG8_SB(b, h) + boff + n * 2048 + k * 1024); } while (0)
; #define PG8_MMA(ai, bj, At, Bt) do { __builtin_amdgcn_s_setprio(1); _Pragma("unroll") for (int m = 0; m < 4; ++m) _Pragma("unroll") for (int n = 0; n < 2; ++n) _Pragma("unroll") for (int k = 0; k < 2; ++k) \
;         acc[ai][bj][m][n] = __builtin_amdgcn_mfma_f32_16x16x32_bf16(Bt[n][k], At[m][k], acc[ai][bj][m][n], 0, 0, 0); __builtin_amdgcn_s_setprio(0); } while (0)
; #define PG8_WAIT_V(n) asm volatile("s_waitcnt vmcnt(" #n ")" ::: "memory")
; #define PG8_WAIT_L(n) asm volatile("s_waitcnt lgkmcnt(" #n ")" ::: "memory")
; #define PG8_BAR __builtin_amdgcn_s_barrier()
; #define PG8_SCHED __builtin_amdgcn_sched_barrier(0)
; template <class Epi, bool ALIGN_EPI>
; __device__ __forceinline__ void gemm_phase(LAS unsigned char* lds, const Gemm g, const StaticOrder& S, const Epi& E) {
;     ...
;             PG8_WAIT_V(8); PG8_WAIT_L(0); PG8_BAR; PG8_MMA(1, 0, At, B0); PG8_MMA(1, 1, At, B1); PG8_BAR; PG8_SCHED;
;             PG8_LDB(B0, 1, 0); PG8_LDB(B1, 1, 1); PG8_SCHED; PG8_LDA(At, 1, 0); PG8_STAGE(PG8_SA(0, 1), a2 + hA, voffA);
;             PG8_WAIT_V(8); PG8_WAIT_L(0); PG8_BAR; PG8_MMA(0, 0, At, B0); PG8_MMA(0, 1, At, B1); PG8_BAR; PG8_SCHED;
	v_mfma_f32_16x16x32_bf16 v[60:63], v[168:171], v[202:205], v[60:63]
	v_mfma_f32_16x16x32_bf16 v[60:63], v[172:175], v[206:209], v[60:63]
	v_mfma_f32_16x16x32_bf16 v[56:59], v[176:179], v[202:205], v[56:59]
	v_mfma_f32_16x16x32_bf16 v[56:59], v[180:183], v[206:209], v[56:59]
	v_mfma_f32_16x16x32_bf16 v[48:51], v[168:171], v[210:213], v[48:51]
	v_mfma_f32_16x16x32_bf16 v[48:51], v[172:175], v[214:217], v[48:51]
	v_mfma_f32_16x16x32_bf16 v[40:43], v[176:179], v[210:213], v[40:43]
	v_mfma_f32_16x16x32_bf16 v[40:43], v[180:183], v[214:217], v[40:43]
	v_mfma_f32_16x16x32_bf16 v[32:35], v[168:171], v[218:221], v[32:35]
	v_mfma_f32_16x16x32_bf16 v[32:35], v[172:175], v[222:225], v[32:35]
	v_mfma_f32_16x16x32_bf16 v[24:27], v[176:179], v[218:221], v[24:27]
	v_mfma_f32_16x16x32_bf16 v[24:27], v[180:183], v[222:225], v[24:27]
	v_mfma_f32_16x16x32_bf16 v[16:19], v[168:171], v[226:229], v[16:19]
	v_mfma_f32_16x16x32_bf16 v[16:19], v[172:175], v[230:233], v[16:19]
	v_mfma_f32_16x16x32_bf16 v[8:11], v[176:179], v[226:229], v[8:11]
	v_mfma_f32_16x16x32_bf16 v[8:11], v[180:183], v[230:233], v[8:11]
	s_setprio 0
	s_setprio 1
	v_mfma_f32_16x16x32_bf16 v[52:55], v[184:187], v[202:205], v[52:55]
	v_mfma_f32_16x16x32_bf16 v[52:55], v[188:191], v[206:209], v[52:55]
	v_mfma_f32_16x16x32_bf16 v[44:47], v[194:197], v[202:205], v[44:47]
	v_mfma_f32_16x16x32_bf16 v[44:47], v[198:201], v[206:209], v[44:47]
	v_mfma_f32_16x16x32_bf16 v[36:39], v[184:187], v[210:213], v[36:39]
	v_mfma_f32_16x16x32_bf16 v[36:39], v[188:191], v[214:217], v[36:39]
	v_mfma_f32_16x16x32_bf16 v[28:31], v[194:197], v[210:213], v[28:31]
	v_mfma_f32_16x16x32_bf16 v[28:31], v[198:201], v[214:217], v[28:31]
	v_mfma_f32_16x16x32_bf16 v[20:23], v[184:187], v[218:221], v[20:23]
	v_mfma_f32_16x16x32_bf16 v[20:23], v[188:191], v[222:225], v[20:23]
	v_mfma_f32_16x16x32_bf16 v[12:15], v[194:197], v[218:221], v[12:15]
	v_mfma_f32_16x16x32_bf16 v[12:15], v[198:201], v[222:225], v[12:15]
	v_mfma_f32_16x16x32_bf16 v[4:7], v[184:187], v[226:229], v[4:7]
	v_mfma_f32_16x16x32_bf16 v[4:7], v[188:191], v[230:233], v[4:7]
	v_mfma_f32_16x16x32_bf16 v[0:3], v[194:197], v[226:229], v[0:3]
	v_mfma_f32_16x16x32_bf16 v[0:3], v[198:201], v[230:233], v[0:3]
	s_barrier
	s_setprio 0
	s_add_i32 s72, 0, 0x18000
	v_add_u32_e32 v167, s72, v149
	s_add_i32 s73, 0, 0x1c000
	ds_read_b128 v[168:171], v167
	ds_read_b128 v[172:175], v167 offset:1024
	ds_read_b128 v[176:179], v167 offset:2048
	ds_read_b128 v[180:183], v167 offset:3072
	v_add_u32_e32 v167, s73, v149
	ds_read_b128 v[184:187], v167
	ds_read_b128 v[188:191], v167 offset:1024
	ds_read_b128 v[194:197], v167 offset:2048
	ds_read_b128 v[198:201], v167 offset:3072
	s_add_u32 s54, s54, 0x80000
	s_addc_u32 s55, s55, 0
	s_mov_b32 m0, s56
	v_lshl_add_u64 v[242:243], s[54:55], 0, v[134:135]
	ds_read_b128 v[202:205], v155 offset:32768
	ds_read_b128 v[206:209], v155 offset:33792
	ds_read_b128 v[210:213], v155 offset:34816
	ds_read_b128 v[214:217], v155 offset:35840
	ds_read_b128 v[218:221], v155 offset:36864
	ds_read_b128 v[222:225], v155 offset:37888
	ds_read_b128 v[226:229], v155 offset:38912
	ds_read_b128 v[230:233], v155 offset:39936
	global_load_lds_dwordx4 v[242:243], off
	v_lshl_add_u64 v[242:243], s[54:55], 0, v[130:131]
	s_mov_b32 m0, s57
	s_nop 0
	global_load_lds_dwordx4 v[242:243], off
	s_waitcnt vmcnt(8)
	s_waitcnt lgkmcnt(0)
	s_setprio 1
	s_barrier
	v_mfma_f32_16x16x32_bf16 v[124:127], v[168:171], v[202:205], v[124:127]
	v_mfma_f32_16x16x32_bf16 v[124:127], v[172:175], v[206:209], v[124:127]
	v_mfma_f32_16x16x32_bf16 v[120:123], v[176:179], v[202:205], v[120:123]
	v_mfma_f32_16x16x32_bf16 v[120:123], v[180:183], v[206:209], v[120:123]
	v_mfma_f32_16x16x32_bf16 v[108:111], v[168:171], v[210:213], v[108:111]
	v_mfma_f32_16x16x32_bf16 v[108:111], v[172:175], v[214:217], v[108:111]
	v_mfma_f32_16x16x32_bf16 v[104:107], v[176:179], v[210:213], v[104:107]
	v_mfma_f32_16x16x32_bf16 v[104:107], v[180:183], v[214:217], v[104:107]
	v_mfma_f32_16x16x32_bf16 v[92:95], v[168:171], v[218:221], v[92:95]
	v_mfma_f32_16x16x32_bf16 v[92:95], v[172:175], v[222:225], v[92:95]
	v_mfma_f32_16x16x32_bf16 v[88:91], v[176:179], v[218:221], v[88:91]
	v_mfma_f32_16x16x32_bf16 v[88:91], v[180:183], v[222:225], v[88:91]
	v_mfma_f32_16x16x32_bf16 v[76:79], v[168:171], v[226:229], v[76:79]
	v_mfma_f32_16x16x32_bf16 v[76:79], v[172:175], v[230:233], v[76:79]
	v_mfma_f32_16x16x32_bf16 v[72:75], v[176:179], v[226:229], v[72:75]
	v_mfma_f32_16x16x32_bf16 v[72:75], v[180:183], v[230:233], v[72:75]
	s_setprio 0
	s_setprio 1
	v_mfma_f32_16x16x32_bf16 v[116:119], v[184:187], v[202:205], v[116:119]
	v_mfma_f32_16x16x32_bf16 v[116:119], v[188:191], v[206:209], v[116:119]
	v_mfma_f32_16x16x32_bf16 v[112:115], v[194:197], v[202:205], v[112:115]
	v_mfma_f32_16x16x32_bf16 v[112:115], v[198:201], v[206:209], v[112:115]
	v_mfma_f32_16x16x32_bf16 v[100:103], v[184:187], v[210:213], v[100:103]
	v_mfma_f32_16x16x32_bf16 v[100:103], v[188:191], v[214:217], v[100:103]
	v_mfma_f32_16x16x32_bf16 v[96:99], v[194:197], v[210:213], v[96:99]
	v_mfma_f32_16x16x32_bf16 v[96:99], v[198:201], v[214:217], v[96:99]
	v_mfma_f32_16x16x32_bf16 v[84:87], v[184:187], v[218:221], v[84:87]
	v_mfma_f32_16x16x32_bf16 v[84:87], v[188:191], v[222:225], v[84:87]
	v_mfma_f32_16x16x32_bf16 v[80:83], v[194:197], v[218:221], v[80:83]
	v_mfma_f32_16x16x32_bf16 v[80:83], v[198:201], v[222:225], v[80:83]
	v_mfma_f32_16x16x32_bf16 v[68:71], v[184:187], v[226:229], v[68:71]
	v_mfma_f32_16x16x32_bf16 v[68:71], v[188:191], v[230:233], v[68:71]
	v_mfma_f32_16x16x32_bf16 v[64:67], v[194:197], v[226:229], v[64:67]
	v_mfma_f32_16x16x32_bf16 v[64:67], v[198:201], v[230:233], v[64:67]
	s_barrier
; #define PG8_STAGE(bufoff, gbase, voff) do { _Pragma("unroll") for (int _i = 0; _i < 2; ++_i) \
;         __builtin_amdgcn_global_load_lds((const unsigned*)((const char*)(gbase) + (voff)[_i]), (LAS unsigned*)(lds + (bufoff) + ldsw + _i * 8192), 16, 0, 0); } while (0)
; #define PG8_LDA(dst, b, h) do { _Pragma("unroll") for (int m = 0; m < 4; ++m) _Pragma("unroll") for (int k = 0; k < 2; ++k) dst[m][k] = *(const LAS bf16x8*)(lds + PG8_SA(b, h) + aoff + m * 2048 + k * 1024); } while (0)
; #define PG8_MMA(ai, bj, At, Bt) do { __builtin_amdgcn_s_setprio(1); _Pragma("unroll") for (int m = 0; m < 4; ++m) _Pragma("unroll") for (int n = 0; n < 2; ++n) _Pragma("unroll") for (int k = 0; k < 2; ++k) \
;         acc[ai][bj][m][n] = __builtin_amdgcn_mfma_f32_16x16x32_bf16(Bt[n][k], At[m][k], acc[ai][bj][m][n], 0, 0, 0); __builtin_amdgcn_s_setprio(0); } while (0)
; #define PG8_WAIT_V(n) asm volatile("s_waitcnt vmcnt(" #n ")" ::: "memory")
; #define PG8_WAIT_L(n) asm volatile("s_waitcnt lgkmcnt(" #n ")" ::: "memory")
; #define PG8_BAR __builtin_amdgcn_s_barrier()
; #define PG8_SCHED __builtin_amdgcn_sched_barrier(0)
; template <class Epi, bool ALIGN_EPI>
; __device__ __forceinline__ void gemm_phase(LAS unsigned char* lds, const Gemm g, const StaticOrder& S, const Epi& E) {
;     ...
;             PG8_LDA(At, 1, 1); PG8_STAGE(PG8_SB(1, 0), b3, voffB); PG8_STAGE(PG8_SB(1, 1), b3 + hB, voffB); PG8_STAGE(PG8_SA(1, 0), a3, voffA);
;             PG8_WAIT_V(8); PG8_WAIT_L(0); PG8_BAR; PG8_MMA(1, 0, At, B0); PG8_MMA(1, 1, At, B1); PG8_BAR; PG8_SCHED;
;         }
;         if constexpr (ALIGN_EPI) { if (wr == 0) PG8_BAR; }
	s_setprio 0
	s_add_i32 s54, s72, s33
	v_lshl_add_u64 v[234:235], v[234:235], 0, s[20:21]
	s_mov_b32 m0, s54
	ds_read_b128 v[202:205], v155 offset:49152
	ds_read_b128 v[206:209], v155 offset:50176
	ds_read_b128 v[210:213], v155 offset:51200
	ds_read_b128 v[214:217], v155 offset:52224
	ds_read_b128 v[218:221], v155 offset:53248
	ds_read_b128 v[222:225], v155 offset:54272
	ds_read_b128 v[226:229], v155 offset:55296
	ds_read_b128 v[230:233], v155 offset:56320
	global_load_lds_dwordx4 v[234:235], off
	s_add_i32 m0, s54, 0x2000
	s_add_u32 s8, s8, 0x80080
	v_lshl_add_u64 v[234:235], v[236:237], 0, s[20:21]
	s_addc_u32 s9, s9, 0
	s_add_i32 s54, s73, s33
	global_load_lds_dwordx4 v[234:235], off
	v_lshl_add_u64 v[234:235], s[8:9], 0, v[132:133]
	s_mov_b32 m0, s54
	s_nop 0
	global_load_lds_dwordx4 v[234:235], off
	v_lshl_add_u64 v[234:235], s[8:9], 0, v[128:129]
	s_add_i32 m0, s54, 0x2000
	s_nop 0
	global_load_lds_dwordx4 v[234:235], off
	v_lshl_add_u64 v[234:235], v[238:239], 0, s[20:21]
	s_mov_b32 m0, s60
	s_nop 0
	global_load_lds_dwordx4 v[234:235], off
	v_lshl_add_u64 v[234:235], v[240:241], 0, s[20:21]
	s_mov_b32 m0, s61
	s_nop 0
	global_load_lds_dwordx4 v[234:235], off
	s_waitcnt vmcnt(8)
	s_waitcnt lgkmcnt(0)
	s_setprio 1
	s_barrier
	v_mfma_f32_16x16x32_bf16 v[60:63], v[168:171], v[202:205], v[60:63]
	v_mfma_f32_16x16x32_bf16 v[60:63], v[172:175], v[206:209], v[60:63]
	v_mfma_f32_16x16x32_bf16 v[56:59], v[176:179], v[202:205], v[56:59]
	v_mfma_f32_16x16x32_bf16 v[56:59], v[180:183], v[206:209], v[56:59]
	v_mfma_f32_16x16x32_bf16 v[48:51], v[168:171], v[210:213], v[48:51]
	v_mfma_f32_16x16x32_bf16 v[48:51], v[172:175], v[214:217], v[48:51]
	v_mfma_f32_16x16x32_bf16 v[40:43], v[176:179], v[210:213], v[40:43]
	v_mfma_f32_16x16x32_bf16 v[40:43], v[180:183], v[214:217], v[40:43]
	v_mfma_f32_16x16x32_bf16 v[32:35], v[168:171], v[218:221], v[32:35]
	v_mfma_f32_16x16x32_bf16 v[32:35], v[172:175], v[222:225], v[32:35]
	v_mfma_f32_16x16x32_bf16 v[24:27], v[176:179], v[218:221], v[24:27]
	v_mfma_f32_16x16x32_bf16 v[24:27], v[180:183], v[222:225], v[24:27]
	v_mfma_f32_16x16x32_bf16 v[16:19], v[168:171], v[226:229], v[16:19]
	v_mfma_f32_16x16x32_bf16 v[16:19], v[172:175], v[230:233], v[16:19]
	v_mfma_f32_16x16x32_bf16 v[8:11], v[176:179], v[226:229], v[8:11]
	v_mfma_f32_16x16x32_bf16 v[8:11], v[180:183], v[230:233], v[8:11]
	s_setprio 0
	s_setprio 1
	v_mfma_f32_16x16x32_bf16 v[52:55], v[184:187], v[202:205], v[52:55]
	v_mfma_f32_16x16x32_bf16 v[52:55], v[188:191], v[206:209], v[52:55]
	v_mfma_f32_16x16x32_bf16 v[44:47], v[194:197], v[202:205], v[44:47]
	v_mfma_f32_16x16x32_bf16 v[44:47], v[198:201], v[206:209], v[44:47]
	v_mfma_f32_16x16x32_bf16 v[36:39], v[184:187], v[210:213], v[36:39]
	v_mfma_f32_16x16x32_bf16 v[36:39], v[188:191], v[214:217], v[36:39]
	v_mfma_f32_16x16x32_bf16 v[28:31], v[194:197], v[210:213], v[28:31]
	v_mfma_f32_16x16x32_bf16 v[28:31], v[198:201], v[214:217], v[28:31]
	v_mfma_f32_16x16x32_bf16 v[20:23], v[184:187], v[218:221], v[20:23]
	v_mfma_f32_16x16x32_bf16 v[20:23], v[188:191], v[222:225], v[20:23]
	v_mfma_f32_16x16x32_bf16 v[12:15], v[194:197], v[218:221], v[12:15]
	v_mfma_f32_16x16x32_bf16 v[12:15], v[198:201], v[222:225], v[12:15]
	v_mfma_f32_16x16x32_bf16 v[4:7], v[184:187], v[226:229], v[4:7]
	v_mfma_f32_16x16x32_bf16 v[4:7], v[188:191], v[230:233], v[4:7]
	v_mfma_f32_16x16x32_bf16 v[0:3], v[194:197], v[226:229], v[0:3]
	v_mfma_f32_16x16x32_bf16 v[0:3], v[198:201], v[230:233], v[0:3]
	s_barrier
	s_setprio 0
	s_add_i32 s71, s71, 2
	s_add_u32 s6, s6, 0x100
	s_addc_u32 s7, s7, 0
	s_add_u32 s69, s69, 0x100
	s_addc_u32 s70, s70, 0
	s_cmp_gt_u32 s71, 29
	s_cbranch_scc0 .LBB0_252
	s_and_b64 vcc, exec, s[22:23]
	s_cbranch_vccz .LBB0_255
	s_barrier

; #define PG8_STAGE(bufoff, gbase, voff) do { _Pragma("unroll") for (int _i = 0; _i < 2; ++_i) \
;         __builtin_amdgcn_global_load_lds((const unsigned*)((const char*)(gbase) + (voff)[_i]), (LAS unsigned*)(lds + (bufoff) + ldsw + _i * 8192), 16, 0, 0); } while (0)
; #define PG8_LDA(dst, b, h) do { _Pragma("unroll") for (int m = 0; m < 4; ++m) _Pragma("unroll") for (int k = 0; k < 2; ++k) dst[m][k] = *(const LAS bf16x8*)(lds + PG8_SA(b, h) + aoff + m * 2048 + k * 1024); } while (0)
; #define PG8_LDB(dst, b, h) do { _Pragma("unroll") for (int n = 0; n < 2; ++n) _Pragma("unroll") for (int k = 0; k < 2; ++k) dst[n][k] = *(const LAS bf16x8*)(lds + PG8_SB(b, h) + boff + n * 2048 + k * 1024); } while (0)
; #define PG8_MMA(ai, bj, At, Bt) do { __builtin_amdgcn_s_setprio(1); _Pragma("unroll") for (int m = 0; m < 4; ++m) _Pragma("unroll") for (int n = 0; n < 2; ++n) _Pragma("unroll") for (int k = 0; k < 2; ++k) \
;         acc[ai][bj][m][n] = __builtin_amdgcn_mfma_f32_16x16x32_bf16(Bt[n][k], At[m][k], acc[ai][bj][m][n], 0, 0, 0); __builtin_amdgcn_s_setprio(0); } while (0)
; #define PG8_WAIT_V(n) asm volatile("s_waitcnt vmcnt(" #n ")" ::: "memory")
; #define PG8_WAIT_L(n) asm volatile("s_waitcnt lgkmcnt(" #n ")" ::: "memory")
; #define PG8_BAR __builtin_amdgcn_s_barrier()
; #define PG8_SCHED __builtin_amdgcn_sched_barrier(0)
; template <class Epi, bool ALIGN_EPI>
; __device__ __forceinline__ void gemm_phase(LAS unsigned char* lds, const Gemm g, const StaticOrder& S, const Epi& E) {
;     ...
;         for (int t = 0; t < nt; t += 2) {
;             const bool last = (t == nt - 2);
;             const char* a1 = cA + (size_t)(t + 1) * kstep;
;             const char* a2 = last ? nA : cA + (size_t)(t + 2) * kstep; const char* b2 = last ? nB : cB + (size_t)(t + 2) * kstep;
;             const char* a3 = a2 + kstep; const char* b3 = b2 + kstep;
;             PG8_LDB(B0, 0, 0); PG8_LDB(B1, 0, 1); PG8_SCHED; PG8_LDA(At, 0, 0); PG8_STAGE(PG8_SA(1, 1), a1 + hA, voffA);
;             PG8_WAIT_V(8); PG8_WAIT_L(0); PG8_BAR; PG8_MMA(0, 0, At, B0); PG8_MMA(0, 1, At, B1); PG8_BAR; PG8_SCHED;
;             PG8_LDA(At, 0, 1); PG8_STAGE(PG8_SB(0, 0), b2, voffB); PG8_STAGE(PG8_SB(0, 1), b2 + hB, voffB); PG8_STAGE(PG8_SA(0, 0), a2, voffA);
;             PG8_WAIT_V(8); PG8_WAIT_L(0); PG8_BAR; PG8_MMA(1, 0, At, B0); PG8_MMA(1, 1, At, B1); PG8_BAR; PG8_SCHED;
.LBB0_385:
	ds_read_b128 v[152:155], v149
	ds_read_b128 v[156:159], v149 offset:1024
	ds_read_b128 v[160:163], v149 offset:2048
	ds_read_b128 v[164:167], v149 offset:3072
	ds_read_b128 v[168:171], v150
	ds_read_b128 v[172:175], v150 offset:1024
	ds_read_b128 v[176:179], v150 offset:2048
	ds_read_b128 v[180:183], v150 offset:3072
	s_add_u32 s40, s36, 0xfff80080
	s_addc_u32 s41, s37, -1
	s_cmp_eq_u32 s61, 4
	s_cselect_b32 s43, s27, s41
	s_cselect_b32 s42, s57, s40
	s_cselect_b32 s41, s25, s60
	s_cselect_b32 s40, s58, s59
	v_lshl_add_u64 v[144:145], s[36:37], 0, v[136:137]
	s_add_i32 m0, s35, 0xc000
	ds_read_b128 v[184:187], v151
	ds_read_b128 v[188:191], v151 offset:1024
	ds_read_b128 v[194:197], v151 offset:2048
	ds_read_b128 v[198:201], v151 offset:3072
	ds_read_b128 v[202:205], v151 offset:4096
	ds_read_b128 v[206:209], v151 offset:5120
	ds_read_b128 v[210:213], v151 offset:6144
	ds_read_b128 v[214:217], v151 offset:7168
	global_load_lds_dwordx4 v[144:145], off
	v_lshl_add_u64 v[144:145], s[36:37], 0, v[138:139]
	s_add_i32 m0, s35, 0xe000
	s_nop 0
	global_load_lds_dwordx4 v[144:145], off
	s_waitcnt vmcnt(8)
	s_waitcnt lgkmcnt(0)
	s_setprio 1
	s_barrier
	v_mfma_f32_16x16x32_bf16 v[124:127], v[152:155], v[184:187], v[124:127]
	v_mfma_f32_16x16x32_bf16 v[124:127], v[156:159], v[188:191], v[124:127]
	v_mfma_f32_16x16x32_bf16 v[120:123], v[160:163], v[184:187], v[120:123]
	v_mfma_f32_16x16x32_bf16 v[120:123], v[164:167], v[188:191], v[120:123]
	v_mfma_f32_16x16x32_bf16 v[116:119], v[152:155], v[194:197], v[116:119]
	v_mfma_f32_16x16x32_bf16 v[116:119], v[156:159], v[198:201], v[116:119]
	v_mfma_f32_16x16x32_bf16 v[108:111], v[160:163], v[194:197], v[108:111]
	v_mfma_f32_16x16x32_bf16 v[108:111], v[164:167], v[198:201], v[108:111]
	v_mfma_f32_16x16x32_bf16 v[100:103], v[152:155], v[202:205], v[100:103]
	v_mfma_f32_16x16x32_bf16 v[100:103], v[156:159], v[206:209], v[100:103]
	v_mfma_f32_16x16x32_bf16 v[92:95], v[160:163], v[202:205], v[92:95]
	v_mfma_f32_16x16x32_bf16 v[92:95], v[164:167], v[206:209], v[92:95]
	v_mfma_f32_16x16x32_bf16 v[84:87], v[152:155], v[210:213], v[84:87]
	v_mfma_f32_16x16x32_bf16 v[84:87], v[156:159], v[214:217], v[84:87]
	v_mfma_f32_16x16x32_bf16 v[76:79], v[160:163], v[210:213], v[76:79]
	v_mfma_f32_16x16x32_bf16 v[76:79], v[164:167], v[214:217], v[76:79]
	s_setprio 0
	s_setprio 1
	v_mfma_f32_16x16x32_bf16 v[112:115], v[168:171], v[184:187], v[112:115]
	v_mfma_f32_16x16x32_bf16 v[112:115], v[172:175], v[188:191], v[112:115]
	v_mfma_f32_16x16x32_bf16 v[104:107], v[176:179], v[184:187], v[104:107]
	v_mfma_f32_16x16x32_bf16 v[104:107], v[180:183], v[188:191], v[104:107]
	v_mfma_f32_16x16x32_bf16 v[96:99], v[168:171], v[194:197], v[96:99]
	v_mfma_f32_16x16x32_bf16 v[96:99], v[172:175], v[198:201], v[96:99]
	v_mfma_f32_16x16x32_bf16 v[88:91], v[176:179], v[194:197], v[88:91]
	v_mfma_f32_16x16x32_bf16 v[88:91], v[180:183], v[198:201], v[88:91]
	v_mfma_f32_16x16x32_bf16 v[80:83], v[168:171], v[202:205], v[80:83]
	v_mfma_f32_16x16x32_bf16 v[80:83], v[172:175], v[206:209], v[80:83]
	v_mfma_f32_16x16x32_bf16 v[72:75], v[176:179], v[202:205], v[72:75]
	v_mfma_f32_16x16x32_bf16 v[72:75], v[180:183], v[206:209], v[72:75]
	v_mfma_f32_16x16x32_bf16 v[68:71], v[168:171], v[210:213], v[68:71]
	v_mfma_f32_16x16x32_bf16 v[68:71], v[172:175], v[214:217], v[68:71]
	v_mfma_f32_16x16x32_bf16 v[64:67], v[176:179], v[210:213], v[64:67]
	v_mfma_f32_16x16x32_bf16 v[64:67], v[180:183], v[214:217], v[64:67]
	s_barrier
	s_setprio 0
	s_add_i32 s62, s53, s45
	v_lshl_add_u64 v[144:145], s[40:41], 0, v[132:133]
	s_mov_b32 m0, s62
	ds_read_b128 v[184:187], v151 offset:16384
	ds_read_b128 v[188:191], v151 offset:17408
	ds_read_b128 v[194:197], v151 offset:18432
	ds_read_b128 v[198:201], v151 offset:19456
	ds_read_b128 v[202:205], v151 offset:20480
	ds_read_b128 v[206:209], v151 offset:21504
	ds_read_b128 v[210:213], v151 offset:22528
	ds_read_b128 v[214:217], v151 offset:23552
	global_load_lds_dwordx4 v[144:145], off
	s_add_i32 m0, s62, 0x2000
	s_add_u32 s62, s40, 0x20000
	v_lshl_add_u64 v[218:219], s[40:41], 0, v[128:129]
	s_addc_u32 s63, s41, 0
	s_add_i32 s64, s54, s45
	global_load_lds_dwordx4 v[218:219], off
	v_lshl_add_u64 v[220:221], s[62:63], 0, v[132:133]
	s_mov_b32 m0, s64
	v_lshl_add_u64 v[222:223], s[42:43], 0, v[130:131]
	global_load_lds_dwordx4 v[220:221], off
	v_lshl_add_u64 v[220:221], s[62:63], 0, v[128:129]
	s_add_i32 m0, s64, 0x2000
	s_nop 0
	global_load_lds_dwordx4 v[220:221], off
	v_lshl_add_u64 v[220:221], s[42:43], 0, v[134:135]
	s_mov_b32 m0, s35
	s_nop 0
	global_load_lds_dwordx4 v[220:221], off
	s_mov_b32 m0, s47
	s_nop 0
	global_load_lds_dwordx4 v[222:223], off
	s_waitcnt vmcnt(8)
	s_waitcnt lgkmcnt(0)
	s_setprio 1
	s_barrier
; #define PG8_STAGE(bufoff, gbase, voff) do { _Pragma("unroll") for (int _i = 0; _i < 2; ++_i) \
;         __builtin_amdgcn_global_load_lds((const unsigned*)((const char*)(gbase) + (voff)[_i]), (LAS unsigned*)(lds + (bufoff) + ldsw + _i * 8192), 16, 0, 0); } while (0)
; #define PG8_LDA(dst, b, h) do { _Pragma("unroll") for (int m = 0; m < 4; ++m) _Pragma("unroll") for (int k = 0; k < 2; ++k) dst[m][k] = *(const LAS bf16x8*)(lds + PG8_SA(b, h) + aoff + m * 2048 + k * 1024); } while (0)
; #define PG8_LDB(dst, b, h) do { _Pragma("unroll") for (int n = 0; n < 2; ++n) _Pragma("unroll") for (int k = 0; k < 2; ++k) dst[n][k] = *(const LAS bf16x8*)(lds + PG8_SB(b, h) + boff + n * 2048 + k * 1024); } while (0)
; #define PG8_MMA(ai, bj, At, Bt) do { __builtin_amdgcn_s_setprio(1); _Pragma("unroll") for (int m = 0; m < 4; ++m) _Pragma("unroll") for (int n = 0; n < 2; ++n) _Pragma("unroll") for (int k = 0; k < 2; ++k) \
;         acc[ai][bj][m][n] = __builtin_amdgcn_mfma_f32_16x16x32_bf16(Bt[n][k], At[m][k], acc[ai][bj][m][n], 0, 0, 0); __builtin_amdgcn_s_setprio(0); } while (0)
; #define PG8_WAIT_V(n) asm volatile("s_waitcnt vmcnt(" #n ")" ::: "memory")
; #define PG8_WAIT_L(n) asm volatile("s_waitcnt lgkmcnt(" #n ")" ::: "memory")
; #define PG8_BAR __builtin_amdgcn_s_barrier()
; #define PG8_SCHED __builtin_amdgcn_sched_barrier(0)
; template <class Epi, bool ALIGN_EPI>
; __device__ __forceinline__ void gemm_phase(LAS unsigned char* lds, const Gemm g, const StaticOrder& S, const Epi& E) {
;     ...
;             PG8_WAIT_V(8); PG8_WAIT_L(0); PG8_BAR; PG8_MMA(1, 0, At, B0); PG8_MMA(1, 1, At, B1); PG8_BAR; PG8_SCHED;
;             PG8_LDB(B0, 1, 0); PG8_LDB(B1, 1, 1); PG8_SCHED; PG8_LDA(At, 1, 0); PG8_STAGE(PG8_SA(0, 1), a2 + hA, voffA);
;             PG8_WAIT_V(8); PG8_WAIT_L(0); PG8_BAR; PG8_MMA(0, 0, At, B0); PG8_MMA(0, 1, At, B1); PG8_BAR; PG8_SCHED;
	v_mfma_f32_16x16x32_bf16 v[60:63], v[152:155], v[184:187], v[60:63]
	v_mfma_f32_16x16x32_bf16 v[60:63], v[156:159], v[188:191], v[60:63]
	v_mfma_f32_16x16x32_bf16 v[56:59], v[160:163], v[184:187], v[56:59]
	v_mfma_f32_16x16x32_bf16 v[56:59], v[164:167], v[188:191], v[56:59]
	v_mfma_f32_16x16x32_bf16 v[52:55], v[152:155], v[194:197], v[52:55]
	v_mfma_f32_16x16x32_bf16 v[52:55], v[156:159], v[198:201], v[52:55]
	v_mfma_f32_16x16x32_bf16 v[44:47], v[160:163], v[194:197], v[44:47]
	v_mfma_f32_16x16x32_bf16 v[44:47], v[164:167], v[198:201], v[44:47]
	v_mfma_f32_16x16x32_bf16 v[36:39], v[152:155], v[202:205], v[36:39]
	v_mfma_f32_16x16x32_bf16 v[36:39], v[156:159], v[206:209], v[36:39]
	v_mfma_f32_16x16x32_bf16 v[28:31], v[160:163], v[202:205], v[28:31]
	v_mfma_f32_16x16x32_bf16 v[28:31], v[164:167], v[206:209], v[28:31]
	v_mfma_f32_16x16x32_bf16 v[20:23], v[152:155], v[210:213], v[20:23]
	v_mfma_f32_16x16x32_bf16 v[20:23], v[156:159], v[214:217], v[20:23]
	v_mfma_f32_16x16x32_bf16 v[12:15], v[160:163], v[210:213], v[12:15]
	v_mfma_f32_16x16x32_bf16 v[12:15], v[164:167], v[214:217], v[12:15]
	s_setprio 0
	s_setprio 1
	v_mfma_f32_16x16x32_bf16 v[48:51], v[168:171], v[184:187], v[48:51]
	v_mfma_f32_16x16x32_bf16 v[48:51], v[172:175], v[188:191], v[48:51]
	v_mfma_f32_16x16x32_bf16 v[40:43], v[176:179], v[184:187], v[40:43]
	v_mfma_f32_16x16x32_bf16 v[40:43], v[180:183], v[188:191], v[40:43]
	v_mfma_f32_16x16x32_bf16 v[32:35], v[168:171], v[194:197], v[32:35]
	v_mfma_f32_16x16x32_bf16 v[32:35], v[172:175], v[198:201], v[32:35]
	v_mfma_f32_16x16x32_bf16 v[24:27], v[176:179], v[194:197], v[24:27]
	v_mfma_f32_16x16x32_bf16 v[24:27], v[180:183], v[198:201], v[24:27]
	v_mfma_f32_16x16x32_bf16 v[16:19], v[168:171], v[202:205], v[16:19]
	v_mfma_f32_16x16x32_bf16 v[16:19], v[172:175], v[206:209], v[16:19]
	v_mfma_f32_16x16x32_bf16 v[8:11], v[176:179], v[202:205], v[8:11]
	v_mfma_f32_16x16x32_bf16 v[8:11], v[180:183], v[206:209], v[8:11]
	v_mfma_f32_16x16x32_bf16 v[4:7], v[168:171], v[210:213], v[4:7]
	v_mfma_f32_16x16x32_bf16 v[4:7], v[172:175], v[214:217], v[4:7]
	v_mfma_f32_16x16x32_bf16 v[0:3], v[176:179], v[210:213], v[0:3]
	v_mfma_f32_16x16x32_bf16 v[0:3], v[180:183], v[214:217], v[0:3]
	s_barrier
	s_setprio 0
	s_add_i32 s62, 0, 0x18000
	s_add_i32 s63, 0, 0x1c000
	v_add_u32_e32 v164, s62, v147
	v_add_u32_e32 v180, s63, v147
	ds_read_b128 v[152:155], v164
	ds_read_b128 v[156:159], v164 offset:1024
	ds_read_b128 v[160:163], v164 offset:2048
	ds_read_b128 v[164:167], v164 offset:3072
	ds_read_b128 v[168:171], v180
	ds_read_b128 v[172:175], v180 offset:1024
	ds_read_b128 v[176:179], v180 offset:2048
	ds_read_b128 v[180:183], v180 offset:3072
	s_add_u32 s42, s42, 0x80000
	s_addc_u32 s43, s43, 0
	s_mov_b32 m0, s48
	v_lshl_add_u64 v[224:225], s[42:43], 0, v[134:135]
	ds_read_b128 v[184:187], v151 offset:32768
	ds_read_b128 v[188:191], v151 offset:33792
	ds_read_b128 v[194:197], v151 offset:34816
	ds_read_b128 v[198:201], v151 offset:35840
	ds_read_b128 v[202:205], v151 offset:36864
	ds_read_b128 v[206:209], v151 offset:37888
	ds_read_b128 v[210:213], v151 offset:38912
	ds_read_b128 v[214:217], v151 offset:39936
	global_load_lds_dwordx4 v[224:225], off
	v_lshl_add_u64 v[224:225], s[42:43], 0, v[130:131]
	s_mov_b32 m0, s49
	s_nop 0
	global_load_lds_dwordx4 v[224:225], off
	s_waitcnt vmcnt(8)
	s_waitcnt lgkmcnt(0)
	s_setprio 1
	s_barrier
	v_mfma_f32_16x16x32_bf16 v[124:127], v[152:155], v[184:187], v[124:127]
	v_mfma_f32_16x16x32_bf16 v[124:127], v[156:159], v[188:191], v[124:127]
	v_mfma_f32_16x16x32_bf16 v[120:123], v[160:163], v[184:187], v[120:123]
	v_mfma_f32_16x16x32_bf16 v[120:123], v[164:167], v[188:191], v[120:123]
	v_mfma_f32_16x16x32_bf16 v[116:119], v[152:155], v[194:197], v[116:119]
	v_mfma_f32_16x16x32_bf16 v[116:119], v[156:159], v[198:201], v[116:119]
	v_mfma_f32_16x16x32_bf16 v[108:111], v[160:163], v[194:197], v[108:111]
	v_mfma_f32_16x16x32_bf16 v[108:111], v[164:167], v[198:201], v[108:111]
	v_mfma_f32_16x16x32_bf16 v[100:103], v[152:155], v[202:205], v[100:103]
	v_mfma_f32_16x16x32_bf16 v[100:103], v[156:159], v[206:209], v[100:103]
	v_mfma_f32_16x16x32_bf16 v[92:95], v[160:163], v[202:205], v[92:95]
	v_mfma_f32_16x16x32_bf16 v[92:95], v[164:167], v[206:209], v[92:95]
	v_mfma_f32_16x16x32_bf16 v[84:87], v[152:155], v[210:213], v[84:87]
	v_mfma_f32_16x16x32_bf16 v[84:87], v[156:159], v[214:217], v[84:87]
	v_mfma_f32_16x16x32_bf16 v[76:79], v[160:163], v[210:213], v[76:79]
	v_mfma_f32_16x16x32_bf16 v[76:79], v[164:167], v[214:217], v[76:79]
	s_setprio 0
	s_setprio 1
	v_mfma_f32_16x16x32_bf16 v[112:115], v[168:171], v[184:187], v[112:115]
	v_mfma_f32_16x16x32_bf16 v[112:115], v[172:175], v[188:191], v[112:115]
	v_mfma_f32_16x16x32_bf16 v[104:107], v[176:179], v[184:187], v[104:107]
	v_mfma_f32_16x16x32_bf16 v[104:107], v[180:183], v[188:191], v[104:107]
	v_mfma_f32_16x16x32_bf16 v[96:99], v[168:171], v[194:197], v[96:99]
	v_mfma_f32_16x16x32_bf16 v[96:99], v[172:175], v[198:201], v[96:99]
	v_mfma_f32_16x16x32_bf16 v[88:91], v[176:179], v[194:197], v[88:91]
	v_mfma_f32_16x16x32_bf16 v[88:91], v[180:183], v[198:201], v[88:91]
	v_mfma_f32_16x16x32_bf16 v[80:83], v[168:171], v[202:205], v[80:83]
	v_mfma_f32_16x16x32_bf16 v[80:83], v[172:175], v[206:209], v[80:83]
	v_mfma_f32_16x16x32_bf16 v[72:75], v[176:179], v[202:205], v[72:75]
	v_mfma_f32_16x16x32_bf16 v[72:75], v[180:183], v[206:209], v[72:75]
	v_mfma_f32_16x16x32_bf16 v[68:71], v[168:171], v[210:213], v[68:71]
	v_mfma_f32_16x16x32_bf16 v[68:71], v[172:175], v[214:217], v[68:71]
	v_mfma_f32_16x16x32_bf16 v[64:67], v[176:179], v[210:213], v[64:67]
	v_mfma_f32_16x16x32_bf16 v[64:67], v[180:183], v[214:217], v[64:67]
	s_barrier
; #define PG8_STAGE(bufoff, gbase, voff) do { _Pragma("unroll") for (int _i = 0; _i < 2; ++_i) \
;         __builtin_amdgcn_global_load_lds((const unsigned*)((const char*)(gbase) + (voff)[_i]), (LAS unsigned*)(lds + (bufoff) + ldsw + _i * 8192), 16, 0, 0); } while (0)
; #define PG8_LDA(dst, b, h) do { _Pragma("unroll") for (int m = 0; m < 4; ++m) _Pragma("unroll") for (int k = 0; k < 2; ++k) dst[m][k] = *(const LAS bf16x8*)(lds + PG8_SA(b, h) + aoff + m * 2048 + k * 1024); } while (0)
; #define PG8_MMA(ai, bj, At, Bt) do { __builtin_amdgcn_s_setprio(1); _Pragma("unroll") for (int m = 0; m < 4; ++m) _Pragma("unroll") for (int n = 0; n < 2; ++n) _Pragma("unroll") for (int k = 0; k < 2; ++k) \
;         acc[ai][bj][m][n] = __builtin_amdgcn_mfma_f32_16x16x32_bf16(Bt[n][k], At[m][k], acc[ai][bj][m][n], 0, 0, 0); __builtin_amdgcn_s_setprio(0); } while (0)
; #define PG8_WAIT_V(n) asm volatile("s_waitcnt vmcnt(" #n ")" ::: "memory")
; #define PG8_WAIT_L(n) asm volatile("s_waitcnt lgkmcnt(" #n ")" ::: "memory")
; #define PG8_BAR __builtin_amdgcn_s_barrier()
; #define PG8_SCHED __builtin_amdgcn_sched_barrier(0)
; template <class Epi, bool ALIGN_EPI>
; __device__ __forceinline__ void gemm_phase(LAS unsigned char* lds, const Gemm g, const StaticOrder& S, const Epi& E) {
;     ...
;             PG8_LDA(At, 1, 1); PG8_STAGE(PG8_SB(1, 0), b3, voffB); PG8_STAGE(PG8_SB(1, 1), b3 + hB, voffB); PG8_STAGE(PG8_SA(1, 0), a3, voffA);
;             PG8_WAIT_V(8); PG8_WAIT_L(0); PG8_BAR; PG8_MMA(1, 0, At, B0); PG8_MMA(1, 1, At, B1); PG8_BAR; PG8_SCHED;
;         }
;         if constexpr (ALIGN_EPI) { if (wr == 0) PG8_BAR; }
	s_setprio 0
	s_add_i32 s42, s62, s45
	v_lshl_add_u64 v[144:145], v[144:145], 0, s[18:19]
	s_mov_b32 m0, s42
	ds_read_b128 v[184:187], v151 offset:49152
	ds_read_b128 v[188:191], v151 offset:50176
	ds_read_b128 v[194:197], v151 offset:51200
	ds_read_b128 v[198:201], v151 offset:52224
	ds_read_b128 v[202:205], v151 offset:53248
	ds_read_b128 v[206:209], v151 offset:54272
	ds_read_b128 v[210:213], v151 offset:55296
	ds_read_b128 v[214:217], v151 offset:56320
	global_load_lds_dwordx4 v[144:145], off
	s_add_i32 m0, s42, 0x2000
	s_add_u32 s40, s40, 0x20080
	v_lshl_add_u64 v[144:145], v[218:219], 0, s[18:19]
	s_addc_u32 s41, s41, 0
	s_add_i32 s42, s63, s45
	global_load_lds_dwordx4 v[144:145], off
	v_lshl_add_u64 v[144:145], s[40:41], 0, v[132:133]
	s_mov_b32 m0, s42
	s_nop 0
	global_load_lds_dwordx4 v[144:145], off
	v_lshl_add_u64 v[144:145], s[40:41], 0, v[128:129]
	s_add_i32 m0, s42, 0x2000
	s_nop 0
	global_load_lds_dwordx4 v[144:145], off
	v_lshl_add_u64 v[144:145], v[220:221], 0, s[18:19]
	s_mov_b32 m0, s50
	s_nop 0
	global_load_lds_dwordx4 v[144:145], off
	v_lshl_add_u64 v[144:145], v[222:223], 0, s[18:19]
	s_mov_b32 m0, s51
	s_nop 0
	global_load_lds_dwordx4 v[144:145], off
	s_waitcnt vmcnt(8)
	s_waitcnt lgkmcnt(0)
	s_setprio 1
	s_barrier
	v_mfma_f32_16x16x32_bf16 v[60:63], v[152:155], v[184:187], v[60:63]
	v_mfma_f32_16x16x32_bf16 v[60:63], v[156:159], v[188:191], v[60:63]
	v_mfma_f32_16x16x32_bf16 v[56:59], v[160:163], v[184:187], v[56:59]
	v_mfma_f32_16x16x32_bf16 v[56:59], v[164:167], v[188:191], v[56:59]
	v_mfma_f32_16x16x32_bf16 v[52:55], v[152:155], v[194:197], v[52:55]
	v_mfma_f32_16x16x32_bf16 v[52:55], v[156:159], v[198:201], v[52:55]
	v_mfma_f32_16x16x32_bf16 v[44:47], v[160:163], v[194:197], v[44:47]
	v_mfma_f32_16x16x32_bf16 v[44:47], v[164:167], v[198:201], v[44:47]
	v_mfma_f32_16x16x32_bf16 v[36:39], v[152:155], v[202:205], v[36:39]
	v_mfma_f32_16x16x32_bf16 v[36:39], v[156:159], v[206:209], v[36:39]
	v_mfma_f32_16x16x32_bf16 v[28:31], v[160:163], v[202:205], v[28:31]
	v_mfma_f32_16x16x32_bf16 v[28:31], v[164:167], v[206:209], v[28:31]
	v_mfma_f32_16x16x32_bf16 v[20:23], v[152:155], v[210:213], v[20:23]
	v_mfma_f32_16x16x32_bf16 v[20:23], v[156:159], v[214:217], v[20:23]
	v_mfma_f32_16x16x32_bf16 v[12:15], v[160:163], v[210:213], v[12:15]
	v_mfma_f32_16x16x32_bf16 v[12:15], v[164:167], v[214:217], v[12:15]
	s_setprio 0
	s_setprio 1
	v_mfma_f32_16x16x32_bf16 v[48:51], v[168:171], v[184:187], v[48:51]
	v_mfma_f32_16x16x32_bf16 v[48:51], v[172:175], v[188:191], v[48:51]
	v_mfma_f32_16x16x32_bf16 v[40:43], v[176:179], v[184:187], v[40:43]
	v_mfma_f32_16x16x32_bf16 v[40:43], v[180:183], v[188:191], v[40:43]
	v_mfma_f32_16x16x32_bf16 v[32:35], v[168:171], v[194:197], v[32:35]
	v_mfma_f32_16x16x32_bf16 v[32:35], v[172:175], v[198:201], v[32:35]
	v_mfma_f32_16x16x32_bf16 v[24:27], v[176:179], v[194:197], v[24:27]
	v_mfma_f32_16x16x32_bf16 v[24:27], v[180:183], v[198:201], v[24:27]
	v_mfma_f32_16x16x32_bf16 v[16:19], v[168:171], v[202:205], v[16:19]
	v_mfma_f32_16x16x32_bf16 v[16:19], v[172:175], v[206:209], v[16:19]
	v_mfma_f32_16x16x32_bf16 v[8:11], v[176:179], v[202:205], v[8:11]
	v_mfma_f32_16x16x32_bf16 v[8:11], v[180:183], v[206:209], v[8:11]
	v_mfma_f32_16x16x32_bf16 v[4:7], v[168:171], v[210:213], v[4:7]
	v_mfma_f32_16x16x32_bf16 v[4:7], v[172:175], v[214:217], v[4:7]
	v_mfma_f32_16x16x32_bf16 v[0:3], v[176:179], v[210:213], v[0:3]
	v_mfma_f32_16x16x32_bf16 v[0:3], v[180:183], v[214:217], v[0:3]
	s_barrier
	s_setprio 0
	s_add_i32 s61, s61, 2
	s_add_u32 s36, s36, 0x100
	s_addc_u32 s37, s37, 0
	s_add_u32 s59, s59, 0x100
	s_addc_u32 s60, s60, 0
	s_cmp_gt_u32 s61, 5
	s_cbranch_scc0 .LBB0_385
	s_and_b64 vcc, exec, s[20:21]
	s_cbranch_vccz .LBB0_388
	s_barrier

; #define PG8_STAGE(bufoff, gbase, voff) do { _Pragma("unroll") for (int _i = 0; _i < 2; ++_i) \
;         __builtin_amdgcn_global_load_lds((const unsigned*)((const char*)(gbase) + (voff)[_i]), (LAS unsigned*)(lds + (bufoff) + ldsw + _i * 8192), 16, 0, 0); } while (0)
; #define PG8_LDA(dst, b, h) do { _Pragma("unroll") for (int m = 0; m < 4; ++m) _Pragma("unroll") for (int k = 0; k < 2; ++k) dst[m][k] = *(const LAS bf16x8*)(lds + PG8_SA(b, h) + aoff + m * 2048 + k * 1024); } while (0)
; #define PG8_LDB(dst, b, h) do { _Pragma("unroll") for (int n = 0; n < 2; ++n) _Pragma("unroll") for (int k = 0; k < 2; ++k) dst[n][k] = *(const LAS bf16x8*)(lds + PG8_SB(b, h) + boff + n * 2048 + k * 1024); } while (0)
; #define PG8_MMA(ai, bj, At, Bt) do { __builtin_amdgcn_s_setprio(1); _Pragma("unroll") for (int m = 0; m < 4; ++m) _Pragma("unroll") for (int n = 0; n < 2; ++n) _Pragma("unroll") for (int k = 0; k < 2; ++k) \
;         acc[ai][bj][m][n] = __builtin_amdgcn_mfma_f32_16x16x32_bf16(Bt[n][k], At[m][k], acc[ai][bj][m][n], 0, 0, 0); __builtin_amdgcn_s_setprio(0); } while (0)
; #define PG8_WAIT_V(n) asm volatile("s_waitcnt vmcnt(" #n ")" ::: "memory")
; #define PG8_WAIT_L(n) asm volatile("s_waitcnt lgkmcnt(" #n ")" ::: "memory")
; #define PG8_BAR __builtin_amdgcn_s_barrier()
; #define PG8_SCHED __builtin_amdgcn_sched_barrier(0)
; template <class Epi, bool ALIGN_EPI>
; __device__ __forceinline__ void gemm_phase(LAS unsigned char* lds, const Gemm g, const StaticOrder& S, const Epi& E) {
;     ...
;         for (int t = 0; t < nt; t += 2) {
;             const bool last = (t == nt - 2);
;             const char* a1 = cA + (size_t)(t + 1) * kstep;
;             const char* a2 = last ? nA : cA + (size_t)(t + 2) * kstep; const char* b2 = last ? nB : cB + (size_t)(t + 2) * kstep;
;             const char* a3 = a2 + kstep; const char* b3 = b2 + kstep;
;             PG8_LDB(B0, 0, 0); PG8_LDB(B1, 0, 1); PG8_SCHED; PG8_LDA(At, 0, 0); PG8_STAGE(PG8_SA(1, 1), a1 + hA, voffA);
;             PG8_WAIT_V(8); PG8_WAIT_L(0); PG8_BAR; PG8_MMA(0, 0, At, B0); PG8_MMA(0, 1, At, B1); PG8_BAR; PG8_SCHED;
;             PG8_LDA(At, 0, 1); PG8_STAGE(PG8_SB(0, 0), b2, voffB); PG8_STAGE(PG8_SB(0, 1), b2 + hB, voffB); PG8_STAGE(PG8_SA(0, 0), a2, voffA);
;             PG8_WAIT_V(8); PG8_WAIT_L(0); PG8_BAR; PG8_MMA(1, 0, At, B0); PG8_MMA(1, 1, At, B1); PG8_BAR; PG8_SCHED;
.LBB0_403:
	ds_read_b128 v[152:155], v149
	ds_read_b128 v[156:159], v149 offset:1024
	ds_read_b128 v[160:163], v149 offset:2048
	ds_read_b128 v[164:167], v149 offset:3072
	ds_read_b128 v[168:171], v150
	ds_read_b128 v[172:175], v150 offset:1024
	ds_read_b128 v[176:179], v150 offset:2048
	ds_read_b128 v[180:183], v150 offset:3072
	s_add_u32 s30, s6, 0xfff80080
	s_addc_u32 s31, s7, -1
	s_cmp_eq_u32 s53, 8
	s_cselect_b32 s35, s23, s31
	s_cselect_b32 s34, s50, s30
	s_cselect_b32 s31, s25, s52
	s_cselect_b32 s30, s24, s51
	v_lshl_add_u64 v[144:145], s[6:7], 0, v[136:137]
	s_add_i32 m0, s0, 0xc000
	ds_read_b128 v[184:187], v151
	ds_read_b128 v[188:191], v151 offset:1024
	ds_read_b128 v[194:197], v151 offset:2048
	ds_read_b128 v[198:201], v151 offset:3072
	ds_read_b128 v[202:205], v151 offset:4096
	ds_read_b128 v[206:209], v151 offset:5120
	ds_read_b128 v[210:213], v151 offset:6144
	ds_read_b128 v[214:217], v151 offset:7168
	global_load_lds_dwordx4 v[144:145], off
	v_lshl_add_u64 v[144:145], s[6:7], 0, v[138:139]
	s_add_i32 m0, s0, 0xe000
	s_nop 0
	global_load_lds_dwordx4 v[144:145], off
	s_waitcnt vmcnt(8)
	s_waitcnt lgkmcnt(0)
	s_setprio 1
	s_barrier
	v_mfma_f32_16x16x32_bf16 v[124:127], v[152:155], v[184:187], v[124:127]
	v_mfma_f32_16x16x32_bf16 v[124:127], v[156:159], v[188:191], v[124:127]
	v_mfma_f32_16x16x32_bf16 v[120:123], v[160:163], v[184:187], v[120:123]
	v_mfma_f32_16x16x32_bf16 v[120:123], v[164:167], v[188:191], v[120:123]
	v_mfma_f32_16x16x32_bf16 v[116:119], v[152:155], v[194:197], v[116:119]
	v_mfma_f32_16x16x32_bf16 v[116:119], v[156:159], v[198:201], v[116:119]
	v_mfma_f32_16x16x32_bf16 v[108:111], v[160:163], v[194:197], v[108:111]
	v_mfma_f32_16x16x32_bf16 v[108:111], v[164:167], v[198:201], v[108:111]
	v_mfma_f32_16x16x32_bf16 v[100:103], v[152:155], v[202:205], v[100:103]
	v_mfma_f32_16x16x32_bf16 v[100:103], v[156:159], v[206:209], v[100:103]
	v_mfma_f32_16x16x32_bf16 v[92:95], v[160:163], v[202:205], v[92:95]
	v_mfma_f32_16x16x32_bf16 v[92:95], v[164:167], v[206:209], v[92:95]
	v_mfma_f32_16x16x32_bf16 v[84:87], v[152:155], v[210:213], v[84:87]
	v_mfma_f32_16x16x32_bf16 v[84:87], v[156:159], v[214:217], v[84:87]
	v_mfma_f32_16x16x32_bf16 v[76:79], v[160:163], v[210:213], v[76:79]
	v_mfma_f32_16x16x32_bf16 v[76:79], v[164:167], v[214:217], v[76:79]
	s_setprio 0
	s_setprio 1
	v_mfma_f32_16x16x32_bf16 v[112:115], v[168:171], v[184:187], v[112:115]
	v_mfma_f32_16x16x32_bf16 v[112:115], v[172:175], v[188:191], v[112:115]
	v_mfma_f32_16x16x32_bf16 v[104:107], v[176:179], v[184:187], v[104:107]
	v_mfma_f32_16x16x32_bf16 v[104:107], v[180:183], v[188:191], v[104:107]
	v_mfma_f32_16x16x32_bf16 v[96:99], v[168:171], v[194:197], v[96:99]
	v_mfma_f32_16x16x32_bf16 v[96:99], v[172:175], v[198:201], v[96:99]
	v_mfma_f32_16x16x32_bf16 v[88:91], v[176:179], v[194:197], v[88:91]
	v_mfma_f32_16x16x32_bf16 v[88:91], v[180:183], v[198:201], v[88:91]
	v_mfma_f32_16x16x32_bf16 v[80:83], v[168:171], v[202:205], v[80:83]
	v_mfma_f32_16x16x32_bf16 v[80:83], v[172:175], v[206:209], v[80:83]
	v_mfma_f32_16x16x32_bf16 v[72:75], v[176:179], v[202:205], v[72:75]
	v_mfma_f32_16x16x32_bf16 v[72:75], v[180:183], v[206:209], v[72:75]
	v_mfma_f32_16x16x32_bf16 v[68:71], v[168:171], v[210:213], v[68:71]
	v_mfma_f32_16x16x32_bf16 v[68:71], v[172:175], v[214:217], v[68:71]
	v_mfma_f32_16x16x32_bf16 v[64:67], v[176:179], v[210:213], v[64:67]
	v_mfma_f32_16x16x32_bf16 v[64:67], v[180:183], v[214:217], v[64:67]
	s_barrier
	s_setprio 0
	s_add_i32 s54, s45, s2
	v_lshl_add_u64 v[144:145], s[30:31], 0, v[132:133]
	s_mov_b32 m0, s54
	ds_read_b128 v[184:187], v151 offset:16384
	ds_read_b128 v[188:191], v151 offset:17408
	ds_read_b128 v[194:197], v151 offset:18432
	ds_read_b128 v[198:201], v151 offset:19456
	ds_read_b128 v[202:205], v151 offset:20480
	ds_read_b128 v[206:209], v151 offset:21504
	ds_read_b128 v[210:213], v151 offset:22528
	ds_read_b128 v[214:217], v151 offset:23552
	global_load_lds_dwordx4 v[144:145], off
	s_add_i32 m0, s54, 0x2000
	s_add_u32 s54, s30, 0x30000
	v_lshl_add_u64 v[218:219], s[30:31], 0, v[128:129]
	s_addc_u32 s55, s31, 0
	s_add_i32 s56, s46, s2
	global_load_lds_dwordx4 v[218:219], off
	v_lshl_add_u64 v[220:221], s[54:55], 0, v[132:133]
	s_mov_b32 m0, s56
	v_lshl_add_u64 v[222:223], s[34:35], 0, v[130:131]
	global_load_lds_dwordx4 v[220:221], off
	v_lshl_add_u64 v[220:221], s[54:55], 0, v[128:129]
	s_add_i32 m0, s56, 0x2000
	s_nop 0
	global_load_lds_dwordx4 v[220:221], off
	v_lshl_add_u64 v[220:221], s[34:35], 0, v[134:135]
	s_mov_b32 m0, s0
	s_nop 0
	global_load_lds_dwordx4 v[220:221], off
	s_mov_b32 m0, s1
	s_nop 0
	global_load_lds_dwordx4 v[222:223], off
	s_waitcnt vmcnt(8)
	s_waitcnt lgkmcnt(0)
	s_setprio 1
	s_barrier
; #define PG8_STAGE(bufoff, gbase, voff) do { _Pragma("unroll") for (int _i = 0; _i < 2; ++_i) \
;         __builtin_amdgcn_global_load_lds((const unsigned*)((const char*)(gbase) + (voff)[_i]), (LAS unsigned*)(lds + (bufoff) + ldsw + _i * 8192), 16, 0, 0); } while (0)
; #define PG8_LDA(dst, b, h) do { _Pragma("unroll") for (int m = 0; m < 4; ++m) _Pragma("unroll") for (int k = 0; k < 2; ++k) dst[m][k] = *(const LAS bf16x8*)(lds + PG8_SA(b, h) + aoff + m * 2048 + k * 1024); } while (0)
; #define PG8_LDB(dst, b, h) do { _Pragma("unroll") for (int n = 0; n < 2; ++n) _Pragma("unroll") for (int k = 0; k < 2; ++k) dst[n][k] = *(const LAS bf16x8*)(lds + PG8_SB(b, h) + boff + n * 2048 + k * 1024); } while (0)
; #define PG8_MMA(ai, bj, At, Bt) do { __builtin_amdgcn_s_setprio(1); _Pragma("unroll") for (int m = 0; m < 4; ++m) _Pragma("unroll") for (int n = 0; n < 2; ++n) _Pragma("unroll") for (int k = 0; k < 2; ++k) \
;         acc[ai][bj][m][n] = __builtin_amdgcn_mfma_f32_16x16x32_bf16(Bt[n][k], At[m][k], acc[ai][bj][m][n], 0, 0, 0); __builtin_amdgcn_s_setprio(0); } while (0)
; #define PG8_WAIT_V(n) asm volatile("s_waitcnt vmcnt(" #n ")" ::: "memory")
; #define PG8_WAIT_L(n) asm volatile("s_waitcnt lgkmcnt(" #n ")" ::: "memory")
; #define PG8_BAR __builtin_amdgcn_s_barrier()
; #define PG8_SCHED __builtin_amdgcn_sched_barrier(0)
; template <class Epi, bool ALIGN_EPI>
; __device__ __forceinline__ void gemm_phase(LAS unsigned char* lds, const Gemm g, const StaticOrder& S, const Epi& E) {
;     ...
;             PG8_WAIT_V(8); PG8_WAIT_L(0); PG8_BAR; PG8_MMA(1, 0, At, B0); PG8_MMA(1, 1, At, B1); PG8_BAR; PG8_SCHED;
;             PG8_LDB(B0, 1, 0); PG8_LDB(B1, 1, 1); PG8_SCHED; PG8_LDA(At, 1, 0); PG8_STAGE(PG8_SA(0, 1), a2 + hA, voffA);
;             PG8_WAIT_V(8); PG8_WAIT_L(0); PG8_BAR; PG8_MMA(0, 0, At, B0); PG8_MMA(0, 1, At, B1); PG8_BAR; PG8_SCHED;
	v_mfma_f32_16x16x32_bf16 v[60:63], v[152:155], v[184:187], v[60:63]
	v_mfma_f32_16x16x32_bf16 v[60:63], v[156:159], v[188:191], v[60:63]
	v_mfma_f32_16x16x32_bf16 v[56:59], v[160:163], v[184:187], v[56:59]
	v_mfma_f32_16x16x32_bf16 v[56:59], v[164:167], v[188:191], v[56:59]
	v_mfma_f32_16x16x32_bf16 v[52:55], v[152:155], v[194:197], v[52:55]
	v_mfma_f32_16x16x32_bf16 v[52:55], v[156:159], v[198:201], v[52:55]
	v_mfma_f32_16x16x32_bf16 v[44:47], v[160:163], v[194:197], v[44:47]
	v_mfma_f32_16x16x32_bf16 v[44:47], v[164:167], v[198:201], v[44:47]
	v_mfma_f32_16x16x32_bf16 v[36:39], v[152:155], v[202:205], v[36:39]
	v_mfma_f32_16x16x32_bf16 v[36:39], v[156:159], v[206:209], v[36:39]
	v_mfma_f32_16x16x32_bf16 v[28:31], v[160:163], v[202:205], v[28:31]
	v_mfma_f32_16x16x32_bf16 v[28:31], v[164:167], v[206:209], v[28:31]
	v_mfma_f32_16x16x32_bf16 v[20:23], v[152:155], v[210:213], v[20:23]
	v_mfma_f32_16x16x32_bf16 v[20:23], v[156:159], v[214:217], v[20:23]
	v_mfma_f32_16x16x32_bf16 v[12:15], v[160:163], v[210:213], v[12:15]
	v_mfma_f32_16x16x32_bf16 v[12:15], v[164:167], v[214:217], v[12:15]
	s_setprio 0
	s_setprio 1
	v_mfma_f32_16x16x32_bf16 v[48:51], v[168:171], v[184:187], v[48:51]
	v_mfma_f32_16x16x32_bf16 v[48:51], v[172:175], v[188:191], v[48:51]
	v_mfma_f32_16x16x32_bf16 v[40:43], v[176:179], v[184:187], v[40:43]
	v_mfma_f32_16x16x32_bf16 v[40:43], v[180:183], v[188:191], v[40:43]
	v_mfma_f32_16x16x32_bf16 v[32:35], v[168:171], v[194:197], v[32:35]
	v_mfma_f32_16x16x32_bf16 v[32:35], v[172:175], v[198:201], v[32:35]
	v_mfma_f32_16x16x32_bf16 v[24:27], v[176:179], v[194:197], v[24:27]
	v_mfma_f32_16x16x32_bf16 v[24:27], v[180:183], v[198:201], v[24:27]
	v_mfma_f32_16x16x32_bf16 v[16:19], v[168:171], v[202:205], v[16:19]
	v_mfma_f32_16x16x32_bf16 v[16:19], v[172:175], v[206:209], v[16:19]
	v_mfma_f32_16x16x32_bf16 v[8:11], v[176:179], v[202:205], v[8:11]
	v_mfma_f32_16x16x32_bf16 v[8:11], v[180:183], v[206:209], v[8:11]
	v_mfma_f32_16x16x32_bf16 v[4:7], v[168:171], v[210:213], v[4:7]
	v_mfma_f32_16x16x32_bf16 v[4:7], v[172:175], v[214:217], v[4:7]
	v_mfma_f32_16x16x32_bf16 v[0:3], v[176:179], v[210:213], v[0:3]
	v_mfma_f32_16x16x32_bf16 v[0:3], v[180:183], v[214:217], v[0:3]
	s_barrier
	s_setprio 0
	s_add_i32 s54, 0, 0x18000
	s_add_i32 s55, 0, 0x1c000
	v_add_u32_e32 v164, s54, v147
	v_add_u32_e32 v180, s55, v147
	ds_read_b128 v[152:155], v164
	ds_read_b128 v[156:159], v164 offset:1024
	ds_read_b128 v[160:163], v164 offset:2048
	ds_read_b128 v[164:167], v164 offset:3072
	ds_read_b128 v[168:171], v180
	ds_read_b128 v[172:175], v180 offset:1024
	ds_read_b128 v[176:179], v180 offset:2048
	ds_read_b128 v[180:183], v180 offset:3072
	s_add_u32 s34, s34, 0x80000
	s_addc_u32 s35, s35, 0
	s_mov_b32 m0, s29
	v_lshl_add_u64 v[224:225], s[34:35], 0, v[134:135]
	ds_read_b128 v[184:187], v151 offset:32768
	ds_read_b128 v[188:191], v151 offset:33792
	ds_read_b128 v[194:197], v151 offset:34816
	ds_read_b128 v[198:201], v151 offset:35840
	ds_read_b128 v[202:205], v151 offset:36864
	ds_read_b128 v[206:209], v151 offset:37888
	ds_read_b128 v[210:213], v151 offset:38912
	ds_read_b128 v[214:217], v151 offset:39936
	global_load_lds_dwordx4 v[224:225], off
	v_lshl_add_u64 v[224:225], s[34:35], 0, v[130:131]
	s_mov_b32 m0, s40
	s_nop 0
	global_load_lds_dwordx4 v[224:225], off
	s_waitcnt vmcnt(8)
	s_waitcnt lgkmcnt(0)
	s_setprio 1
	s_barrier
	v_mfma_f32_16x16x32_bf16 v[124:127], v[152:155], v[184:187], v[124:127]
	v_mfma_f32_16x16x32_bf16 v[124:127], v[156:159], v[188:191], v[124:127]
	v_mfma_f32_16x16x32_bf16 v[120:123], v[160:163], v[184:187], v[120:123]
	v_mfma_f32_16x16x32_bf16 v[120:123], v[164:167], v[188:191], v[120:123]
	v_mfma_f32_16x16x32_bf16 v[116:119], v[152:155], v[194:197], v[116:119]
	v_mfma_f32_16x16x32_bf16 v[116:119], v[156:159], v[198:201], v[116:119]
	v_mfma_f32_16x16x32_bf16 v[108:111], v[160:163], v[194:197], v[108:111]
	v_mfma_f32_16x16x32_bf16 v[108:111], v[164:167], v[198:201], v[108:111]
	v_mfma_f32_16x16x32_bf16 v[100:103], v[152:155], v[202:205], v[100:103]
	v_mfma_f32_16x16x32_bf16 v[100:103], v[156:159], v[206:209], v[100:103]
	v_mfma_f32_16x16x32_bf16 v[92:95], v[160:163], v[202:205], v[92:95]
	v_mfma_f32_16x16x32_bf16 v[92:95], v[164:167], v[206:209], v[92:95]
	v_mfma_f32_16x16x32_bf16 v[84:87], v[152:155], v[210:213], v[84:87]
	v_mfma_f32_16x16x32_bf16 v[84:87], v[156:159], v[214:217], v[84:87]
	v_mfma_f32_16x16x32_bf16 v[76:79], v[160:163], v[210:213], v[76:79]
	v_mfma_f32_16x16x32_bf16 v[76:79], v[164:167], v[214:217], v[76:79]
	s_setprio 0
	s_setprio 1
	v_mfma_f32_16x16x32_bf16 v[112:115], v[168:171], v[184:187], v[112:115]
	v_mfma_f32_16x16x32_bf16 v[112:115], v[172:175], v[188:191], v[112:115]
	v_mfma_f32_16x16x32_bf16 v[104:107], v[176:179], v[184:187], v[104:107]
	v_mfma_f32_16x16x32_bf16 v[104:107], v[180:183], v[188:191], v[104:107]
	v_mfma_f32_16x16x32_bf16 v[96:99], v[168:171], v[194:197], v[96:99]
	v_mfma_f32_16x16x32_bf16 v[96:99], v[172:175], v[198:201], v[96:99]
	v_mfma_f32_16x16x32_bf16 v[88:91], v[176:179], v[194:197], v[88:91]
	v_mfma_f32_16x16x32_bf16 v[88:91], v[180:183], v[198:201], v[88:91]
	v_mfma_f32_16x16x32_bf16 v[80:83], v[168:171], v[202:205], v[80:83]
	v_mfma_f32_16x16x32_bf16 v[80:83], v[172:175], v[206:209], v[80:83]
	v_mfma_f32_16x16x32_bf16 v[72:75], v[176:179], v[202:205], v[72:75]
	v_mfma_f32_16x16x32_bf16 v[72:75], v[180:183], v[206:209], v[72:75]
	v_mfma_f32_16x16x32_bf16 v[68:71], v[168:171], v[210:213], v[68:71]
	v_mfma_f32_16x16x32_bf16 v[68:71], v[172:175], v[214:217], v[68:71]
	v_mfma_f32_16x16x32_bf16 v[64:67], v[176:179], v[210:213], v[64:67]
	v_mfma_f32_16x16x32_bf16 v[64:67], v[180:183], v[214:217], v[64:67]
	s_barrier
; #define PG8_STAGE(bufoff, gbase, voff) do { _Pragma("unroll") for (int _i = 0; _i < 2; ++_i) \
;         __builtin_amdgcn_global_load_lds((const unsigned*)((const char*)(gbase) + (voff)[_i]), (LAS unsigned*)(lds + (bufoff) + ldsw + _i * 8192), 16, 0, 0); } while (0)
; #define PG8_LDA(dst, b, h) do { _Pragma("unroll") for (int m = 0; m < 4; ++m) _Pragma("unroll") for (int k = 0; k < 2; ++k) dst[m][k] = *(const LAS bf16x8*)(lds + PG8_SA(b, h) + aoff + m * 2048 + k * 1024); } while (0)
; #define PG8_MMA(ai, bj, At, Bt) do { __builtin_amdgcn_s_setprio(1); _Pragma("unroll") for (int m = 0; m < 4; ++m) _Pragma("unroll") for (int n = 0; n < 2; ++n) _Pragma("unroll") for (int k = 0; k < 2; ++k) \
;         acc[ai][bj][m][n] = __builtin_amdgcn_mfma_f32_16x16x32_bf16(Bt[n][k], At[m][k], acc[ai][bj][m][n], 0, 0, 0); __builtin_amdgcn_s_setprio(0); } while (0)
; #define PG8_WAIT_V(n) asm volatile("s_waitcnt vmcnt(" #n ")" ::: "memory")
; #define PG8_WAIT_L(n) asm volatile("s_waitcnt lgkmcnt(" #n ")" ::: "memory")
; #define PG8_BAR __builtin_amdgcn_s_barrier()
; #define PG8_SCHED __builtin_amdgcn_sched_barrier(0)
; template <class Epi, bool ALIGN_EPI>
; __device__ __forceinline__ void gemm_phase(LAS unsigned char* lds, const Gemm g, const StaticOrder& S, const Epi& E) {
;     ...
;             PG8_LDA(At, 1, 1); PG8_STAGE(PG8_SB(1, 0), b3, voffB); PG8_STAGE(PG8_SB(1, 1), b3 + hB, voffB); PG8_STAGE(PG8_SA(1, 0), a3, voffA);
;             PG8_WAIT_V(8); PG8_WAIT_L(0); PG8_BAR; PG8_MMA(1, 0, At, B0); PG8_MMA(1, 1, At, B1); PG8_BAR; PG8_SCHED;
;         }
;         if constexpr (ALIGN_EPI) { if (wr == 0) PG8_BAR; }
	s_setprio 0
	s_add_i32 s34, s54, s2
	v_lshl_add_u64 v[144:145], v[144:145], 0, s[16:17]
	s_mov_b32 m0, s34
	ds_read_b128 v[184:187], v151 offset:49152
	ds_read_b128 v[188:191], v151 offset:50176
	ds_read_b128 v[194:197], v151 offset:51200
	ds_read_b128 v[198:201], v151 offset:52224
	ds_read_b128 v[202:205], v151 offset:53248
	ds_read_b128 v[206:209], v151 offset:54272
	ds_read_b128 v[210:213], v151 offset:55296
	ds_read_b128 v[214:217], v151 offset:56320
	global_load_lds_dwordx4 v[144:145], off
	s_add_i32 m0, s34, 0x2000
	s_add_u32 s30, s30, 0x30080
	v_lshl_add_u64 v[144:145], v[218:219], 0, s[16:17]
	s_addc_u32 s31, s31, 0
	s_add_i32 s34, s55, s2
	global_load_lds_dwordx4 v[144:145], off
	v_lshl_add_u64 v[144:145], s[30:31], 0, v[132:133]
	s_mov_b32 m0, s34
	s_nop 0
	global_load_lds_dwordx4 v[144:145], off
	v_lshl_add_u64 v[144:145], s[30:31], 0, v[128:129]
	s_add_i32 m0, s34, 0x2000
	s_nop 0
	global_load_lds_dwordx4 v[144:145], off
	v_lshl_add_u64 v[144:145], v[220:221], 0, s[16:17]
	s_mov_b32 m0, s42
	s_nop 0
	global_load_lds_dwordx4 v[144:145], off
	v_lshl_add_u64 v[144:145], v[222:223], 0, s[16:17]
	s_mov_b32 m0, s43
	s_nop 0
	global_load_lds_dwordx4 v[144:145], off
	s_waitcnt vmcnt(8)
	s_waitcnt lgkmcnt(0)
	s_setprio 1
	s_barrier
	v_mfma_f32_16x16x32_bf16 v[60:63], v[152:155], v[184:187], v[60:63]
	v_mfma_f32_16x16x32_bf16 v[60:63], v[156:159], v[188:191], v[60:63]
	v_mfma_f32_16x16x32_bf16 v[56:59], v[160:163], v[184:187], v[56:59]
	v_mfma_f32_16x16x32_bf16 v[56:59], v[164:167], v[188:191], v[56:59]
	v_mfma_f32_16x16x32_bf16 v[52:55], v[152:155], v[194:197], v[52:55]
	v_mfma_f32_16x16x32_bf16 v[52:55], v[156:159], v[198:201], v[52:55]
	v_mfma_f32_16x16x32_bf16 v[44:47], v[160:163], v[194:197], v[44:47]
	v_mfma_f32_16x16x32_bf16 v[44:47], v[164:167], v[198:201], v[44:47]
	v_mfma_f32_16x16x32_bf16 v[36:39], v[152:155], v[202:205], v[36:39]
	v_mfma_f32_16x16x32_bf16 v[36:39], v[156:159], v[206:209], v[36:39]
	v_mfma_f32_16x16x32_bf16 v[28:31], v[160:163], v[202:205], v[28:31]
	v_mfma_f32_16x16x32_bf16 v[28:31], v[164:167], v[206:209], v[28:31]
	v_mfma_f32_16x16x32_bf16 v[20:23], v[152:155], v[210:213], v[20:23]
	v_mfma_f32_16x16x32_bf16 v[20:23], v[156:159], v[214:217], v[20:23]
	v_mfma_f32_16x16x32_bf16 v[12:15], v[160:163], v[210:213], v[12:15]
	v_mfma_f32_16x16x32_bf16 v[12:15], v[164:167], v[214:217], v[12:15]
	s_setprio 0
	s_setprio 1
	v_mfma_f32_16x16x32_bf16 v[48:51], v[168:171], v[184:187], v[48:51]
	v_mfma_f32_16x16x32_bf16 v[48:51], v[172:175], v[188:191], v[48:51]
	v_mfma_f32_16x16x32_bf16 v[40:43], v[176:179], v[184:187], v[40:43]
	v_mfma_f32_16x16x32_bf16 v[40:43], v[180:183], v[188:191], v[40:43]
	v_mfma_f32_16x16x32_bf16 v[32:35], v[168:171], v[194:197], v[32:35]
	v_mfma_f32_16x16x32_bf16 v[32:35], v[172:175], v[198:201], v[32:35]
	v_mfma_f32_16x16x32_bf16 v[24:27], v[176:179], v[194:197], v[24:27]
	v_mfma_f32_16x16x32_bf16 v[24:27], v[180:183], v[198:201], v[24:27]
	v_mfma_f32_16x16x32_bf16 v[16:19], v[168:171], v[202:205], v[16:19]
	v_mfma_f32_16x16x32_bf16 v[16:19], v[172:175], v[206:209], v[16:19]
	v_mfma_f32_16x16x32_bf16 v[8:11], v[176:179], v[202:205], v[8:11]
	v_mfma_f32_16x16x32_bf16 v[8:11], v[180:183], v[206:209], v[8:11]
	v_mfma_f32_16x16x32_bf16 v[4:7], v[168:171], v[210:213], v[4:7]
	v_mfma_f32_16x16x32_bf16 v[4:7], v[172:175], v[214:217], v[4:7]
	v_mfma_f32_16x16x32_bf16 v[0:3], v[176:179], v[210:213], v[0:3]
	v_mfma_f32_16x16x32_bf16 v[0:3], v[180:183], v[214:217], v[0:3]
	s_barrier
	s_setprio 0
	s_add_i32 s53, s53, 2
	s_add_u32 s6, s6, 0x100
	s_addc_u32 s7, s7, 0
	s_add_u32 s51, s51, 0x100
	s_addc_u32 s52, s52, 0
	s_cmp_gt_u32 s53, 9
	s_cbranch_scc0 .LBB0_403
	s_and_b64 vcc, exec, s[18:19]
	s_cbranch_vccz .LBB0_406
	s_barrier

; #define PG8_STAGE(bufoff, gbase, voff) do { _Pragma("unroll") for (int _i = 0; _i < 2; ++_i) \
;         __builtin_amdgcn_global_load_lds((const unsigned*)((const char*)(gbase) + (voff)[_i]), (LAS unsigned*)(lds + (bufoff) + ldsw + _i * 8192), 16, 0, 0); } while (0)
; #define PG8_LDA(dst, b, h) do { _Pragma("unroll") for (int m = 0; m < 4; ++m) _Pragma("unroll") for (int k = 0; k < 2; ++k) dst[m][k] = *(const LAS bf16x8*)(lds + PG8_SA(b, h) + aoff + m * 2048 + k * 1024); } while (0)
; #define PG8_LDB(dst, b, h) do { _Pragma("unroll") for (int n = 0; n < 2; ++n) _Pragma("unroll") for (int k = 0; k < 2; ++k) dst[n][k] = *(const LAS bf16x8*)(lds + PG8_SB(b, h) + boff + n * 2048 + k * 1024); } while (0)
; #define PG8_MMA(ai, bj, At, Bt) do { __builtin_amdgcn_s_setprio(1); _Pragma("unroll") for (int m = 0; m < 4; ++m) _Pragma("unroll") for (int n = 0; n < 2; ++n) _Pragma("unroll") for (int k = 0; k < 2; ++k) \
;         acc[ai][bj][m][n] = __builtin_amdgcn_mfma_f32_16x16x32_bf16(Bt[n][k], At[m][k], acc[ai][bj][m][n], 0, 0, 0); __builtin_amdgcn_s_setprio(0); } while (0)
; #define PG8_WAIT_V(n) asm volatile("s_waitcnt vmcnt(" #n ")" ::: "memory")
; #define PG8_WAIT_L(n) asm volatile("s_waitcnt lgkmcnt(" #n ")" ::: "memory")
; #define PG8_BAR __builtin_amdgcn_s_barrier()
; #define PG8_SCHED __builtin_amdgcn_sched_barrier(0)
; template <class Epi, bool ALIGN_EPI>
; __device__ __forceinline__ void gemm_phase(LAS unsigned char* lds, const Gemm g, const StaticOrder& S, const Epi& E) {
;     ...
;         for (int t = 0; t < nt; t += 2) {
;             const bool last = (t == nt - 2);
;             const char* a1 = cA + (size_t)(t + 1) * kstep;
;             const char* a2 = last ? nA : cA + (size_t)(t + 2) * kstep; const char* b2 = last ? nB : cB + (size_t)(t + 2) * kstep;
;             const char* a3 = a2 + kstep; const char* b3 = b2 + kstep;
;             PG8_LDB(B0, 0, 0); PG8_LDB(B1, 0, 1); PG8_SCHED; PG8_LDA(At, 0, 0); PG8_STAGE(PG8_SA(1, 1), a1 + hA, voffA);
;             PG8_WAIT_V(8); PG8_WAIT_L(0); PG8_BAR; PG8_MMA(0, 0, At, B0); PG8_MMA(0, 1, At, B1); PG8_BAR; PG8_SCHED;
;             PG8_LDA(At, 0, 1); PG8_STAGE(PG8_SB(0, 0), b2, voffB); PG8_STAGE(PG8_SB(0, 1), b2 + hB, voffB); PG8_STAGE(PG8_SA(0, 0), a2, voffA);
;             PG8_WAIT_V(8); PG8_WAIT_L(0); PG8_BAR; PG8_MMA(1, 0, At, B0); PG8_MMA(1, 1, At, B1); PG8_BAR; PG8_SCHED;
.LBB0_419:
	ds_read_b128 v[148:151], v145
	ds_read_b128 v[152:155], v145 offset:1024
	ds_read_b128 v[156:159], v145 offset:2048
	ds_read_b128 v[160:163], v145 offset:3072
	ds_read_b128 v[164:167], v146
	ds_read_b128 v[168:171], v146 offset:1024
	ds_read_b128 v[172:175], v146 offset:2048
	ds_read_b128 v[176:179], v146 offset:3072
	s_add_u32 s30, s28, 0xfff80080
	s_addc_u32 s31, s29, -1
	s_cmp_eq_u32 s53, 28
	s_cselect_b32 s35, s19, s31
	s_cselect_b32 s34, s49, s30
	s_cselect_b32 s31, s17, s52
	s_cselect_b32 s30, s50, s51
	v_lshl_add_u64 v[140:141], s[28:29], 0, v[136:137]
	s_add_i32 m0, s27, 0xc000
	ds_read_b128 v[180:183], v147
	ds_read_b128 v[184:187], v147 offset:1024
	ds_read_b128 v[188:191], v147 offset:2048
	ds_read_b128 v[194:197], v147 offset:3072
	ds_read_b128 v[198:201], v147 offset:4096
	ds_read_b128 v[202:205], v147 offset:5120
	ds_read_b128 v[206:209], v147 offset:6144
	ds_read_b128 v[210:213], v147 offset:7168
	global_load_lds_dwordx4 v[140:141], off
	v_lshl_add_u64 v[140:141], s[28:29], 0, v[138:139]
	s_add_i32 m0, s27, 0xe000
	s_nop 0
	global_load_lds_dwordx4 v[140:141], off
	s_waitcnt vmcnt(8)
	s_waitcnt lgkmcnt(0)
	s_setprio 1
	s_barrier
	v_mfma_f32_16x16x32_bf16 v[124:127], v[148:151], v[180:183], v[124:127]
	v_mfma_f32_16x16x32_bf16 v[124:127], v[152:155], v[184:187], v[124:127]
	v_mfma_f32_16x16x32_bf16 v[120:123], v[156:159], v[180:183], v[120:123]
	v_mfma_f32_16x16x32_bf16 v[120:123], v[160:163], v[184:187], v[120:123]
	v_mfma_f32_16x16x32_bf16 v[116:119], v[148:151], v[188:191], v[116:119]
	v_mfma_f32_16x16x32_bf16 v[116:119], v[152:155], v[194:197], v[116:119]
	v_mfma_f32_16x16x32_bf16 v[108:111], v[156:159], v[188:191], v[108:111]
	v_mfma_f32_16x16x32_bf16 v[108:111], v[160:163], v[194:197], v[108:111]
	v_mfma_f32_16x16x32_bf16 v[100:103], v[148:151], v[198:201], v[100:103]
	v_mfma_f32_16x16x32_bf16 v[100:103], v[152:155], v[202:205], v[100:103]
	v_mfma_f32_16x16x32_bf16 v[92:95], v[156:159], v[198:201], v[92:95]
	v_mfma_f32_16x16x32_bf16 v[92:95], v[160:163], v[202:205], v[92:95]
	v_mfma_f32_16x16x32_bf16 v[84:87], v[148:151], v[206:209], v[84:87]
	v_mfma_f32_16x16x32_bf16 v[84:87], v[152:155], v[210:213], v[84:87]
	v_mfma_f32_16x16x32_bf16 v[76:79], v[156:159], v[206:209], v[76:79]
	v_mfma_f32_16x16x32_bf16 v[76:79], v[160:163], v[210:213], v[76:79]
	s_setprio 0
	s_setprio 1
	v_mfma_f32_16x16x32_bf16 v[112:115], v[164:167], v[180:183], v[112:115]
	v_mfma_f32_16x16x32_bf16 v[112:115], v[168:171], v[184:187], v[112:115]
	v_mfma_f32_16x16x32_bf16 v[104:107], v[172:175], v[180:183], v[104:107]
	v_mfma_f32_16x16x32_bf16 v[104:107], v[176:179], v[184:187], v[104:107]
	v_mfma_f32_16x16x32_bf16 v[96:99], v[164:167], v[188:191], v[96:99]
	v_mfma_f32_16x16x32_bf16 v[96:99], v[168:171], v[194:197], v[96:99]
	v_mfma_f32_16x16x32_bf16 v[88:91], v[172:175], v[188:191], v[88:91]
	v_mfma_f32_16x16x32_bf16 v[88:91], v[176:179], v[194:197], v[88:91]
	v_mfma_f32_16x16x32_bf16 v[80:83], v[164:167], v[198:201], v[80:83]
	v_mfma_f32_16x16x32_bf16 v[80:83], v[168:171], v[202:205], v[80:83]
	v_mfma_f32_16x16x32_bf16 v[72:75], v[172:175], v[198:201], v[72:75]
	v_mfma_f32_16x16x32_bf16 v[72:75], v[176:179], v[202:205], v[72:75]
	v_mfma_f32_16x16x32_bf16 v[68:71], v[164:167], v[206:209], v[68:71]
	v_mfma_f32_16x16x32_bf16 v[68:71], v[168:171], v[210:213], v[68:71]
	v_mfma_f32_16x16x32_bf16 v[64:67], v[172:175], v[206:209], v[64:67]
	v_mfma_f32_16x16x32_bf16 v[64:67], v[176:179], v[210:213], v[64:67]
	s_barrier
	s_setprio 0
	s_add_i32 s54, s45, s1
	v_lshl_add_u64 v[140:141], s[30:31], 0, v[132:133]
	s_mov_b32 m0, s54
	ds_read_b128 v[180:183], v147 offset:16384
	ds_read_b128 v[184:187], v147 offset:17408
	ds_read_b128 v[188:191], v147 offset:18432
	ds_read_b128 v[194:197], v147 offset:19456
	ds_read_b128 v[198:201], v147 offset:20480
	ds_read_b128 v[202:205], v147 offset:21504
	ds_read_b128 v[206:209], v147 offset:22528
	ds_read_b128 v[210:213], v147 offset:23552
	global_load_lds_dwordx4 v[140:141], off
	s_add_i32 m0, s54, 0x2000
	s_add_u32 s54, s30, 0x80000
	v_lshl_add_u64 v[214:215], s[30:31], 0, v[128:129]
	s_addc_u32 s55, s31, 0
	s_add_i32 s56, s46, s1
	global_load_lds_dwordx4 v[214:215], off
	v_lshl_add_u64 v[216:217], s[54:55], 0, v[132:133]
	s_mov_b32 m0, s56
	v_lshl_add_u64 v[218:219], s[34:35], 0, v[130:131]
	global_load_lds_dwordx4 v[216:217], off
	v_lshl_add_u64 v[216:217], s[54:55], 0, v[128:129]
	s_add_i32 m0, s56, 0x2000
	s_nop 0
	global_load_lds_dwordx4 v[216:217], off
	v_lshl_add_u64 v[216:217], s[34:35], 0, v[134:135]
	s_mov_b32 m0, s27
	s_nop 0
	global_load_lds_dwordx4 v[216:217], off
	s_mov_b32 m0, s39
	s_nop 0
	global_load_lds_dwordx4 v[218:219], off
	s_waitcnt vmcnt(8)
	s_waitcnt lgkmcnt(0)
	s_setprio 1
	s_barrier
; #define PG8_STAGE(bufoff, gbase, voff) do { _Pragma("unroll") for (int _i = 0; _i < 2; ++_i) \
;         __builtin_amdgcn_global_load_lds((const unsigned*)((const char*)(gbase) + (voff)[_i]), (LAS unsigned*)(lds + (bufoff) + ldsw + _i * 8192), 16, 0, 0); } while (0)
; #define PG8_LDA(dst, b, h) do { _Pragma("unroll") for (int m = 0; m < 4; ++m) _Pragma("unroll") for (int k = 0; k < 2; ++k) dst[m][k] = *(const LAS bf16x8*)(lds + PG8_SA(b, h) + aoff + m * 2048 + k * 1024); } while (0)
; #define PG8_LDB(dst, b, h) do { _Pragma("unroll") for (int n = 0; n < 2; ++n) _Pragma("unroll") for (int k = 0; k < 2; ++k) dst[n][k] = *(const LAS bf16x8*)(lds + PG8_SB(b, h) + boff + n * 2048 + k * 1024); } while (0)
; #define PG8_MMA(ai, bj, At, Bt) do { __builtin_amdgcn_s_setprio(1); _Pragma("unroll") for (int m = 0; m < 4; ++m) _Pragma("unroll") for (int n = 0; n < 2; ++n) _Pragma("unroll") for (int k = 0; k < 2; ++k) \
;         acc[ai][bj][m][n] = __builtin_amdgcn_mfma_f32_16x16x32_bf16(Bt[n][k], At[m][k], acc[ai][bj][m][n], 0, 0, 0); __builtin_amdgcn_s_setprio(0); } while (0)
; #define PG8_WAIT_V(n) asm volatile("s_waitcnt vmcnt(" #n ")" ::: "memory")
; #define PG8_WAIT_L(n) asm volatile("s_waitcnt lgkmcnt(" #n ")" ::: "memory")
; #define PG8_BAR __builtin_amdgcn_s_barrier()
; #define PG8_SCHED __builtin_amdgcn_sched_barrier(0)
; template <class Epi, bool ALIGN_EPI>
; __device__ __forceinline__ void gemm_phase(LAS unsigned char* lds, const Gemm g, const StaticOrder& S, const Epi& E) {
;     ...
;             PG8_WAIT_V(8); PG8_WAIT_L(0); PG8_BAR; PG8_MMA(1, 0, At, B0); PG8_MMA(1, 1, At, B1); PG8_BAR; PG8_SCHED;
;             PG8_LDB(B0, 1, 0); PG8_LDB(B1, 1, 1); PG8_SCHED; PG8_LDA(At, 1, 0); PG8_STAGE(PG8_SA(0, 1), a2 + hA, voffA);
;             PG8_WAIT_V(8); PG8_WAIT_L(0); PG8_BAR; PG8_MMA(0, 0, At, B0); PG8_MMA(0, 1, At, B1); PG8_BAR; PG8_SCHED;
	v_mfma_f32_16x16x32_bf16 v[60:63], v[148:151], v[180:183], v[60:63]
	v_mfma_f32_16x16x32_bf16 v[60:63], v[152:155], v[184:187], v[60:63]
	v_mfma_f32_16x16x32_bf16 v[56:59], v[156:159], v[180:183], v[56:59]
	v_mfma_f32_16x16x32_bf16 v[56:59], v[160:163], v[184:187], v[56:59]
	v_mfma_f32_16x16x32_bf16 v[52:55], v[148:151], v[188:191], v[52:55]
	v_mfma_f32_16x16x32_bf16 v[52:55], v[152:155], v[194:197], v[52:55]
	v_mfma_f32_16x16x32_bf16 v[44:47], v[156:159], v[188:191], v[44:47]
	v_mfma_f32_16x16x32_bf16 v[44:47], v[160:163], v[194:197], v[44:47]
	v_mfma_f32_16x16x32_bf16 v[36:39], v[148:151], v[198:201], v[36:39]
	v_mfma_f32_16x16x32_bf16 v[36:39], v[152:155], v[202:205], v[36:39]
	v_mfma_f32_16x16x32_bf16 v[28:31], v[156:159], v[198:201], v[28:31]
	v_mfma_f32_16x16x32_bf16 v[28:31], v[160:163], v[202:205], v[28:31]
	v_mfma_f32_16x16x32_bf16 v[20:23], v[148:151], v[206:209], v[20:23]
	v_mfma_f32_16x16x32_bf16 v[20:23], v[152:155], v[210:213], v[20:23]
	v_mfma_f32_16x16x32_bf16 v[12:15], v[156:159], v[206:209], v[12:15]
	v_mfma_f32_16x16x32_bf16 v[12:15], v[160:163], v[210:213], v[12:15]
	s_setprio 0
	s_setprio 1
	v_mfma_f32_16x16x32_bf16 v[48:51], v[164:167], v[180:183], v[48:51]
	v_mfma_f32_16x16x32_bf16 v[48:51], v[168:171], v[184:187], v[48:51]
	v_mfma_f32_16x16x32_bf16 v[40:43], v[172:175], v[180:183], v[40:43]
	v_mfma_f32_16x16x32_bf16 v[40:43], v[176:179], v[184:187], v[40:43]
	v_mfma_f32_16x16x32_bf16 v[32:35], v[164:167], v[188:191], v[32:35]
	v_mfma_f32_16x16x32_bf16 v[32:35], v[168:171], v[194:197], v[32:35]
	v_mfma_f32_16x16x32_bf16 v[24:27], v[172:175], v[188:191], v[24:27]
	v_mfma_f32_16x16x32_bf16 v[24:27], v[176:179], v[194:197], v[24:27]
	v_mfma_f32_16x16x32_bf16 v[16:19], v[164:167], v[198:201], v[16:19]
	v_mfma_f32_16x16x32_bf16 v[16:19], v[168:171], v[202:205], v[16:19]
	v_mfma_f32_16x16x32_bf16 v[8:11], v[172:175], v[198:201], v[8:11]
	v_mfma_f32_16x16x32_bf16 v[8:11], v[176:179], v[202:205], v[8:11]
	v_mfma_f32_16x16x32_bf16 v[4:7], v[164:167], v[206:209], v[4:7]
	v_mfma_f32_16x16x32_bf16 v[4:7], v[168:171], v[210:213], v[4:7]
	v_mfma_f32_16x16x32_bf16 v[0:3], v[172:175], v[206:209], v[0:3]
	v_mfma_f32_16x16x32_bf16 v[0:3], v[176:179], v[210:213], v[0:3]
	s_barrier
	s_setprio 0
	s_add_i32 s54, 0, 0x18000
	s_add_i32 s55, 0, 0x1c000
	v_add_u32_e32 v160, s54, v143
	v_add_u32_e32 v176, s55, v143
	ds_read_b128 v[148:151], v160
	ds_read_b128 v[152:155], v160 offset:1024
	ds_read_b128 v[156:159], v160 offset:2048
	ds_read_b128 v[160:163], v160 offset:3072
	ds_read_b128 v[164:167], v176
	ds_read_b128 v[168:171], v176 offset:1024
	ds_read_b128 v[172:175], v176 offset:2048
	ds_read_b128 v[176:179], v176 offset:3072
	s_add_u32 s34, s34, 0x80000
	s_addc_u32 s35, s35, 0
	s_mov_b32 m0, s40
	v_lshl_add_u64 v[220:221], s[34:35], 0, v[134:135]
	ds_read_b128 v[180:183], v147 offset:32768
	ds_read_b128 v[184:187], v147 offset:33792
	ds_read_b128 v[188:191], v147 offset:34816
	ds_read_b128 v[194:197], v147 offset:35840
	ds_read_b128 v[198:201], v147 offset:36864
	ds_read_b128 v[202:205], v147 offset:37888
	ds_read_b128 v[206:209], v147 offset:38912
	ds_read_b128 v[210:213], v147 offset:39936
	global_load_lds_dwordx4 v[220:221], off
	v_lshl_add_u64 v[220:221], s[34:35], 0, v[130:131]
	s_mov_b32 m0, s41
	s_nop 0
	global_load_lds_dwordx4 v[220:221], off
	s_waitcnt vmcnt(8)
	s_waitcnt lgkmcnt(0)
	s_setprio 1
	s_barrier
	v_mfma_f32_16x16x32_bf16 v[124:127], v[148:151], v[180:183], v[124:127]
	v_mfma_f32_16x16x32_bf16 v[124:127], v[152:155], v[184:187], v[124:127]
	v_mfma_f32_16x16x32_bf16 v[120:123], v[156:159], v[180:183], v[120:123]
	v_mfma_f32_16x16x32_bf16 v[120:123], v[160:163], v[184:187], v[120:123]
	v_mfma_f32_16x16x32_bf16 v[116:119], v[148:151], v[188:191], v[116:119]
	v_mfma_f32_16x16x32_bf16 v[116:119], v[152:155], v[194:197], v[116:119]
	v_mfma_f32_16x16x32_bf16 v[108:111], v[156:159], v[188:191], v[108:111]
	v_mfma_f32_16x16x32_bf16 v[108:111], v[160:163], v[194:197], v[108:111]
	v_mfma_f32_16x16x32_bf16 v[100:103], v[148:151], v[198:201], v[100:103]
	v_mfma_f32_16x16x32_bf16 v[100:103], v[152:155], v[202:205], v[100:103]
	v_mfma_f32_16x16x32_bf16 v[92:95], v[156:159], v[198:201], v[92:95]
	v_mfma_f32_16x16x32_bf16 v[92:95], v[160:163], v[202:205], v[92:95]
	v_mfma_f32_16x16x32_bf16 v[84:87], v[148:151], v[206:209], v[84:87]
	v_mfma_f32_16x16x32_bf16 v[84:87], v[152:155], v[210:213], v[84:87]
	v_mfma_f32_16x16x32_bf16 v[76:79], v[156:159], v[206:209], v[76:79]
	v_mfma_f32_16x16x32_bf16 v[76:79], v[160:163], v[210:213], v[76:79]
	s_setprio 0
	s_setprio 1
	v_mfma_f32_16x16x32_bf16 v[112:115], v[164:167], v[180:183], v[112:115]
	v_mfma_f32_16x16x32_bf16 v[112:115], v[168:171], v[184:187], v[112:115]
	v_mfma_f32_16x16x32_bf16 v[104:107], v[172:175], v[180:183], v[104:107]
	v_mfma_f32_16x16x32_bf16 v[104:107], v[176:179], v[184:187], v[104:107]
	v_mfma_f32_16x16x32_bf16 v[96:99], v[164:167], v[188:191], v[96:99]
	v_mfma_f32_16x16x32_bf16 v[96:99], v[168:171], v[194:197], v[96:99]
	v_mfma_f32_16x16x32_bf16 v[88:91], v[172:175], v[188:191], v[88:91]
	v_mfma_f32_16x16x32_bf16 v[88:91], v[176:179], v[194:197], v[88:91]
	v_mfma_f32_16x16x32_bf16 v[80:83], v[164:167], v[198:201], v[80:83]
	v_mfma_f32_16x16x32_bf16 v[80:83], v[168:171], v[202:205], v[80:83]
	v_mfma_f32_16x16x32_bf16 v[72:75], v[172:175], v[198:201], v[72:75]
	v_mfma_f32_16x16x32_bf16 v[72:75], v[176:179], v[202:205], v[72:75]
	v_mfma_f32_16x16x32_bf16 v[68:71], v[164:167], v[206:209], v[68:71]
	v_mfma_f32_16x16x32_bf16 v[68:71], v[168:171], v[210:213], v[68:71]
	v_mfma_f32_16x16x32_bf16 v[64:67], v[172:175], v[206:209], v[64:67]
	v_mfma_f32_16x16x32_bf16 v[64:67], v[176:179], v[210:213], v[64:67]
	s_barrier
; #define PG8_STAGE(bufoff, gbase, voff) do { _Pragma("unroll") for (int _i = 0; _i < 2; ++_i) \
;         __builtin_amdgcn_global_load_lds((const unsigned*)((const char*)(gbase) + (voff)[_i]), (LAS unsigned*)(lds + (bufoff) + ldsw + _i * 8192), 16, 0, 0); } while (0)
; #define PG8_LDA(dst, b, h) do { _Pragma("unroll") for (int m = 0; m < 4; ++m) _Pragma("unroll") for (int k = 0; k < 2; ++k) dst[m][k] = *(const LAS bf16x8*)(lds + PG8_SA(b, h) + aoff + m * 2048 + k * 1024); } while (0)
; #define PG8_MMA(ai, bj, At, Bt) do { __builtin_amdgcn_s_setprio(1); _Pragma("unroll") for (int m = 0; m < 4; ++m) _Pragma("unroll") for (int n = 0; n < 2; ++n) _Pragma("unroll") for (int k = 0; k < 2; ++k) \
;         acc[ai][bj][m][n] = __builtin_amdgcn_mfma_f32_16x16x32_bf16(Bt[n][k], At[m][k], acc[ai][bj][m][n], 0, 0, 0); __builtin_amdgcn_s_setprio(0); } while (0)
; #define PG8_WAIT_V(n) asm volatile("s_waitcnt vmcnt(" #n ")" ::: "memory")
; #define PG8_WAIT_L(n) asm volatile("s_waitcnt lgkmcnt(" #n ")" ::: "memory")
; #define PG8_BAR __builtin_amdgcn_s_barrier()
; #define PG8_SCHED __builtin_amdgcn_sched_barrier(0)
; template <class Epi, bool ALIGN_EPI>
; __device__ __forceinline__ void gemm_phase(LAS unsigned char* lds, const Gemm g, const StaticOrder& S, const Epi& E) {
;     ...
;             PG8_WAIT_V(8); PG8_WAIT_L(0); PG8_BAR; PG8_MMA(0, 0, At, B0); PG8_MMA(0, 1, At, B1); PG8_BAR; PG8_SCHED;
;             PG8_LDA(At, 1, 1); PG8_STAGE(PG8_SB(1, 0), b3, voffB); PG8_STAGE(PG8_SB(1, 1), b3 + hB, voffB); PG8_STAGE(PG8_SA(1, 0), a3, voffA);
;             PG8_WAIT_V(8); PG8_WAIT_L(0); PG8_BAR; PG8_MMA(1, 0, At, B0); PG8_MMA(1, 1, At, B1); PG8_BAR; PG8_SCHED;
;         }
;         if constexpr (ALIGN_EPI) { if (wr == 0) PG8_BAR; }
	s_setprio 0
	s_add_i32 s34, s54, s1
	v_lshl_add_u64 v[140:141], v[140:141], 0, s[10:11]
	s_mov_b32 m0, s34
	ds_read_b128 v[180:183], v147 offset:49152
	ds_read_b128 v[184:187], v147 offset:50176
	ds_read_b128 v[188:191], v147 offset:51200
	ds_read_b128 v[194:197], v147 offset:52224
	ds_read_b128 v[198:201], v147 offset:53248
	ds_read_b128 v[202:205], v147 offset:54272
	ds_read_b128 v[206:209], v147 offset:55296
	ds_read_b128 v[210:213], v147 offset:56320
	global_load_lds_dwordx4 v[140:141], off
	s_add_i32 m0, s34, 0x2000
	s_add_u32 s30, s30, 0x80080
	v_lshl_add_u64 v[140:141], v[214:215], 0, s[10:11]
	s_addc_u32 s31, s31, 0
	s_add_i32 s34, s55, s1
	global_load_lds_dwordx4 v[140:141], off
	v_lshl_add_u64 v[140:141], s[30:31], 0, v[132:133]
	s_mov_b32 m0, s34
	s_nop 0
	global_load_lds_dwordx4 v[140:141], off
	v_lshl_add_u64 v[140:141], s[30:31], 0, v[128:129]
	s_add_i32 m0, s34, 0x2000
	s_nop 0
	global_load_lds_dwordx4 v[140:141], off
	v_lshl_add_u64 v[140:141], v[216:217], 0, s[10:11]
	s_mov_b32 m0, s42
	s_nop 0
	global_load_lds_dwordx4 v[140:141], off
	v_lshl_add_u64 v[140:141], v[218:219], 0, s[10:11]
	s_mov_b32 m0, s43
	s_nop 0
	global_load_lds_dwordx4 v[140:141], off
	s_waitcnt vmcnt(8)
	s_waitcnt lgkmcnt(0)
	s_setprio 1
	s_barrier
	v_mfma_f32_16x16x32_bf16 v[60:63], v[148:151], v[180:183], v[60:63]
	v_mfma_f32_16x16x32_bf16 v[60:63], v[152:155], v[184:187], v[60:63]
	v_mfma_f32_16x16x32_bf16 v[56:59], v[156:159], v[180:183], v[56:59]
	v_mfma_f32_16x16x32_bf16 v[56:59], v[160:163], v[184:187], v[56:59]
	v_mfma_f32_16x16x32_bf16 v[52:55], v[148:151], v[188:191], v[52:55]
	v_mfma_f32_16x16x32_bf16 v[52:55], v[152:155], v[194:197], v[52:55]
	v_mfma_f32_16x16x32_bf16 v[44:47], v[156:159], v[188:191], v[44:47]
	v_mfma_f32_16x16x32_bf16 v[44:47], v[160:163], v[194:197], v[44:47]
	v_mfma_f32_16x16x32_bf16 v[36:39], v[148:151], v[198:201], v[36:39]
	v_mfma_f32_16x16x32_bf16 v[36:39], v[152:155], v[202:205], v[36:39]
	v_mfma_f32_16x16x32_bf16 v[28:31], v[156:159], v[198:201], v[28:31]
	v_mfma_f32_16x16x32_bf16 v[28:31], v[160:163], v[202:205], v[28:31]
	v_mfma_f32_16x16x32_bf16 v[20:23], v[148:151], v[206:209], v[20:23]
	v_mfma_f32_16x16x32_bf16 v[20:23], v[152:155], v[210:213], v[20:23]
	v_mfma_f32_16x16x32_bf16 v[12:15], v[156:159], v[206:209], v[12:15]
	v_mfma_f32_16x16x32_bf16 v[12:15], v[160:163], v[210:213], v[12:15]
	s_setprio 0
	s_setprio 1
	v_mfma_f32_16x16x32_bf16 v[48:51], v[164:167], v[180:183], v[48:51]
	v_mfma_f32_16x16x32_bf16 v[48:51], v[168:171], v[184:187], v[48:51]
	v_mfma_f32_16x16x32_bf16 v[40:43], v[172:175], v[180:183], v[40:43]
	v_mfma_f32_16x16x32_bf16 v[40:43], v[176:179], v[184:187], v[40:43]
	v_mfma_f32_16x16x32_bf16 v[32:35], v[164:167], v[188:191], v[32:35]
	v_mfma_f32_16x16x32_bf16 v[32:35], v[168:171], v[194:197], v[32:35]
	v_mfma_f32_16x16x32_bf16 v[24:27], v[172:175], v[188:191], v[24:27]
	v_mfma_f32_16x16x32_bf16 v[24:27], v[176:179], v[194:197], v[24:27]
	v_mfma_f32_16x16x32_bf16 v[16:19], v[164:167], v[198:201], v[16:19]
	v_mfma_f32_16x16x32_bf16 v[16:19], v[168:171], v[202:205], v[16:19]
	v_mfma_f32_16x16x32_bf16 v[8:11], v[172:175], v[198:201], v[8:11]
	v_mfma_f32_16x16x32_bf16 v[8:11], v[176:179], v[202:205], v[8:11]
	v_mfma_f32_16x16x32_bf16 v[4:7], v[164:167], v[206:209], v[4:7]
	v_mfma_f32_16x16x32_bf16 v[4:7], v[168:171], v[210:213], v[4:7]
	v_mfma_f32_16x16x32_bf16 v[0:3], v[172:175], v[206:209], v[0:3]
	v_mfma_f32_16x16x32_bf16 v[0:3], v[176:179], v[210:213], v[0:3]
	s_barrier
	s_setprio 0
	s_add_i32 s53, s53, 2
	s_add_u32 s28, s28, 0x100
	s_addc_u32 s29, s29, 0
	s_add_u32 s51, s51, 0x100
	s_addc_u32 s52, s52, 0
	s_cmp_gt_u32 s53, 29
	s_cbranch_scc0 .LBB0_419
	s_and_b64 vcc, exec, s[14:15]
	s_cbranch_vccz .LBB0_422
	s_barrier

; #define PG8_STAGE(bufoff, gbase, voff) do { _Pragma("unroll") for (int _i = 0; _i < 2; ++_i) \
;         __builtin_amdgcn_global_load_lds((const unsigned*)((const char*)(gbase) + (voff)[_i]), (LAS unsigned*)(lds + (bufoff) + ldsw + _i * 8192), 16, 0, 0); } while (0)
; #define PG8_LDA(dst, b, h) do { _Pragma("unroll") for (int m = 0; m < 4; ++m) _Pragma("unroll") for (int k = 0; k < 2; ++k) dst[m][k] = *(const LAS bf16x8*)(lds + PG8_SA(b, h) + aoff + m * 2048 + k * 1024); } while (0)
; #define PG8_LDB(dst, b, h) do { _Pragma("unroll") for (int n = 0; n < 2; ++n) _Pragma("unroll") for (int k = 0; k < 2; ++k) dst[n][k] = *(const LAS bf16x8*)(lds + PG8_SB(b, h) + boff + n * 2048 + k * 1024); } while (0)
; #define PG8_MMA(ai, bj, At, Bt) do { __builtin_amdgcn_s_setprio(1); _Pragma("unroll") for (int m = 0; m < 4; ++m) _Pragma("unroll") for (int n = 0; n < 2; ++n) _Pragma("unroll") for (int k = 0; k < 2; ++k) \
;         acc[ai][bj][m][n] = __builtin_amdgcn_mfma_f32_16x16x32_bf16(Bt[n][k], At[m][k], acc[ai][bj][m][n], 0, 0, 0); __builtin_amdgcn_s_setprio(0); } while (0)
; #define PG8_WAIT_V(n) asm volatile("s_waitcnt vmcnt(" #n ")" ::: "memory")
; #define PG8_WAIT_L(n) asm volatile("s_waitcnt lgkmcnt(" #n ")" ::: "memory")
; #define PG8_BAR __builtin_amdgcn_s_barrier()
; #define PG8_SCHED __builtin_amdgcn_sched_barrier(0)
; template <class Epi, bool ALIGN_EPI>
; __device__ __forceinline__ void gemm_phase(LAS unsigned char* lds, const Gemm g, const StaticOrder& S, const Epi& E) {
;     ...
;         for (int t = 0; t < nt; t += 2) {
;             const bool last = (t == nt - 2);
;             const char* a1 = cA + (size_t)(t + 1) * kstep;
;             const char* a2 = last ? nA : cA + (size_t)(t + 2) * kstep; const char* b2 = last ? nB : cB + (size_t)(t + 2) * kstep;
;             const char* a3 = a2 + kstep; const char* b3 = b2 + kstep;
;             PG8_LDB(B0, 0, 0); PG8_LDB(B1, 0, 1); PG8_SCHED; PG8_LDA(At, 0, 0); PG8_STAGE(PG8_SA(1, 1), a1 + hA, voffA);
;             PG8_WAIT_V(8); PG8_WAIT_L(0); PG8_BAR; PG8_MMA(0, 0, At, B0); PG8_MMA(0, 1, At, B1); PG8_BAR; PG8_SCHED;
;             PG8_LDA(At, 0, 1); PG8_STAGE(PG8_SB(0, 0), b2, voffB); PG8_STAGE(PG8_SB(0, 1), b2 + hB, voffB); PG8_STAGE(PG8_SA(0, 0), a2, voffA);
;             PG8_WAIT_V(8); PG8_WAIT_L(0); PG8_BAR; PG8_MMA(1, 0, At, B0); PG8_MMA(1, 1, At, B1); PG8_BAR; PG8_SCHED;
.LBB0_775:
	ds_read_b128 v[128:131], v196
	ds_read_b128 v[132:135], v196 offset:1024
	ds_read_b128 v[136:139], v196 offset:2048
	ds_read_b128 v[140:143], v196 offset:3072
	ds_read_b128 v[144:147], v197
	ds_read_b128 v[148:151], v197 offset:1024
	ds_read_b128 v[152:155], v197 offset:2048
	ds_read_b128 v[156:159], v197 offset:3072
	s_add_u32 s37, s40, 0xfff80080
	s_addc_u32 s38, s41, -1
	s_cmp_eq_u32 s29, 28
	s_cselect_b32 s45, s0, s38
	s_cselect_b32 s44, s1, s37
	s_cselect_b32 s43, s2, s27
	s_cselect_b32 s42, s3, s9
	v_lshl_add_u64 v[216:217], s[40:41], 0, v[168:169]
	s_add_i32 m0, s50, 0xc000
	ds_read_b128 v[176:179], v198
	ds_read_b128 v[180:183], v198 offset:1024
	ds_read_b128 v[184:187], v198 offset:2048
	ds_read_b128 v[188:191], v198 offset:3072
	ds_read_b128 v[200:203], v198 offset:4096
	ds_read_b128 v[204:207], v198 offset:5120
	ds_read_b128 v[208:211], v198 offset:6144
	ds_read_b128 v[212:215], v198 offset:7168
	global_load_lds_dwordx4 v[216:217], off
	v_lshl_add_u64 v[216:217], s[40:41], 0, v[170:171]
	s_add_i32 m0, s50, 0xe000
	s_nop 0
	global_load_lds_dwordx4 v[216:217], off
	s_waitcnt vmcnt(8)
	s_waitcnt lgkmcnt(0)
	s_setprio 1
	s_barrier
	v_mfma_f32_16x16x32_bf16 v[124:127], v[128:131], v[176:179], v[124:127]
	v_mfma_f32_16x16x32_bf16 v[124:127], v[132:135], v[180:183], v[124:127]
	v_mfma_f32_16x16x32_bf16 v[120:123], v[136:139], v[176:179], v[120:123]
	v_mfma_f32_16x16x32_bf16 v[120:123], v[140:143], v[180:183], v[120:123]
	v_mfma_f32_16x16x32_bf16 v[108:111], v[128:131], v[184:187], v[108:111]
	v_mfma_f32_16x16x32_bf16 v[108:111], v[132:135], v[188:191], v[108:111]
	v_mfma_f32_16x16x32_bf16 v[104:107], v[136:139], v[184:187], v[104:107]
	v_mfma_f32_16x16x32_bf16 v[104:107], v[140:143], v[188:191], v[104:107]
	v_mfma_f32_16x16x32_bf16 v[92:95], v[128:131], v[200:203], v[92:95]
	v_mfma_f32_16x16x32_bf16 v[92:95], v[132:135], v[204:207], v[92:95]
	v_mfma_f32_16x16x32_bf16 v[88:91], v[136:139], v[200:203], v[88:91]
	v_mfma_f32_16x16x32_bf16 v[88:91], v[140:143], v[204:207], v[88:91]
	v_mfma_f32_16x16x32_bf16 v[76:79], v[128:131], v[208:211], v[76:79]
	v_mfma_f32_16x16x32_bf16 v[76:79], v[132:135], v[212:215], v[76:79]
	v_mfma_f32_16x16x32_bf16 v[72:75], v[136:139], v[208:211], v[72:75]
	v_mfma_f32_16x16x32_bf16 v[72:75], v[140:143], v[212:215], v[72:75]
	s_setprio 0
	s_setprio 1
	v_mfma_f32_16x16x32_bf16 v[116:119], v[144:147], v[176:179], v[116:119]
	v_mfma_f32_16x16x32_bf16 v[116:119], v[148:151], v[180:183], v[116:119]
	v_mfma_f32_16x16x32_bf16 v[112:115], v[152:155], v[176:179], v[112:115]
	v_mfma_f32_16x16x32_bf16 v[112:115], v[156:159], v[180:183], v[112:115]
	v_mfma_f32_16x16x32_bf16 v[100:103], v[144:147], v[184:187], v[100:103]
	v_mfma_f32_16x16x32_bf16 v[100:103], v[148:151], v[188:191], v[100:103]
	v_mfma_f32_16x16x32_bf16 v[96:99], v[152:155], v[184:187], v[96:99]
	v_mfma_f32_16x16x32_bf16 v[96:99], v[156:159], v[188:191], v[96:99]
	v_mfma_f32_16x16x32_bf16 v[84:87], v[144:147], v[200:203], v[84:87]
	v_mfma_f32_16x16x32_bf16 v[84:87], v[148:151], v[204:207], v[84:87]
	v_mfma_f32_16x16x32_bf16 v[80:83], v[152:155], v[200:203], v[80:83]
	v_mfma_f32_16x16x32_bf16 v[80:83], v[156:159], v[204:207], v[80:83]
	v_mfma_f32_16x16x32_bf16 v[68:71], v[144:147], v[208:211], v[68:71]
	v_mfma_f32_16x16x32_bf16 v[68:71], v[148:151], v[212:215], v[68:71]
	v_mfma_f32_16x16x32_bf16 v[64:67], v[152:155], v[208:211], v[64:67]
	v_mfma_f32_16x16x32_bf16 v[64:67], v[156:159], v[212:215], v[64:67]
	s_barrier
	s_setprio 0
	s_add_i32 s37, s60, s49
	v_lshl_add_u64 v[216:217], s[42:43], 0, v[162:163]
	s_mov_b32 m0, s37
	ds_read_b128 v[176:179], v198 offset:16384
	ds_read_b128 v[180:183], v198 offset:17408
	ds_read_b128 v[184:187], v198 offset:18432
	ds_read_b128 v[188:191], v198 offset:19456
	ds_read_b128 v[200:203], v198 offset:20480
	ds_read_b128 v[204:207], v198 offset:21504
	ds_read_b128 v[208:211], v198 offset:22528
	ds_read_b128 v[212:215], v198 offset:23552
	global_load_lds_dwordx4 v[216:217], off
	s_add_i32 m0, s37, 0x2000
	s_add_u32 s38, s42, 0x80000
	v_lshl_add_u64 v[218:219], s[42:43], 0, v[166:167]
	s_addc_u32 s39, s43, 0
	s_add_i32 s37, s61, s49
	global_load_lds_dwordx4 v[218:219], off
	v_lshl_add_u64 v[220:221], s[38:39], 0, v[162:163]
	s_mov_b32 m0, s37
	v_lshl_add_u64 v[222:223], s[44:45], 0, v[164:165]
	global_load_lds_dwordx4 v[220:221], off
	v_lshl_add_u64 v[220:221], s[38:39], 0, v[166:167]
	s_add_i32 m0, s37, 0x2000
	s_nop 0
	global_load_lds_dwordx4 v[220:221], off
	v_lshl_add_u64 v[220:221], s[44:45], 0, v[160:161]
	s_mov_b32 m0, s50
	s_nop 0
	global_load_lds_dwordx4 v[220:221], off
	s_mov_b32 m0, s51
	s_nop 0
	global_load_lds_dwordx4 v[222:223], off
	s_waitcnt vmcnt(8)
	s_waitcnt lgkmcnt(0)
	s_setprio 1
	s_barrier
; #define PG8_STAGE(bufoff, gbase, voff) do { _Pragma("unroll") for (int _i = 0; _i < 2; ++_i) \
;         __builtin_amdgcn_global_load_lds((const unsigned*)((const char*)(gbase) + (voff)[_i]), (LAS unsigned*)(lds + (bufoff) + ldsw + _i * 8192), 16, 0, 0); } while (0)
; #define PG8_LDA(dst, b, h) do { _Pragma("unroll") for (int m = 0; m < 4; ++m) _Pragma("unroll") for (int k = 0; k < 2; ++k) dst[m][k] = *(const LAS bf16x8*)(lds + PG8_SA(b, h) + aoff + m * 2048 + k * 1024); } while (0)
; #define PG8_LDB(dst, b, h) do { _Pragma("unroll") for (int n = 0; n < 2; ++n) _Pragma("unroll") for (int k = 0; k < 2; ++k) dst[n][k] = *(const LAS bf16x8*)(lds + PG8_SB(b, h) + boff + n * 2048 + k * 1024); } while (0)
; #define PG8_MMA(ai, bj, At, Bt) do { __builtin_amdgcn_s_setprio(1); _Pragma("unroll") for (int m = 0; m < 4; ++m) _Pragma("unroll") for (int n = 0; n < 2; ++n) _Pragma("unroll") for (int k = 0; k < 2; ++k) \
;         acc[ai][bj][m][n] = __builtin_amdgcn_mfma_f32_16x16x32_bf16(Bt[n][k], At[m][k], acc[ai][bj][m][n], 0, 0, 0); __builtin_amdgcn_s_setprio(0); } while (0)
; #define PG8_WAIT_V(n) asm volatile("s_waitcnt vmcnt(" #n ")" ::: "memory")
; #define PG8_WAIT_L(n) asm volatile("s_waitcnt lgkmcnt(" #n ")" ::: "memory")
; #define PG8_BAR __builtin_amdgcn_s_barrier()
; #define PG8_SCHED __builtin_amdgcn_sched_barrier(0)
; template <class Epi, bool ALIGN_EPI>
; __device__ __forceinline__ void gemm_phase(LAS unsigned char* lds, const Gemm g, const StaticOrder& S, const Epi& E) {
;     ...
;             PG8_WAIT_V(8); PG8_WAIT_L(0); PG8_BAR; PG8_MMA(1, 0, At, B0); PG8_MMA(1, 1, At, B1); PG8_BAR; PG8_SCHED;
;             PG8_LDB(B0, 1, 0); PG8_LDB(B1, 1, 1); PG8_SCHED; PG8_LDA(At, 1, 0); PG8_STAGE(PG8_SA(0, 1), a2 + hA, voffA);
;             PG8_WAIT_V(8); PG8_WAIT_L(0); PG8_BAR; PG8_MMA(0, 0, At, B0); PG8_MMA(0, 1, At, B1); PG8_BAR; PG8_SCHED;
	v_mfma_f32_16x16x32_bf16 v[60:63], v[128:131], v[176:179], v[60:63]
	v_mfma_f32_16x16x32_bf16 v[60:63], v[132:135], v[180:183], v[60:63]
	v_mfma_f32_16x16x32_bf16 v[56:59], v[136:139], v[176:179], v[56:59]
	v_mfma_f32_16x16x32_bf16 v[56:59], v[140:143], v[180:183], v[56:59]
	v_mfma_f32_16x16x32_bf16 v[44:47], v[128:131], v[184:187], v[44:47]
	v_mfma_f32_16x16x32_bf16 v[44:47], v[132:135], v[188:191], v[44:47]
	v_mfma_f32_16x16x32_bf16 v[40:43], v[136:139], v[184:187], v[40:43]
	v_mfma_f32_16x16x32_bf16 v[40:43], v[140:143], v[188:191], v[40:43]
	v_mfma_f32_16x16x32_bf16 v[28:31], v[128:131], v[200:203], v[28:31]
	v_mfma_f32_16x16x32_bf16 v[28:31], v[132:135], v[204:207], v[28:31]
	v_mfma_f32_16x16x32_bf16 v[24:27], v[136:139], v[200:203], v[24:27]
	v_mfma_f32_16x16x32_bf16 v[24:27], v[140:143], v[204:207], v[24:27]
	v_mfma_f32_16x16x32_bf16 v[16:19], v[128:131], v[208:211], v[16:19]
	v_mfma_f32_16x16x32_bf16 v[16:19], v[132:135], v[212:215], v[16:19]
	v_mfma_f32_16x16x32_bf16 v[8:11], v[136:139], v[208:211], v[8:11]
	v_mfma_f32_16x16x32_bf16 v[8:11], v[140:143], v[212:215], v[8:11]
	s_setprio 0
	s_setprio 1
	v_mfma_f32_16x16x32_bf16 v[52:55], v[144:147], v[176:179], v[52:55]
	v_mfma_f32_16x16x32_bf16 v[52:55], v[148:151], v[180:183], v[52:55]
	v_mfma_f32_16x16x32_bf16 v[48:51], v[152:155], v[176:179], v[48:51]
	v_mfma_f32_16x16x32_bf16 v[48:51], v[156:159], v[180:183], v[48:51]
	v_mfma_f32_16x16x32_bf16 v[36:39], v[144:147], v[184:187], v[36:39]
	v_mfma_f32_16x16x32_bf16 v[36:39], v[148:151], v[188:191], v[36:39]
	v_mfma_f32_16x16x32_bf16 v[32:35], v[152:155], v[184:187], v[32:35]
	v_mfma_f32_16x16x32_bf16 v[32:35], v[156:159], v[188:191], v[32:35]
	v_mfma_f32_16x16x32_bf16 v[20:23], v[144:147], v[200:203], v[20:23]
	v_mfma_f32_16x16x32_bf16 v[20:23], v[148:151], v[204:207], v[20:23]
	v_mfma_f32_16x16x32_bf16 v[12:15], v[152:155], v[200:203], v[12:15]
	v_mfma_f32_16x16x32_bf16 v[12:15], v[156:159], v[204:207], v[12:15]
	v_mfma_f32_16x16x32_bf16 v[4:7], v[144:147], v[208:211], v[4:7]
	v_mfma_f32_16x16x32_bf16 v[4:7], v[148:151], v[212:215], v[4:7]
	v_mfma_f32_16x16x32_bf16 v[0:3], v[152:155], v[208:211], v[0:3]
	v_mfma_f32_16x16x32_bf16 v[0:3], v[156:159], v[212:215], v[0:3]
	s_barrier
	s_setprio 0
	s_add_i32 s37, 0, 0x18000
	s_add_i32 s63, 0, 0x1c000
	v_add_u32_e32 v140, s37, v194
	v_add_u32_e32 v156, s63, v194
	ds_read_b128 v[128:131], v140
	ds_read_b128 v[132:135], v140 offset:1024
	ds_read_b128 v[136:139], v140 offset:2048
	ds_read_b128 v[140:143], v140 offset:3072
	ds_read_b128 v[144:147], v156
	ds_read_b128 v[148:151], v156 offset:1024
	ds_read_b128 v[152:155], v156 offset:2048
	ds_read_b128 v[156:159], v156 offset:3072
	s_add_u32 s38, s44, 0x80000
	s_addc_u32 s39, s45, 0
	s_mov_b32 m0, s52
	v_lshl_add_u64 v[224:225], s[38:39], 0, v[160:161]
	ds_read_b128 v[176:179], v198 offset:32768
	ds_read_b128 v[180:183], v198 offset:33792
	ds_read_b128 v[184:187], v198 offset:34816
	ds_read_b128 v[188:191], v198 offset:35840
	ds_read_b128 v[200:203], v198 offset:36864
	ds_read_b128 v[204:207], v198 offset:37888
	ds_read_b128 v[208:211], v198 offset:38912
	ds_read_b128 v[212:215], v198 offset:39936
	global_load_lds_dwordx4 v[224:225], off
	v_lshl_add_u64 v[224:225], s[38:39], 0, v[164:165]
	s_mov_b32 m0, s53
	s_nop 0
	global_load_lds_dwordx4 v[224:225], off
	s_waitcnt vmcnt(8)
	s_waitcnt lgkmcnt(0)
	s_setprio 1
	s_barrier
	v_mfma_f32_16x16x32_bf16 v[124:127], v[128:131], v[176:179], v[124:127]
	v_mfma_f32_16x16x32_bf16 v[124:127], v[132:135], v[180:183], v[124:127]
	v_mfma_f32_16x16x32_bf16 v[120:123], v[136:139], v[176:179], v[120:123]
	v_mfma_f32_16x16x32_bf16 v[120:123], v[140:143], v[180:183], v[120:123]
	v_mfma_f32_16x16x32_bf16 v[108:111], v[128:131], v[184:187], v[108:111]
	v_mfma_f32_16x16x32_bf16 v[108:111], v[132:135], v[188:191], v[108:111]
	v_mfma_f32_16x16x32_bf16 v[104:107], v[136:139], v[184:187], v[104:107]
	v_mfma_f32_16x16x32_bf16 v[104:107], v[140:143], v[188:191], v[104:107]
	v_mfma_f32_16x16x32_bf16 v[92:95], v[128:131], v[200:203], v[92:95]
	v_mfma_f32_16x16x32_bf16 v[92:95], v[132:135], v[204:207], v[92:95]
	v_mfma_f32_16x16x32_bf16 v[88:91], v[136:139], v[200:203], v[88:91]
	v_mfma_f32_16x16x32_bf16 v[88:91], v[140:143], v[204:207], v[88:91]
	v_mfma_f32_16x16x32_bf16 v[76:79], v[128:131], v[208:211], v[76:79]
	v_mfma_f32_16x16x32_bf16 v[76:79], v[132:135], v[212:215], v[76:79]
	v_mfma_f32_16x16x32_bf16 v[72:75], v[136:139], v[208:211], v[72:75]
	v_mfma_f32_16x16x32_bf16 v[72:75], v[140:143], v[212:215], v[72:75]
	s_setprio 0
	s_setprio 1
	v_mfma_f32_16x16x32_bf16 v[116:119], v[144:147], v[176:179], v[116:119]
	v_mfma_f32_16x16x32_bf16 v[116:119], v[148:151], v[180:183], v[116:119]
	v_mfma_f32_16x16x32_bf16 v[112:115], v[152:155], v[176:179], v[112:115]
	v_mfma_f32_16x16x32_bf16 v[112:115], v[156:159], v[180:183], v[112:115]
	v_mfma_f32_16x16x32_bf16 v[100:103], v[144:147], v[184:187], v[100:103]
	v_mfma_f32_16x16x32_bf16 v[100:103], v[148:151], v[188:191], v[100:103]
	v_mfma_f32_16x16x32_bf16 v[96:99], v[152:155], v[184:187], v[96:99]
	v_mfma_f32_16x16x32_bf16 v[96:99], v[156:159], v[188:191], v[96:99]
	v_mfma_f32_16x16x32_bf16 v[84:87], v[144:147], v[200:203], v[84:87]
	v_mfma_f32_16x16x32_bf16 v[84:87], v[148:151], v[204:207], v[84:87]
	v_mfma_f32_16x16x32_bf16 v[80:83], v[152:155], v[200:203], v[80:83]
	v_mfma_f32_16x16x32_bf16 v[80:83], v[156:159], v[204:207], v[80:83]
	v_mfma_f32_16x16x32_bf16 v[68:71], v[144:147], v[208:211], v[68:71]
	v_mfma_f32_16x16x32_bf16 v[68:71], v[148:151], v[212:215], v[68:71]
	v_mfma_f32_16x16x32_bf16 v[64:67], v[152:155], v[208:211], v[64:67]
	v_mfma_f32_16x16x32_bf16 v[64:67], v[156:159], v[212:215], v[64:67]
	s_barrier
; #define PG8_STAGE(bufoff, gbase, voff) do { _Pragma("unroll") for (int _i = 0; _i < 2; ++_i) \
;         __builtin_amdgcn_global_load_lds((const unsigned*)((const char*)(gbase) + (voff)[_i]), (LAS unsigned*)(lds + (bufoff) + ldsw + _i * 8192), 16, 0, 0); } while (0)
; #define PG8_LDA(dst, b, h) do { _Pragma("unroll") for (int m = 0; m < 4; ++m) _Pragma("unroll") for (int k = 0; k < 2; ++k) dst[m][k] = *(const LAS bf16x8*)(lds + PG8_SA(b, h) + aoff + m * 2048 + k * 1024); } while (0)
; #define PG8_MMA(ai, bj, At, Bt) do { __builtin_amdgcn_s_setprio(1); _Pragma("unroll") for (int m = 0; m < 4; ++m) _Pragma("unroll") for (int n = 0; n < 2; ++n) _Pragma("unroll") for (int k = 0; k < 2; ++k) \
;         acc[ai][bj][m][n] = __builtin_amdgcn_mfma_f32_16x16x32_bf16(Bt[n][k], At[m][k], acc[ai][bj][m][n], 0, 0, 0); __builtin_amdgcn_s_setprio(0); } while (0)
; #define PG8_WAIT_V(n) asm volatile("s_waitcnt vmcnt(" #n ")" ::: "memory")
; #define PG8_WAIT_L(n) asm volatile("s_waitcnt lgkmcnt(" #n ")" ::: "memory")
; #define PG8_BAR __builtin_amdgcn_s_barrier()
; #define PG8_SCHED __builtin_amdgcn_sched_barrier(0)
; template <class Epi, bool ALIGN_EPI>
; __device__ __forceinline__ void gemm_phase(LAS unsigned char* lds, const Gemm g, const StaticOrder& S, const Epi& E) {
;     ...
;             PG8_WAIT_V(8); PG8_WAIT_L(0); PG8_BAR; PG8_MMA(0, 0, At, B0); PG8_MMA(0, 1, At, B1); PG8_BAR; PG8_SCHED;
;             PG8_LDA(At, 1, 1); PG8_STAGE(PG8_SB(1, 0), b3, voffB); PG8_STAGE(PG8_SB(1, 1), b3 + hB, voffB); PG8_STAGE(PG8_SA(1, 0), a3, voffA);
;             PG8_WAIT_V(8); PG8_WAIT_L(0); PG8_BAR; PG8_MMA(1, 0, At, B0); PG8_MMA(1, 1, At, B1); PG8_BAR; PG8_SCHED;
;         }
;         if constexpr (ALIGN_EPI) { if (wr == 0) PG8_BAR; }
	s_setprio 0
	s_add_i32 s37, s37, s49
	v_lshl_add_u64 v[216:217], v[216:217], 0, s[20:21]
	s_mov_b32 m0, s37
	ds_read_b128 v[176:179], v198 offset:49152
	ds_read_b128 v[180:183], v198 offset:50176
	ds_read_b128 v[184:187], v198 offset:51200
	ds_read_b128 v[188:191], v198 offset:52224
	ds_read_b128 v[200:203], v198 offset:53248
	ds_read_b128 v[204:207], v198 offset:54272
	ds_read_b128 v[208:211], v198 offset:55296
	ds_read_b128 v[212:215], v198 offset:56320
	global_load_lds_dwordx4 v[216:217], off
	s_add_i32 m0, s37, 0x2000
	s_add_u32 s38, s42, 0x80080
	v_lshl_add_u64 v[216:217], v[218:219], 0, s[20:21]
	s_addc_u32 s39, s43, 0
	s_add_i32 s37, s63, s49
	global_load_lds_dwordx4 v[216:217], off
	v_lshl_add_u64 v[216:217], s[38:39], 0, v[162:163]
	s_mov_b32 m0, s37
	s_nop 0
	global_load_lds_dwordx4 v[216:217], off
	v_lshl_add_u64 v[216:217], s[38:39], 0, v[166:167]
	s_add_i32 m0, s37, 0x2000
	s_nop 0
	global_load_lds_dwordx4 v[216:217], off
	v_lshl_add_u64 v[216:217], v[220:221], 0, s[20:21]
	s_mov_b32 m0, s57
	s_nop 0
	global_load_lds_dwordx4 v[216:217], off
	v_lshl_add_u64 v[216:217], v[222:223], 0, s[20:21]
	s_mov_b32 m0, s58
	s_nop 0
	global_load_lds_dwordx4 v[216:217], off
	s_waitcnt vmcnt(8)
	s_waitcnt lgkmcnt(0)
	s_setprio 1
	s_barrier
	v_mfma_f32_16x16x32_bf16 v[60:63], v[128:131], v[176:179], v[60:63]
	v_mfma_f32_16x16x32_bf16 v[60:63], v[132:135], v[180:183], v[60:63]
	v_mfma_f32_16x16x32_bf16 v[56:59], v[136:139], v[176:179], v[56:59]
	v_mfma_f32_16x16x32_bf16 v[56:59], v[140:143], v[180:183], v[56:59]
	v_mfma_f32_16x16x32_bf16 v[44:47], v[128:131], v[184:187], v[44:47]
	v_mfma_f32_16x16x32_bf16 v[44:47], v[132:135], v[188:191], v[44:47]
	v_mfma_f32_16x16x32_bf16 v[40:43], v[136:139], v[184:187], v[40:43]
	v_mfma_f32_16x16x32_bf16 v[40:43], v[140:143], v[188:191], v[40:43]
	v_mfma_f32_16x16x32_bf16 v[28:31], v[128:131], v[200:203], v[28:31]
	v_mfma_f32_16x16x32_bf16 v[28:31], v[132:135], v[204:207], v[28:31]
	v_mfma_f32_16x16x32_bf16 v[24:27], v[136:139], v[200:203], v[24:27]
	v_mfma_f32_16x16x32_bf16 v[24:27], v[140:143], v[204:207], v[24:27]
	v_mfma_f32_16x16x32_bf16 v[16:19], v[128:131], v[208:211], v[16:19]
	v_mfma_f32_16x16x32_bf16 v[16:19], v[132:135], v[212:215], v[16:19]
	v_mfma_f32_16x16x32_bf16 v[8:11], v[136:139], v[208:211], v[8:11]
	v_mfma_f32_16x16x32_bf16 v[8:11], v[140:143], v[212:215], v[8:11]
	s_setprio 0
	s_setprio 1
	v_mfma_f32_16x16x32_bf16 v[52:55], v[144:147], v[176:179], v[52:55]
	v_mfma_f32_16x16x32_bf16 v[52:55], v[148:151], v[180:183], v[52:55]
	v_mfma_f32_16x16x32_bf16 v[48:51], v[152:155], v[176:179], v[48:51]
	v_mfma_f32_16x16x32_bf16 v[48:51], v[156:159], v[180:183], v[48:51]
	v_mfma_f32_16x16x32_bf16 v[36:39], v[144:147], v[184:187], v[36:39]
	v_mfma_f32_16x16x32_bf16 v[36:39], v[148:151], v[188:191], v[36:39]
	v_mfma_f32_16x16x32_bf16 v[32:35], v[152:155], v[184:187], v[32:35]
	v_mfma_f32_16x16x32_bf16 v[32:35], v[156:159], v[188:191], v[32:35]
	v_mfma_f32_16x16x32_bf16 v[20:23], v[144:147], v[200:203], v[20:23]
	v_mfma_f32_16x16x32_bf16 v[20:23], v[148:151], v[204:207], v[20:23]
	v_mfma_f32_16x16x32_bf16 v[12:15], v[152:155], v[200:203], v[12:15]
	v_mfma_f32_16x16x32_bf16 v[12:15], v[156:159], v[204:207], v[12:15]
	v_mfma_f32_16x16x32_bf16 v[4:7], v[144:147], v[208:211], v[4:7]
	v_mfma_f32_16x16x32_bf16 v[4:7], v[148:151], v[212:215], v[4:7]
	v_mfma_f32_16x16x32_bf16 v[0:3], v[152:155], v[208:211], v[0:3]
	v_mfma_f32_16x16x32_bf16 v[0:3], v[156:159], v[212:215], v[0:3]
	s_barrier
	s_setprio 0
	s_add_i32 s29, s29, 2
	s_add_u32 s40, s40, 0x100
	s_addc_u32 s41, s41, 0
	s_add_u32 s9, s9, 0x100
	s_addc_u32 s27, s27, 0
	s_cmp_gt_u32 s29, 29
	s_cbranch_scc0 .LBB0_775
	s_and_b64 vcc, exec, s[22:23]
	s_cbranch_vccz .LBB0_778
	s_barrier

; #define PG8_STAGE(bufoff, gbase, voff) do { _Pragma("unroll") for (int _i = 0; _i < 2; ++_i) \
;         __builtin_amdgcn_global_load_lds((const unsigned*)((const char*)(gbase) + (voff)[_i]), (LAS unsigned*)(lds + (bufoff) + ldsw + _i * 8192), 16, 0, 0); } while (0)
; #define PG8_LDA(dst, b, h) do { _Pragma("unroll") for (int m = 0; m < 4; ++m) _Pragma("unroll") for (int k = 0; k < 2; ++k) dst[m][k] = *(const LAS bf16x8*)(lds + PG8_SA(b, h) + aoff + m * 2048 + k * 1024); } while (0)
; #define PG8_LDB(dst, b, h) do { _Pragma("unroll") for (int n = 0; n < 2; ++n) _Pragma("unroll") for (int k = 0; k < 2; ++k) dst[n][k] = *(const LAS bf16x8*)(lds + PG8_SB(b, h) + boff + n * 2048 + k * 1024); } while (0)
; #define PG8_MMA(ai, bj, At, Bt) do { __builtin_amdgcn_s_setprio(1); _Pragma("unroll") for (int m = 0; m < 4; ++m) _Pragma("unroll") for (int n = 0; n < 2; ++n) _Pragma("unroll") for (int k = 0; k < 2; ++k) \
;         acc[ai][bj][m][n] = __builtin_amdgcn_mfma_f32_16x16x32_bf16(Bt[n][k], At[m][k], acc[ai][bj][m][n], 0, 0, 0); __builtin_amdgcn_s_setprio(0); } while (0)
; #define PG8_WAIT_V(n) asm volatile("s_waitcnt vmcnt(" #n ")" ::: "memory")
; #define PG8_WAIT_L(n) asm volatile("s_waitcnt lgkmcnt(" #n ")" ::: "memory")
; #define PG8_BAR __builtin_amdgcn_s_barrier()
; #define PG8_SCHED __builtin_amdgcn_sched_barrier(0)
; template <class Epi, bool ALIGN_EPI>
; __device__ __forceinline__ void gemm_phase(LAS unsigned char* lds, const Gemm g, const StaticOrder& S, const Epi& E) {
;     ...
;         for (int t = 0; t < nt; t += 2) {
;             const bool last = (t == nt - 2);
;             const char* a1 = cA + (size_t)(t + 1) * kstep;
;             const char* a2 = last ? nA : cA + (size_t)(t + 2) * kstep; const char* b2 = last ? nB : cB + (size_t)(t + 2) * kstep;
;             const char* a3 = a2 + kstep; const char* b3 = b2 + kstep;
;             PG8_LDB(B0, 0, 0); PG8_LDB(B1, 0, 1); PG8_SCHED; PG8_LDA(At, 0, 0); PG8_STAGE(PG8_SA(1, 1), a1 + hA, voffA);
;             PG8_WAIT_V(8); PG8_WAIT_L(0); PG8_BAR; PG8_MMA(0, 0, At, B0); PG8_MMA(0, 1, At, B1); PG8_BAR; PG8_SCHED;
;             PG8_LDA(At, 0, 1); PG8_STAGE(PG8_SB(0, 0), b2, voffB); PG8_STAGE(PG8_SB(0, 1), b2 + hB, voffB); PG8_STAGE(PG8_SA(0, 0), a2, voffA);
;             PG8_WAIT_V(8); PG8_WAIT_L(0); PG8_BAR; PG8_MMA(1, 0, At, B0); PG8_MMA(1, 1, At, B1); PG8_BAR; PG8_SCHED;
.LBB0_926:
	ds_read_b128 v[168:171], v153
	ds_read_b128 v[172:175], v153 offset:1024
	ds_read_b128 v[176:179], v153 offset:2048
	ds_read_b128 v[180:183], v153 offset:3072
	ds_read_b128 v[184:187], v155
	ds_read_b128 v[188:191], v155 offset:1024
	ds_read_b128 v[194:197], v155 offset:2048
	ds_read_b128 v[198:201], v155 offset:3072
	s_add_u32 s8, s6, 0xfff80080
	s_addc_u32 s9, s7, -1
	s_cmp_eq_u32 s71, 28
	s_cselect_b32 s55, s47, s9
	s_cselect_b32 s54, s67, s8
	s_cselect_b32 s9, s45, s70
	s_cselect_b32 s8, s68, s69
	v_lshl_add_u64 v[234:235], s[6:7], 0, v[136:137]
	s_add_i32 m0, s39, 0xc000
	ds_read_b128 v[202:205], v156
	ds_read_b128 v[206:209], v156 offset:1024
	ds_read_b128 v[210:213], v156 offset:2048
	ds_read_b128 v[214:217], v156 offset:3072
	ds_read_b128 v[218:221], v156 offset:4096
	ds_read_b128 v[222:225], v156 offset:5120
	ds_read_b128 v[226:229], v156 offset:6144
	ds_read_b128 v[230:233], v156 offset:7168
	global_load_lds_dwordx4 v[234:235], off
	v_lshl_add_u64 v[234:235], s[6:7], 0, v[138:139]
	s_add_i32 m0, s39, 0xe000
	s_nop 0
	global_load_lds_dwordx4 v[234:235], off
	s_waitcnt vmcnt(8)
	s_waitcnt lgkmcnt(0)
	s_setprio 1
	s_barrier
	v_mfma_f32_16x16x32_bf16 v[124:127], v[168:171], v[202:205], v[124:127]
	v_mfma_f32_16x16x32_bf16 v[124:127], v[172:175], v[206:209], v[124:127]
	v_mfma_f32_16x16x32_bf16 v[120:123], v[176:179], v[202:205], v[120:123]
	v_mfma_f32_16x16x32_bf16 v[120:123], v[180:183], v[206:209], v[120:123]
	v_mfma_f32_16x16x32_bf16 v[108:111], v[168:171], v[210:213], v[108:111]
	v_mfma_f32_16x16x32_bf16 v[108:111], v[172:175], v[214:217], v[108:111]
	v_mfma_f32_16x16x32_bf16 v[104:107], v[176:179], v[210:213], v[104:107]
	v_mfma_f32_16x16x32_bf16 v[104:107], v[180:183], v[214:217], v[104:107]
	v_mfma_f32_16x16x32_bf16 v[92:95], v[168:171], v[218:221], v[92:95]
	v_mfma_f32_16x16x32_bf16 v[92:95], v[172:175], v[222:225], v[92:95]
	v_mfma_f32_16x16x32_bf16 v[88:91], v[176:179], v[218:221], v[88:91]
	v_mfma_f32_16x16x32_bf16 v[88:91], v[180:183], v[222:225], v[88:91]
	v_mfma_f32_16x16x32_bf16 v[76:79], v[168:171], v[226:229], v[76:79]
	v_mfma_f32_16x16x32_bf16 v[76:79], v[172:175], v[230:233], v[76:79]
	v_mfma_f32_16x16x32_bf16 v[72:75], v[176:179], v[226:229], v[72:75]
	v_mfma_f32_16x16x32_bf16 v[72:75], v[180:183], v[230:233], v[72:75]
	s_setprio 0
	s_setprio 1
	v_mfma_f32_16x16x32_bf16 v[116:119], v[184:187], v[202:205], v[116:119]
	v_mfma_f32_16x16x32_bf16 v[116:119], v[188:191], v[206:209], v[116:119]
	v_mfma_f32_16x16x32_bf16 v[112:115], v[194:197], v[202:205], v[112:115]
	v_mfma_f32_16x16x32_bf16 v[112:115], v[198:201], v[206:209], v[112:115]
	v_mfma_f32_16x16x32_bf16 v[100:103], v[184:187], v[210:213], v[100:103]
	v_mfma_f32_16x16x32_bf16 v[100:103], v[188:191], v[214:217], v[100:103]
	v_mfma_f32_16x16x32_bf16 v[96:99], v[194:197], v[210:213], v[96:99]
	v_mfma_f32_16x16x32_bf16 v[96:99], v[198:201], v[214:217], v[96:99]
	v_mfma_f32_16x16x32_bf16 v[84:87], v[184:187], v[218:221], v[84:87]
	v_mfma_f32_16x16x32_bf16 v[84:87], v[188:191], v[222:225], v[84:87]
	v_mfma_f32_16x16x32_bf16 v[80:83], v[194:197], v[218:221], v[80:83]
	v_mfma_f32_16x16x32_bf16 v[80:83], v[198:201], v[222:225], v[80:83]
	v_mfma_f32_16x16x32_bf16 v[68:71], v[184:187], v[226:229], v[68:71]
	v_mfma_f32_16x16x32_bf16 v[68:71], v[188:191], v[230:233], v[68:71]
	v_mfma_f32_16x16x32_bf16 v[64:67], v[194:197], v[226:229], v[64:67]
	v_mfma_f32_16x16x32_bf16 v[64:67], v[198:201], v[230:233], v[64:67]
	s_barrier
	s_setprio 0
	s_add_i32 s72, s63, s33
	v_lshl_add_u64 v[234:235], s[8:9], 0, v[132:133]
	s_mov_b32 m0, s72
	ds_read_b128 v[202:205], v156 offset:16384
	ds_read_b128 v[206:209], v156 offset:17408
	ds_read_b128 v[210:213], v156 offset:18432
	ds_read_b128 v[214:217], v156 offset:19456
	ds_read_b128 v[218:221], v156 offset:20480
	ds_read_b128 v[222:225], v156 offset:21504
	ds_read_b128 v[226:229], v156 offset:22528
	ds_read_b128 v[230:233], v156 offset:23552
	global_load_lds_dwordx4 v[234:235], off
	s_add_i32 m0, s72, 0x2000
	s_add_u32 s72, s8, 0x80000
	v_lshl_add_u64 v[236:237], s[8:9], 0, v[128:129]
	s_addc_u32 s73, s9, 0
	s_add_i32 s74, s64, s33
	global_load_lds_dwordx4 v[236:237], off
	v_lshl_add_u64 v[238:239], s[72:73], 0, v[132:133]
	s_mov_b32 m0, s74
	v_lshl_add_u64 v[240:241], s[54:55], 0, v[130:131]
	global_load_lds_dwordx4 v[238:239], off
	v_lshl_add_u64 v[238:239], s[72:73], 0, v[128:129]
	s_add_i32 m0, s74, 0x2000
	s_nop 0
	global_load_lds_dwordx4 v[238:239], off
	v_lshl_add_u64 v[238:239], s[54:55], 0, v[134:135]
	s_mov_b32 m0, s39
	s_nop 0
	global_load_lds_dwordx4 v[238:239], off
	s_mov_b32 m0, s53
	s_nop 0
	global_load_lds_dwordx4 v[240:241], off
	s_waitcnt vmcnt(8)
	s_waitcnt lgkmcnt(0)
	s_setprio 1
	s_barrier
; #define PG8_STAGE(bufoff, gbase, voff) do { _Pragma("unroll") for (int _i = 0; _i < 2; ++_i) \
;         __builtin_amdgcn_global_load_lds((const unsigned*)((const char*)(gbase) + (voff)[_i]), (LAS unsigned*)(lds + (bufoff) + ldsw + _i * 8192), 16, 0, 0); } while (0)
; #define PG8_LDA(dst, b, h) do { _Pragma("unroll") for (int m = 0; m < 4; ++m) _Pragma("unroll") for (int k = 0; k < 2; ++k) dst[m][k] = *(const LAS bf16x8*)(lds + PG8_SA(b, h) + aoff + m * 2048 + k * 1024); } while (0)
; #define PG8_LDB(dst, b, h) do { _Pragma("unroll") for (int n = 0; n < 2; ++n) _Pragma("unroll") for (int k = 0; k < 2; ++k) dst[n][k] = *(const LAS bf16x8*)(lds + PG8_SB(b, h) + boff + n * 2048 + k * 1024); } while (0)
; #define PG8_MMA(ai, bj, At, Bt) do { __builtin_amdgcn_s_setprio(1); _Pragma("unroll") for (int m = 0; m < 4; ++m) _Pragma("unroll") for (int n = 0; n < 2; ++n) _Pragma("unroll") for (int k = 0; k < 2; ++k) \
;         acc[ai][bj][m][n] = __builtin_amdgcn_mfma_f32_16x16x32_bf16(Bt[n][k], At[m][k], acc[ai][bj][m][n], 0, 0, 0); __builtin_amdgcn_s_setprio(0); } while (0)
; #define PG8_WAIT_V(n) asm volatile("s_waitcnt vmcnt(" #n ")" ::: "memory")
; #define PG8_WAIT_L(n) asm volatile("s_waitcnt lgkmcnt(" #n ")" ::: "memory")
; #define PG8_BAR __builtin_amdgcn_s_barrier()
; #define PG8_SCHED __builtin_amdgcn_sched_barrier(0)
; template <class Epi, bool ALIGN_EPI>
; __device__ __forceinline__ void gemm_phase(LAS unsigned char* lds, const Gemm g, const StaticOrder& S, const Epi& E) {
;     ...
;             PG8_WAIT_V(8); PG8_WAIT_L(0); PG8_BAR; PG8_MMA(1, 0, At, B0); PG8_MMA(1, 1, At, B1); PG8_BAR; PG8_SCHED;
;             PG8_LDB(B0, 1, 0); PG8_LDB(B1, 1, 1); PG8_SCHED; PG8_LDA(At, 1, 0); PG8_STAGE(PG8_SA(0, 1), a2 + hA, voffA);
;             PG8_WAIT_V(8); PG8_WAIT_L(0); PG8_BAR; PG8_MMA(0, 0, At, B0); PG8_MMA(0, 1, At, B1); PG8_BAR; PG8_SCHED;
	v_mfma_f32_16x16x32_bf16 v[60:63], v[168:171], v[202:205], v[60:63]
	v_mfma_f32_16x16x32_bf16 v[60:63], v[172:175], v[206:209], v[60:63]
	v_mfma_f32_16x16x32_bf16 v[56:59], v[176:179], v[202:205], v[56:59]
	v_mfma_f32_16x16x32_bf16 v[56:59], v[180:183], v[206:209], v[56:59]
	v_mfma_f32_16x16x32_bf16 v[44:47], v[168:171], v[210:213], v[44:47]
	v_mfma_f32_16x16x32_bf16 v[44:47], v[172:175], v[214:217], v[44:47]
	v_mfma_f32_16x16x32_bf16 v[40:43], v[176:179], v[210:213], v[40:43]
	v_mfma_f32_16x16x32_bf16 v[40:43], v[180:183], v[214:217], v[40:43]
	v_mfma_f32_16x16x32_bf16 v[28:31], v[168:171], v[218:221], v[28:31]
	v_mfma_f32_16x16x32_bf16 v[28:31], v[172:175], v[222:225], v[28:31]
	v_mfma_f32_16x16x32_bf16 v[24:27], v[176:179], v[218:221], v[24:27]
	v_mfma_f32_16x16x32_bf16 v[24:27], v[180:183], v[222:225], v[24:27]
	v_mfma_f32_16x16x32_bf16 v[12:15], v[168:171], v[226:229], v[12:15]
	v_mfma_f32_16x16x32_bf16 v[12:15], v[172:175], v[230:233], v[12:15]
	v_mfma_f32_16x16x32_bf16 v[8:11], v[176:179], v[226:229], v[8:11]
	v_mfma_f32_16x16x32_bf16 v[8:11], v[180:183], v[230:233], v[8:11]
	s_setprio 0
	s_setprio 1
	v_mfma_f32_16x16x32_bf16 v[52:55], v[184:187], v[202:205], v[52:55]
	v_mfma_f32_16x16x32_bf16 v[52:55], v[188:191], v[206:209], v[52:55]
	v_mfma_f32_16x16x32_bf16 v[48:51], v[194:197], v[202:205], v[48:51]
	v_mfma_f32_16x16x32_bf16 v[48:51], v[198:201], v[206:209], v[48:51]
	v_mfma_f32_16x16x32_bf16 v[36:39], v[184:187], v[210:213], v[36:39]
	v_mfma_f32_16x16x32_bf16 v[36:39], v[188:191], v[214:217], v[36:39]
	v_mfma_f32_16x16x32_bf16 v[32:35], v[194:197], v[210:213], v[32:35]
	v_mfma_f32_16x16x32_bf16 v[32:35], v[198:201], v[214:217], v[32:35]
	v_mfma_f32_16x16x32_bf16 v[20:23], v[184:187], v[218:221], v[20:23]
	v_mfma_f32_16x16x32_bf16 v[20:23], v[188:191], v[222:225], v[20:23]
	v_mfma_f32_16x16x32_bf16 v[16:19], v[194:197], v[218:221], v[16:19]
	v_mfma_f32_16x16x32_bf16 v[16:19], v[198:201], v[222:225], v[16:19]
	v_mfma_f32_16x16x32_bf16 v[4:7], v[184:187], v[226:229], v[4:7]
	v_mfma_f32_16x16x32_bf16 v[4:7], v[188:191], v[230:233], v[4:7]
	v_mfma_f32_16x16x32_bf16 v[0:3], v[194:197], v[226:229], v[0:3]
	v_mfma_f32_16x16x32_bf16 v[0:3], v[198:201], v[230:233], v[0:3]
	s_barrier
	s_setprio 0
	s_add_i32 s72, 0, 0x18000
	v_add_u32_e32 v167, s72, v149
	s_add_i32 s73, 0, 0x1c000
	ds_read_b128 v[168:171], v167
	ds_read_b128 v[172:175], v167 offset:1024
	ds_read_b128 v[176:179], v167 offset:2048
	ds_read_b128 v[180:183], v167 offset:3072
	v_add_u32_e32 v167, s73, v149
	ds_read_b128 v[184:187], v167
	ds_read_b128 v[188:191], v167 offset:1024
	ds_read_b128 v[194:197], v167 offset:2048
	ds_read_b128 v[198:201], v167 offset:3072
	s_add_u32 s54, s54, 0x80000
	s_addc_u32 s55, s55, 0
	s_mov_b32 m0, s56
	v_lshl_add_u64 v[242:243], s[54:55], 0, v[134:135]
	ds_read_b128 v[202:205], v156 offset:32768
	ds_read_b128 v[206:209], v156 offset:33792
	ds_read_b128 v[210:213], v156 offset:34816
	ds_read_b128 v[214:217], v156 offset:35840
	ds_read_b128 v[218:221], v156 offset:36864
	ds_read_b128 v[222:225], v156 offset:37888
	ds_read_b128 v[226:229], v156 offset:38912
	ds_read_b128 v[230:233], v156 offset:39936
	global_load_lds_dwordx4 v[242:243], off
	v_lshl_add_u64 v[242:243], s[54:55], 0, v[130:131]
	s_mov_b32 m0, s57
	s_nop 0
	global_load_lds_dwordx4 v[242:243], off
	s_waitcnt vmcnt(8)
	s_waitcnt lgkmcnt(0)
	s_setprio 1
	s_barrier
	v_mfma_f32_16x16x32_bf16 v[124:127], v[168:171], v[202:205], v[124:127]
	v_mfma_f32_16x16x32_bf16 v[124:127], v[172:175], v[206:209], v[124:127]
	v_mfma_f32_16x16x32_bf16 v[120:123], v[176:179], v[202:205], v[120:123]
	v_mfma_f32_16x16x32_bf16 v[120:123], v[180:183], v[206:209], v[120:123]
	v_mfma_f32_16x16x32_bf16 v[108:111], v[168:171], v[210:213], v[108:111]
	v_mfma_f32_16x16x32_bf16 v[108:111], v[172:175], v[214:217], v[108:111]
	v_mfma_f32_16x16x32_bf16 v[104:107], v[176:179], v[210:213], v[104:107]
	v_mfma_f32_16x16x32_bf16 v[104:107], v[180:183], v[214:217], v[104:107]
	v_mfma_f32_16x16x32_bf16 v[92:95], v[168:171], v[218:221], v[92:95]
	v_mfma_f32_16x16x32_bf16 v[92:95], v[172:175], v[222:225], v[92:95]
	v_mfma_f32_16x16x32_bf16 v[88:91], v[176:179], v[218:221], v[88:91]
	v_mfma_f32_16x16x32_bf16 v[88:91], v[180:183], v[222:225], v[88:91]
	v_mfma_f32_16x16x32_bf16 v[76:79], v[168:171], v[226:229], v[76:79]
	v_mfma_f32_16x16x32_bf16 v[76:79], v[172:175], v[230:233], v[76:79]
	v_mfma_f32_16x16x32_bf16 v[72:75], v[176:179], v[226:229], v[72:75]
	v_mfma_f32_16x16x32_bf16 v[72:75], v[180:183], v[230:233], v[72:75]
	s_setprio 0
	s_setprio 1
	v_mfma_f32_16x16x32_bf16 v[116:119], v[184:187], v[202:205], v[116:119]
	v_mfma_f32_16x16x32_bf16 v[116:119], v[188:191], v[206:209], v[116:119]
	v_mfma_f32_16x16x32_bf16 v[112:115], v[194:197], v[202:205], v[112:115]
	v_mfma_f32_16x16x32_bf16 v[112:115], v[198:201], v[206:209], v[112:115]
	v_mfma_f32_16x16x32_bf16 v[100:103], v[184:187], v[210:213], v[100:103]
	v_mfma_f32_16x16x32_bf16 v[100:103], v[188:191], v[214:217], v[100:103]
	v_mfma_f32_16x16x32_bf16 v[96:99], v[194:197], v[210:213], v[96:99]
	v_mfma_f32_16x16x32_bf16 v[96:99], v[198:201], v[214:217], v[96:99]
	v_mfma_f32_16x16x32_bf16 v[84:87], v[184:187], v[218:221], v[84:87]
	v_mfma_f32_16x16x32_bf16 v[84:87], v[188:191], v[222:225], v[84:87]
	v_mfma_f32_16x16x32_bf16 v[80:83], v[194:197], v[218:221], v[80:83]
	v_mfma_f32_16x16x32_bf16 v[80:83], v[198:201], v[222:225], v[80:83]
	v_mfma_f32_16x16x32_bf16 v[68:71], v[184:187], v[226:229], v[68:71]
	v_mfma_f32_16x16x32_bf16 v[68:71], v[188:191], v[230:233], v[68:71]
	v_mfma_f32_16x16x32_bf16 v[64:67], v[194:197], v[226:229], v[64:67]
	v_mfma_f32_16x16x32_bf16 v[64:67], v[198:201], v[230:233], v[64:67]
	s_barrier
; #define PG8_STAGE(bufoff, gbase, voff) do { _Pragma("unroll") for (int _i = 0; _i < 2; ++_i) \
;         __builtin_amdgcn_global_load_lds((const unsigned*)((const char*)(gbase) + (voff)[_i]), (LAS unsigned*)(lds + (bufoff) + ldsw + _i * 8192), 16, 0, 0); } while (0)
; #define PG8_LDA(dst, b, h) do { _Pragma("unroll") for (int m = 0; m < 4; ++m) _Pragma("unroll") for (int k = 0; k < 2; ++k) dst[m][k] = *(const LAS bf16x8*)(lds + PG8_SA(b, h) + aoff + m * 2048 + k * 1024); } while (0)
; #define PG8_MMA(ai, bj, At, Bt) do { __builtin_amdgcn_s_setprio(1); _Pragma("unroll") for (int m = 0; m < 4; ++m) _Pragma("unroll") for (int n = 0; n < 2; ++n) _Pragma("unroll") for (int k = 0; k < 2; ++k) \
;         acc[ai][bj][m][n] = __builtin_amdgcn_mfma_f32_16x16x32_bf16(Bt[n][k], At[m][k], acc[ai][bj][m][n], 0, 0, 0); __builtin_amdgcn_s_setprio(0); } while (0)
; #define PG8_WAIT_V(n) asm volatile("s_waitcnt vmcnt(" #n ")" ::: "memory")
; #define PG8_WAIT_L(n) asm volatile("s_waitcnt lgkmcnt(" #n ")" ::: "memory")
; #define PG8_BAR __builtin_amdgcn_s_barrier()
; #define PG8_SCHED __builtin_amdgcn_sched_barrier(0)
; template <class Epi, bool ALIGN_EPI>
; __device__ __forceinline__ void gemm_phase(LAS unsigned char* lds, const Gemm g, const StaticOrder& S, const Epi& E) {
;     ...
;             PG8_WAIT_V(8); PG8_WAIT_L(0); PG8_BAR; PG8_MMA(0, 0, At, B0); PG8_MMA(0, 1, At, B1); PG8_BAR; PG8_SCHED;
;             PG8_LDA(At, 1, 1); PG8_STAGE(PG8_SB(1, 0), b3, voffB); PG8_STAGE(PG8_SB(1, 1), b3 + hB, voffB); PG8_STAGE(PG8_SA(1, 0), a3, voffA);
;             PG8_WAIT_V(8); PG8_WAIT_L(0); PG8_BAR; PG8_MMA(1, 0, At, B0); PG8_MMA(1, 1, At, B1); PG8_BAR; PG8_SCHED;
;         }
;         if constexpr (ALIGN_EPI) { if (wr == 0) PG8_BAR; }
	s_setprio 0
	s_add_i32 s54, s72, s33
	v_lshl_add_u64 v[234:235], v[234:235], 0, s[18:19]
	s_mov_b32 m0, s54
	ds_read_b128 v[202:205], v156 offset:49152
	ds_read_b128 v[206:209], v156 offset:50176
	ds_read_b128 v[210:213], v156 offset:51200
	ds_read_b128 v[214:217], v156 offset:52224
	ds_read_b128 v[218:221], v156 offset:53248
	ds_read_b128 v[222:225], v156 offset:54272
	ds_read_b128 v[226:229], v156 offset:55296
	ds_read_b128 v[230:233], v156 offset:56320
	global_load_lds_dwordx4 v[234:235], off
	s_add_i32 m0, s54, 0x2000
	s_add_u32 s8, s8, 0x80080
	v_lshl_add_u64 v[234:235], v[236:237], 0, s[18:19]
	s_addc_u32 s9, s9, 0
	s_add_i32 s54, s73, s33
	global_load_lds_dwordx4 v[234:235], off
	v_lshl_add_u64 v[234:235], s[8:9], 0, v[132:133]
	s_mov_b32 m0, s54
	s_nop 0
	global_load_lds_dwordx4 v[234:235], off
	v_lshl_add_u64 v[234:235], s[8:9], 0, v[128:129]
	s_add_i32 m0, s54, 0x2000
	s_nop 0
	global_load_lds_dwordx4 v[234:235], off
	v_lshl_add_u64 v[234:235], v[238:239], 0, s[18:19]
	s_mov_b32 m0, s60
	s_nop 0
	global_load_lds_dwordx4 v[234:235], off
	v_lshl_add_u64 v[234:235], v[240:241], 0, s[18:19]
	s_mov_b32 m0, s61
	s_nop 0
	global_load_lds_dwordx4 v[234:235], off
	s_waitcnt vmcnt(8)
	s_waitcnt lgkmcnt(0)
	s_setprio 1
	s_barrier
	v_mfma_f32_16x16x32_bf16 v[60:63], v[168:171], v[202:205], v[60:63]
	v_mfma_f32_16x16x32_bf16 v[60:63], v[172:175], v[206:209], v[60:63]
	v_mfma_f32_16x16x32_bf16 v[56:59], v[176:179], v[202:205], v[56:59]
	v_mfma_f32_16x16x32_bf16 v[56:59], v[180:183], v[206:209], v[56:59]
	v_mfma_f32_16x16x32_bf16 v[44:47], v[168:171], v[210:213], v[44:47]
	v_mfma_f32_16x16x32_bf16 v[44:47], v[172:175], v[214:217], v[44:47]
	v_mfma_f32_16x16x32_bf16 v[40:43], v[176:179], v[210:213], v[40:43]
	v_mfma_f32_16x16x32_bf16 v[40:43], v[180:183], v[214:217], v[40:43]
	v_mfma_f32_16x16x32_bf16 v[28:31], v[168:171], v[218:221], v[28:31]
	v_mfma_f32_16x16x32_bf16 v[28:31], v[172:175], v[222:225], v[28:31]
	v_mfma_f32_16x16x32_bf16 v[24:27], v[176:179], v[218:221], v[24:27]
	v_mfma_f32_16x16x32_bf16 v[24:27], v[180:183], v[222:225], v[24:27]
	v_mfma_f32_16x16x32_bf16 v[12:15], v[168:171], v[226:229], v[12:15]
	v_mfma_f32_16x16x32_bf16 v[12:15], v[172:175], v[230:233], v[12:15]
	v_mfma_f32_16x16x32_bf16 v[8:11], v[176:179], v[226:229], v[8:11]
	v_mfma_f32_16x16x32_bf16 v[8:11], v[180:183], v[230:233], v[8:11]
	s_setprio 0
	s_setprio 1
	v_mfma_f32_16x16x32_bf16 v[52:55], v[184:187], v[202:205], v[52:55]
	v_mfma_f32_16x16x32_bf16 v[52:55], v[188:191], v[206:209], v[52:55]
	v_mfma_f32_16x16x32_bf16 v[48:51], v[194:197], v[202:205], v[48:51]
	v_mfma_f32_16x16x32_bf16 v[48:51], v[198:201], v[206:209], v[48:51]
	v_mfma_f32_16x16x32_bf16 v[36:39], v[184:187], v[210:213], v[36:39]
	v_mfma_f32_16x16x32_bf16 v[36:39], v[188:191], v[214:217], v[36:39]
	v_mfma_f32_16x16x32_bf16 v[32:35], v[194:197], v[210:213], v[32:35]
	v_mfma_f32_16x16x32_bf16 v[32:35], v[198:201], v[214:217], v[32:35]
	v_mfma_f32_16x16x32_bf16 v[20:23], v[184:187], v[218:221], v[20:23]
	v_mfma_f32_16x16x32_bf16 v[20:23], v[188:191], v[222:225], v[20:23]
	v_mfma_f32_16x16x32_bf16 v[16:19], v[194:197], v[218:221], v[16:19]
	v_mfma_f32_16x16x32_bf16 v[16:19], v[198:201], v[222:225], v[16:19]
	v_mfma_f32_16x16x32_bf16 v[4:7], v[184:187], v[226:229], v[4:7]
	v_mfma_f32_16x16x32_bf16 v[4:7], v[188:191], v[230:233], v[4:7]
	v_mfma_f32_16x16x32_bf16 v[0:3], v[194:197], v[226:229], v[0:3]
	v_mfma_f32_16x16x32_bf16 v[0:3], v[198:201], v[230:233], v[0:3]
	s_barrier
	s_setprio 0
	s_add_i32 s71, s71, 2
	s_add_u32 s6, s6, 0x100
	s_addc_u32 s7, s7, 0
	s_add_u32 s69, s69, 0x100
	s_addc_u32 s70, s70, 0
	s_cmp_gt_u32 s71, 29
	s_cbranch_scc0 .LBB0_926
	s_and_b64 vcc, exec, s[20:21]
	s_cbranch_vccz .LBB0_929
	s_barrier

; #define PG8_STAGE(bufoff, gbase, voff) do { _Pragma("unroll") for (int _i = 0; _i < 2; ++_i) \
;         __builtin_amdgcn_global_load_lds((const unsigned*)((const char*)(gbase) + (voff)[_i]), (LAS unsigned*)(lds + (bufoff) + ldsw + _i * 8192), 16, 0, 0); } while (0)
; #define PG8_LDA(dst, b, h) do { _Pragma("unroll") for (int m = 0; m < 4; ++m) _Pragma("unroll") for (int k = 0; k < 2; ++k) dst[m][k] = *(const LAS bf16x8*)(lds + PG8_SA(b, h) + aoff + m * 2048 + k * 1024); } while (0)
; #define PG8_LDB(dst, b, h) do { _Pragma("unroll") for (int n = 0; n < 2; ++n) _Pragma("unroll") for (int k = 0; k < 2; ++k) dst[n][k] = *(const LAS bf16x8*)(lds + PG8_SB(b, h) + boff + n * 2048 + k * 1024); } while (0)
; #define PG8_MMA(ai, bj, At, Bt) do { __builtin_amdgcn_s_setprio(1); _Pragma("unroll") for (int m = 0; m < 4; ++m) _Pragma("unroll") for (int n = 0; n < 2; ++n) _Pragma("unroll") for (int k = 0; k < 2; ++k) \
;         acc[ai][bj][m][n] = __builtin_amdgcn_mfma_f32_16x16x32_bf16(Bt[n][k], At[m][k], acc[ai][bj][m][n], 0, 0, 0); __builtin_amdgcn_s_setprio(0); } while (0)
; #define PG8_WAIT_V(n) asm volatile("s_waitcnt vmcnt(" #n ")" ::: "memory")
; #define PG8_WAIT_L(n) asm volatile("s_waitcnt lgkmcnt(" #n ")" ::: "memory")
; #define PG8_BAR __builtin_amdgcn_s_barrier()
; #define PG8_SCHED __builtin_amdgcn_sched_barrier(0)
; template <class Epi, bool ALIGN_EPI>
; __device__ __forceinline__ void gemm_phase(LAS unsigned char* lds, const Gemm g, const StaticOrder& S, const Epi& E) {
;     ...
;         for (int t = 0; t < nt; t += 2) {
;             const bool last = (t == nt - 2);
;             const char* a1 = cA + (size_t)(t + 1) * kstep;
;             const char* a2 = last ? nA : cA + (size_t)(t + 2) * kstep; const char* b2 = last ? nB : cB + (size_t)(t + 2) * kstep;
;             const char* a3 = a2 + kstep; const char* b3 = b2 + kstep;
;             PG8_LDB(B0, 0, 0); PG8_LDB(B1, 0, 1); PG8_SCHED; PG8_LDA(At, 0, 0); PG8_STAGE(PG8_SA(1, 1), a1 + hA, voffA);
;             PG8_WAIT_V(8); PG8_WAIT_L(0); PG8_BAR; PG8_MMA(0, 0, At, B0); PG8_MMA(0, 1, At, B1); PG8_BAR; PG8_SCHED;
;             PG8_LDA(At, 0, 1); PG8_STAGE(PG8_SB(0, 0), b2, voffB); PG8_STAGE(PG8_SB(0, 1), b2 + hB, voffB); PG8_STAGE(PG8_SA(0, 0), a2, voffA);
;             PG8_WAIT_V(8); PG8_WAIT_L(0); PG8_BAR; PG8_MMA(1, 0, At, B0); PG8_MMA(1, 1, At, B1); PG8_BAR; PG8_SCHED;
.LBB0_1005:
	ds_read_b128 v[128:131], v175
	ds_read_b128 v[132:135], v175 offset:1024
	ds_read_b128 v[136:139], v175 offset:2048
	ds_read_b128 v[140:143], v175 offset:3072
	ds_read_b128 v[160:163], v176
	ds_read_b128 v[164:167], v176 offset:1024
	ds_read_b128 v[168:171], v176 offset:2048
	ds_read_b128 v[180:183], v176 offset:3072
	s_add_u32 s40, s36, 0xffe00080
	s_addc_u32 s41, s37, -1
	s_cmpk_eq_i32 s57, 0x7c
	s_cselect_b32 s43, s25, s41
	s_cselect_b32 s42, s31, s40
	s_cselect_b32 s41, s23, s56
	s_cselect_b32 s40, s54, s55
	v_lshl_add_u64 v[218:219], s[36:37], 0, v[152:153]
	s_add_i32 m0, s35, 0xc000
	ds_read_b128 v[184:187], v177
	ds_read_b128 v[188:191], v177 offset:1024
	ds_read_b128 v[194:197], v177 offset:2048
	ds_read_b128 v[198:201], v177 offset:3072
	ds_read_b128 v[202:205], v177 offset:4096
	ds_read_b128 v[206:209], v177 offset:5120
	ds_read_b128 v[210:213], v177 offset:6144
	ds_read_b128 v[214:217], v177 offset:7168
	global_load_lds_dwordx4 v[218:219], off
	v_lshl_add_u64 v[218:219], s[36:37], 0, v[154:155]
	s_add_i32 m0, s35, 0xe000
	s_nop 0
	global_load_lds_dwordx4 v[218:219], off
	s_waitcnt vmcnt(8)
	s_waitcnt lgkmcnt(0)
	s_setprio 1
	s_barrier
	v_mfma_f32_16x16x32_bf16 v[124:127], v[128:131], v[184:187], v[124:127]
	v_mfma_f32_16x16x32_bf16 v[124:127], v[132:135], v[188:191], v[124:127]
	v_mfma_f32_16x16x32_bf16 v[120:123], v[136:139], v[184:187], v[120:123]
	v_mfma_f32_16x16x32_bf16 v[120:123], v[140:143], v[188:191], v[120:123]
	v_mfma_f32_16x16x32_bf16 v[112:115], v[128:131], v[194:197], v[112:115]
	v_mfma_f32_16x16x32_bf16 v[112:115], v[132:135], v[198:201], v[112:115]
	v_mfma_f32_16x16x32_bf16 v[104:107], v[136:139], v[194:197], v[104:107]
	v_mfma_f32_16x16x32_bf16 v[104:107], v[140:143], v[198:201], v[104:107]
	v_mfma_f32_16x16x32_bf16 v[92:95], v[128:131], v[202:205], v[92:95]
	v_mfma_f32_16x16x32_bf16 v[92:95], v[132:135], v[206:209], v[92:95]
	v_mfma_f32_16x16x32_bf16 v[88:91], v[136:139], v[202:205], v[88:91]
	v_mfma_f32_16x16x32_bf16 v[88:91], v[140:143], v[206:209], v[88:91]
	v_mfma_f32_16x16x32_bf16 v[76:79], v[128:131], v[210:213], v[76:79]
	v_mfma_f32_16x16x32_bf16 v[76:79], v[132:135], v[214:217], v[76:79]
	v_mfma_f32_16x16x32_bf16 v[72:75], v[136:139], v[210:213], v[72:75]
	v_mfma_f32_16x16x32_bf16 v[72:75], v[140:143], v[214:217], v[72:75]
	s_setprio 0
	s_setprio 1
	v_mfma_f32_16x16x32_bf16 v[116:119], v[160:163], v[184:187], v[116:119]
	v_mfma_f32_16x16x32_bf16 v[116:119], v[164:167], v[188:191], v[116:119]
	v_mfma_f32_16x16x32_bf16 v[108:111], v[168:171], v[184:187], v[108:111]
	v_mfma_f32_16x16x32_bf16 v[108:111], v[180:183], v[188:191], v[108:111]
	v_mfma_f32_16x16x32_bf16 v[100:103], v[160:163], v[194:197], v[100:103]
	v_mfma_f32_16x16x32_bf16 v[100:103], v[164:167], v[198:201], v[100:103]
	v_mfma_f32_16x16x32_bf16 v[96:99], v[168:171], v[194:197], v[96:99]
	v_mfma_f32_16x16x32_bf16 v[96:99], v[180:183], v[198:201], v[96:99]
	v_mfma_f32_16x16x32_bf16 v[84:87], v[160:163], v[202:205], v[84:87]
	v_mfma_f32_16x16x32_bf16 v[84:87], v[164:167], v[206:209], v[84:87]
	v_mfma_f32_16x16x32_bf16 v[80:83], v[168:171], v[202:205], v[80:83]
	v_mfma_f32_16x16x32_bf16 v[80:83], v[180:183], v[206:209], v[80:83]
	v_mfma_f32_16x16x32_bf16 v[68:71], v[160:163], v[210:213], v[68:71]
	v_mfma_f32_16x16x32_bf16 v[68:71], v[164:167], v[214:217], v[68:71]
	v_mfma_f32_16x16x32_bf16 v[64:67], v[168:171], v[210:213], v[64:67]
	v_mfma_f32_16x16x32_bf16 v[64:67], v[180:183], v[214:217], v[64:67]
	s_barrier
	s_setprio 0
	s_add_i32 s58, s51, s33
	v_lshl_add_u64 v[218:219], s[40:41], 0, v[146:147]
	s_mov_b32 m0, s58
	ds_read_b128 v[184:187], v177 offset:16384
	ds_read_b128 v[188:191], v177 offset:17408
	ds_read_b128 v[194:197], v177 offset:18432
	ds_read_b128 v[198:201], v177 offset:19456
	ds_read_b128 v[202:205], v177 offset:20480
	ds_read_b128 v[206:209], v177 offset:21504
	ds_read_b128 v[210:213], v177 offset:22528
	ds_read_b128 v[214:217], v177 offset:23552
	global_load_lds_dwordx4 v[218:219], off
	s_add_i32 m0, s58, 0x2000
	s_add_u32 s58, s40, 0x200000
	v_lshl_add_u64 v[220:221], s[40:41], 0, v[150:151]
	s_addc_u32 s59, s41, 0
	s_add_i32 s60, s52, s33
	global_load_lds_dwordx4 v[220:221], off
	v_lshl_add_u64 v[222:223], s[58:59], 0, v[146:147]
	s_mov_b32 m0, s60
	v_lshl_add_u64 v[224:225], s[42:43], 0, v[148:149]
	global_load_lds_dwordx4 v[222:223], off
	v_lshl_add_u64 v[222:223], s[58:59], 0, v[150:151]
	s_add_i32 m0, s60, 0x2000
	s_nop 0
	global_load_lds_dwordx4 v[222:223], off
	v_lshl_add_u64 v[222:223], s[42:43], 0, v[144:145]
	s_mov_b32 m0, s35
	s_nop 0
	global_load_lds_dwordx4 v[222:223], off
	s_mov_b32 m0, s38
	s_nop 0
	global_load_lds_dwordx4 v[224:225], off
	s_waitcnt vmcnt(8)
	s_waitcnt lgkmcnt(0)
	s_setprio 1
	s_barrier
; #define PG8_STAGE(bufoff, gbase, voff) do { _Pragma("unroll") for (int _i = 0; _i < 2; ++_i) \
;         __builtin_amdgcn_global_load_lds((const unsigned*)((const char*)(gbase) + (voff)[_i]), (LAS unsigned*)(lds + (bufoff) + ldsw + _i * 8192), 16, 0, 0); } while (0)
; #define PG8_LDA(dst, b, h) do { _Pragma("unroll") for (int m = 0; m < 4; ++m) _Pragma("unroll") for (int k = 0; k < 2; ++k) dst[m][k] = *(const LAS bf16x8*)(lds + PG8_SA(b, h) + aoff + m * 2048 + k * 1024); } while (0)
; #define PG8_LDB(dst, b, h) do { _Pragma("unroll") for (int n = 0; n < 2; ++n) _Pragma("unroll") for (int k = 0; k < 2; ++k) dst[n][k] = *(const LAS bf16x8*)(lds + PG8_SB(b, h) + boff + n * 2048 + k * 1024); } while (0)
; #define PG8_MMA(ai, bj, At, Bt) do { __builtin_amdgcn_s_setprio(1); _Pragma("unroll") for (int m = 0; m < 4; ++m) _Pragma("unroll") for (int n = 0; n < 2; ++n) _Pragma("unroll") for (int k = 0; k < 2; ++k) \
;         acc[ai][bj][m][n] = __builtin_amdgcn_mfma_f32_16x16x32_bf16(Bt[n][k], At[m][k], acc[ai][bj][m][n], 0, 0, 0); __builtin_amdgcn_s_setprio(0); } while (0)
; #define PG8_WAIT_V(n) asm volatile("s_waitcnt vmcnt(" #n ")" ::: "memory")
; #define PG8_WAIT_L(n) asm volatile("s_waitcnt lgkmcnt(" #n ")" ::: "memory")
; #define PG8_BAR __builtin_amdgcn_s_barrier()
; #define PG8_SCHED __builtin_amdgcn_sched_barrier(0)
; template <class Epi, bool ALIGN_EPI>
; __device__ __forceinline__ void gemm_phase(LAS unsigned char* lds, const Gemm g, const StaticOrder& S, const Epi& E) {
;     ...
;             PG8_WAIT_V(8); PG8_WAIT_L(0); PG8_BAR; PG8_MMA(1, 0, At, B0); PG8_MMA(1, 1, At, B1); PG8_BAR; PG8_SCHED;
;             PG8_LDB(B0, 1, 0); PG8_LDB(B1, 1, 1); PG8_SCHED; PG8_LDA(At, 1, 0); PG8_STAGE(PG8_SA(0, 1), a2 + hA, voffA);
;             PG8_WAIT_V(8); PG8_WAIT_L(0); PG8_BAR; PG8_MMA(0, 0, At, B0); PG8_MMA(0, 1, At, B1); PG8_BAR; PG8_SCHED;
	v_mfma_f32_16x16x32_bf16 v[60:63], v[128:131], v[184:187], v[60:63]
	v_mfma_f32_16x16x32_bf16 v[60:63], v[132:135], v[188:191], v[60:63]
	v_mfma_f32_16x16x32_bf16 v[56:59], v[136:139], v[184:187], v[56:59]
	v_mfma_f32_16x16x32_bf16 v[56:59], v[140:143], v[188:191], v[56:59]
	v_mfma_f32_16x16x32_bf16 v[44:47], v[128:131], v[194:197], v[44:47]
	v_mfma_f32_16x16x32_bf16 v[44:47], v[132:135], v[198:201], v[44:47]
	v_mfma_f32_16x16x32_bf16 v[40:43], v[136:139], v[194:197], v[40:43]
	v_mfma_f32_16x16x32_bf16 v[40:43], v[140:143], v[198:201], v[40:43]
	v_mfma_f32_16x16x32_bf16 v[28:31], v[128:131], v[202:205], v[28:31]
	v_mfma_f32_16x16x32_bf16 v[28:31], v[132:135], v[206:209], v[28:31]
	v_mfma_f32_16x16x32_bf16 v[24:27], v[136:139], v[202:205], v[24:27]
	v_mfma_f32_16x16x32_bf16 v[24:27], v[140:143], v[206:209], v[24:27]
	v_mfma_f32_16x16x32_bf16 v[12:15], v[128:131], v[210:213], v[12:15]
	v_mfma_f32_16x16x32_bf16 v[12:15], v[132:135], v[214:217], v[12:15]
	v_mfma_f32_16x16x32_bf16 v[8:11], v[136:139], v[210:213], v[8:11]
	v_mfma_f32_16x16x32_bf16 v[8:11], v[140:143], v[214:217], v[8:11]
	s_setprio 0
	s_setprio 1
	v_mfma_f32_16x16x32_bf16 v[52:55], v[160:163], v[184:187], v[52:55]
	v_mfma_f32_16x16x32_bf16 v[52:55], v[164:167], v[188:191], v[52:55]
	v_mfma_f32_16x16x32_bf16 v[48:51], v[168:171], v[184:187], v[48:51]
	v_mfma_f32_16x16x32_bf16 v[48:51], v[180:183], v[188:191], v[48:51]
	v_mfma_f32_16x16x32_bf16 v[36:39], v[160:163], v[194:197], v[36:39]
	v_mfma_f32_16x16x32_bf16 v[36:39], v[164:167], v[198:201], v[36:39]
	v_mfma_f32_16x16x32_bf16 v[32:35], v[168:171], v[194:197], v[32:35]
	v_mfma_f32_16x16x32_bf16 v[32:35], v[180:183], v[198:201], v[32:35]
	v_mfma_f32_16x16x32_bf16 v[20:23], v[160:163], v[202:205], v[20:23]
	v_mfma_f32_16x16x32_bf16 v[20:23], v[164:167], v[206:209], v[20:23]
	v_mfma_f32_16x16x32_bf16 v[16:19], v[168:171], v[202:205], v[16:19]
	v_mfma_f32_16x16x32_bf16 v[16:19], v[180:183], v[206:209], v[16:19]
	v_mfma_f32_16x16x32_bf16 v[4:7], v[160:163], v[210:213], v[4:7]
	v_mfma_f32_16x16x32_bf16 v[4:7], v[164:167], v[214:217], v[4:7]
	v_mfma_f32_16x16x32_bf16 v[0:3], v[168:171], v[210:213], v[0:3]
	v_mfma_f32_16x16x32_bf16 v[0:3], v[180:183], v[214:217], v[0:3]
	s_barrier
	s_setprio 0
	s_add_i32 s58, 0, 0x18000
	s_add_i32 s59, 0, 0x1c000
	v_add_u32_e32 v140, s58, v173
	v_add_u32_e32 v179, s59, v173
	ds_read_b128 v[128:131], v140
	ds_read_b128 v[132:135], v140 offset:1024
	ds_read_b128 v[136:139], v140 offset:2048
	ds_read_b128 v[140:143], v140 offset:3072
	ds_read_b128 v[160:163], v179
	ds_read_b128 v[164:167], v179 offset:1024
	ds_read_b128 v[168:171], v179 offset:2048
	ds_read_b128 v[180:183], v179 offset:3072
	s_add_u32 s42, s42, 0x200000
	s_addc_u32 s43, s43, 0
	s_mov_b32 m0, s39
	v_lshl_add_u64 v[226:227], s[42:43], 0, v[144:145]
	ds_read_b128 v[184:187], v177 offset:32768
	ds_read_b128 v[188:191], v177 offset:33792
	ds_read_b128 v[194:197], v177 offset:34816
	ds_read_b128 v[198:201], v177 offset:35840
	ds_read_b128 v[202:205], v177 offset:36864
	ds_read_b128 v[206:209], v177 offset:37888
	ds_read_b128 v[210:213], v177 offset:38912
	ds_read_b128 v[214:217], v177 offset:39936
	global_load_lds_dwordx4 v[226:227], off
	v_lshl_add_u64 v[226:227], s[42:43], 0, v[148:149]
	s_mov_b32 m0, s44
	s_nop 0
	global_load_lds_dwordx4 v[226:227], off
	s_waitcnt vmcnt(8)
	s_waitcnt lgkmcnt(0)
	s_setprio 1
	s_barrier
	v_mfma_f32_16x16x32_bf16 v[124:127], v[128:131], v[184:187], v[124:127]
	v_mfma_f32_16x16x32_bf16 v[124:127], v[132:135], v[188:191], v[124:127]
	v_mfma_f32_16x16x32_bf16 v[120:123], v[136:139], v[184:187], v[120:123]
	v_mfma_f32_16x16x32_bf16 v[120:123], v[140:143], v[188:191], v[120:123]
	v_mfma_f32_16x16x32_bf16 v[112:115], v[128:131], v[194:197], v[112:115]
	v_mfma_f32_16x16x32_bf16 v[112:115], v[132:135], v[198:201], v[112:115]
	v_mfma_f32_16x16x32_bf16 v[104:107], v[136:139], v[194:197], v[104:107]
	v_mfma_f32_16x16x32_bf16 v[104:107], v[140:143], v[198:201], v[104:107]
	v_mfma_f32_16x16x32_bf16 v[92:95], v[128:131], v[202:205], v[92:95]
	v_mfma_f32_16x16x32_bf16 v[92:95], v[132:135], v[206:209], v[92:95]
	v_mfma_f32_16x16x32_bf16 v[88:91], v[136:139], v[202:205], v[88:91]
	v_mfma_f32_16x16x32_bf16 v[88:91], v[140:143], v[206:209], v[88:91]
	v_mfma_f32_16x16x32_bf16 v[76:79], v[128:131], v[210:213], v[76:79]
	v_mfma_f32_16x16x32_bf16 v[76:79], v[132:135], v[214:217], v[76:79]
	v_mfma_f32_16x16x32_bf16 v[72:75], v[136:139], v[210:213], v[72:75]
	v_mfma_f32_16x16x32_bf16 v[72:75], v[140:143], v[214:217], v[72:75]
	s_setprio 0
	s_setprio 1
	v_mfma_f32_16x16x32_bf16 v[116:119], v[160:163], v[184:187], v[116:119]
	v_mfma_f32_16x16x32_bf16 v[116:119], v[164:167], v[188:191], v[116:119]
	v_mfma_f32_16x16x32_bf16 v[108:111], v[168:171], v[184:187], v[108:111]
	v_mfma_f32_16x16x32_bf16 v[108:111], v[180:183], v[188:191], v[108:111]
	v_mfma_f32_16x16x32_bf16 v[100:103], v[160:163], v[194:197], v[100:103]
	v_mfma_f32_16x16x32_bf16 v[100:103], v[164:167], v[198:201], v[100:103]
	v_mfma_f32_16x16x32_bf16 v[96:99], v[168:171], v[194:197], v[96:99]
	v_mfma_f32_16x16x32_bf16 v[96:99], v[180:183], v[198:201], v[96:99]
	v_mfma_f32_16x16x32_bf16 v[84:87], v[160:163], v[202:205], v[84:87]
	v_mfma_f32_16x16x32_bf16 v[84:87], v[164:167], v[206:209], v[84:87]
	v_mfma_f32_16x16x32_bf16 v[80:83], v[168:171], v[202:205], v[80:83]
	v_mfma_f32_16x16x32_bf16 v[80:83], v[180:183], v[206:209], v[80:83]
	v_mfma_f32_16x16x32_bf16 v[68:71], v[160:163], v[210:213], v[68:71]
	v_mfma_f32_16x16x32_bf16 v[68:71], v[164:167], v[214:217], v[68:71]
	v_mfma_f32_16x16x32_bf16 v[64:67], v[168:171], v[210:213], v[64:67]
	v_mfma_f32_16x16x32_bf16 v[64:67], v[180:183], v[214:217], v[64:67]
	s_barrier
; #define PG8_STAGE(bufoff, gbase, voff) do { _Pragma("unroll") for (int _i = 0; _i < 2; ++_i) \
;         __builtin_amdgcn_global_load_lds((const unsigned*)((const char*)(gbase) + (voff)[_i]), (LAS unsigned*)(lds + (bufoff) + ldsw + _i * 8192), 16, 0, 0); } while (0)
; #define PG8_LDA(dst, b, h) do { _Pragma("unroll") for (int m = 0; m < 4; ++m) _Pragma("unroll") for (int k = 0; k < 2; ++k) dst[m][k] = *(const LAS bf16x8*)(lds + PG8_SA(b, h) + aoff + m * 2048 + k * 1024); } while (0)
; #define PG8_MMA(ai, bj, At, Bt) do { __builtin_amdgcn_s_setprio(1); _Pragma("unroll") for (int m = 0; m < 4; ++m) _Pragma("unroll") for (int n = 0; n < 2; ++n) _Pragma("unroll") for (int k = 0; k < 2; ++k) \
;         acc[ai][bj][m][n] = __builtin_amdgcn_mfma_f32_16x16x32_bf16(Bt[n][k], At[m][k], acc[ai][bj][m][n], 0, 0, 0); __builtin_amdgcn_s_setprio(0); } while (0)
; #define PG8_WAIT_V(n) asm volatile("s_waitcnt vmcnt(" #n ")" ::: "memory")
; #define PG8_WAIT_L(n) asm volatile("s_waitcnt lgkmcnt(" #n ")" ::: "memory")
; #define PG8_BAR __builtin_amdgcn_s_barrier()
; #define PG8_SCHED __builtin_amdgcn_sched_barrier(0)
; template <class Epi, bool ALIGN_EPI>
; __device__ __forceinline__ void gemm_phase(LAS unsigned char* lds, const Gemm g, const StaticOrder& S, const Epi& E) {
;     ...
;             PG8_WAIT_V(8); PG8_WAIT_L(0); PG8_BAR; PG8_MMA(0, 0, At, B0); PG8_MMA(0, 1, At, B1); PG8_BAR; PG8_SCHED;
;             PG8_LDA(At, 1, 1); PG8_STAGE(PG8_SB(1, 0), b3, voffB); PG8_STAGE(PG8_SB(1, 1), b3 + hB, voffB); PG8_STAGE(PG8_SA(1, 0), a3, voffA);
;             PG8_WAIT_V(8); PG8_WAIT_L(0); PG8_BAR; PG8_MMA(1, 0, At, B0); PG8_MMA(1, 1, At, B1); PG8_BAR; PG8_SCHED;
;         }
;         if constexpr (ALIGN_EPI) { if (wr == 0) PG8_BAR; }
	s_setprio 0
	s_add_i32 s42, s58, s33
	v_lshl_add_u64 v[218:219], v[218:219], 0, s[16:17]
	s_mov_b32 m0, s42
	ds_read_b128 v[184:187], v177 offset:49152
	ds_read_b128 v[188:191], v177 offset:50176
	ds_read_b128 v[194:197], v177 offset:51200
	ds_read_b128 v[198:201], v177 offset:52224
	ds_read_b128 v[202:205], v177 offset:53248
	ds_read_b128 v[206:209], v177 offset:54272
	ds_read_b128 v[210:213], v177 offset:55296
	ds_read_b128 v[214:217], v177 offset:56320
	global_load_lds_dwordx4 v[218:219], off
	s_add_i32 m0, s42, 0x2000
	s_add_u32 s40, s40, 0x200080
	v_lshl_add_u64 v[218:219], v[220:221], 0, s[16:17]
	s_addc_u32 s41, s41, 0
	s_add_i32 s42, s59, s33
	global_load_lds_dwordx4 v[218:219], off
	v_lshl_add_u64 v[218:219], s[40:41], 0, v[146:147]
	s_mov_b32 m0, s42
	s_nop 0
	global_load_lds_dwordx4 v[218:219], off
	v_lshl_add_u64 v[218:219], s[40:41], 0, v[150:151]
	s_add_i32 m0, s42, 0x2000
	s_nop 0
	global_load_lds_dwordx4 v[218:219], off
	v_lshl_add_u64 v[218:219], v[222:223], 0, s[16:17]
	s_mov_b32 m0, s48
	s_nop 0
	global_load_lds_dwordx4 v[218:219], off
	v_lshl_add_u64 v[218:219], v[224:225], 0, s[16:17]
	s_mov_b32 m0, s49
	s_nop 0
	global_load_lds_dwordx4 v[218:219], off
	s_waitcnt vmcnt(8)
	s_waitcnt lgkmcnt(0)
	s_setprio 1
	s_barrier
	v_mfma_f32_16x16x32_bf16 v[60:63], v[128:131], v[184:187], v[60:63]
	v_mfma_f32_16x16x32_bf16 v[60:63], v[132:135], v[188:191], v[60:63]
	v_mfma_f32_16x16x32_bf16 v[56:59], v[136:139], v[184:187], v[56:59]
	v_mfma_f32_16x16x32_bf16 v[56:59], v[140:143], v[188:191], v[56:59]
	v_mfma_f32_16x16x32_bf16 v[44:47], v[128:131], v[194:197], v[44:47]
	v_mfma_f32_16x16x32_bf16 v[44:47], v[132:135], v[198:201], v[44:47]
	v_mfma_f32_16x16x32_bf16 v[40:43], v[136:139], v[194:197], v[40:43]
	v_mfma_f32_16x16x32_bf16 v[40:43], v[140:143], v[198:201], v[40:43]
	v_mfma_f32_16x16x32_bf16 v[28:31], v[128:131], v[202:205], v[28:31]
	v_mfma_f32_16x16x32_bf16 v[28:31], v[132:135], v[206:209], v[28:31]
	v_mfma_f32_16x16x32_bf16 v[24:27], v[136:139], v[202:205], v[24:27]
	v_mfma_f32_16x16x32_bf16 v[24:27], v[140:143], v[206:209], v[24:27]
	v_mfma_f32_16x16x32_bf16 v[12:15], v[128:131], v[210:213], v[12:15]
	v_mfma_f32_16x16x32_bf16 v[12:15], v[132:135], v[214:217], v[12:15]
	v_mfma_f32_16x16x32_bf16 v[8:11], v[136:139], v[210:213], v[8:11]
	v_mfma_f32_16x16x32_bf16 v[8:11], v[140:143], v[214:217], v[8:11]
	s_setprio 0
	s_setprio 1
	v_mfma_f32_16x16x32_bf16 v[52:55], v[160:163], v[184:187], v[52:55]
	v_mfma_f32_16x16x32_bf16 v[52:55], v[164:167], v[188:191], v[52:55]
	v_mfma_f32_16x16x32_bf16 v[48:51], v[168:171], v[184:187], v[48:51]
	v_mfma_f32_16x16x32_bf16 v[48:51], v[180:183], v[188:191], v[48:51]
	v_mfma_f32_16x16x32_bf16 v[36:39], v[160:163], v[194:197], v[36:39]
	v_mfma_f32_16x16x32_bf16 v[36:39], v[164:167], v[198:201], v[36:39]
	v_mfma_f32_16x16x32_bf16 v[32:35], v[168:171], v[194:197], v[32:35]
	v_mfma_f32_16x16x32_bf16 v[32:35], v[180:183], v[198:201], v[32:35]
	v_mfma_f32_16x16x32_bf16 v[20:23], v[160:163], v[202:205], v[20:23]
	v_mfma_f32_16x16x32_bf16 v[20:23], v[164:167], v[206:209], v[20:23]
	v_mfma_f32_16x16x32_bf16 v[16:19], v[168:171], v[202:205], v[16:19]
	v_mfma_f32_16x16x32_bf16 v[16:19], v[180:183], v[206:209], v[16:19]
	v_mfma_f32_16x16x32_bf16 v[4:7], v[160:163], v[210:213], v[4:7]
	v_mfma_f32_16x16x32_bf16 v[4:7], v[164:167], v[214:217], v[4:7]
	v_mfma_f32_16x16x32_bf16 v[0:3], v[168:171], v[210:213], v[0:3]
	v_mfma_f32_16x16x32_bf16 v[0:3], v[180:183], v[214:217], v[0:3]
	s_barrier
	s_setprio 0
	s_add_i32 s57, s57, 2
	s_add_u32 s36, s36, 0x100
	s_addc_u32 s37, s37, 0
	s_add_u32 s55, s55, 0x100
	s_addc_u32 s56, s56, 0
	s_cmpk_gt_u32 s57, 0x7d
	s_cbranch_scc0 .LBB0_1005
	s_and_b64 vcc, exec, s[18:19]
	s_cbranch_vccz .LBB0_1008
	s_barrier

; #define PG8_STAGE(bufoff, gbase, voff) do { _Pragma("unroll") for (int _i = 0; _i < 2; ++_i) \
;         __builtin_amdgcn_global_load_lds((const unsigned*)((const char*)(gbase) + (voff)[_i]), (LAS unsigned*)(lds + (bufoff) + ldsw + _i * 8192), 16, 0, 0); } while (0)
; #define PG8_LDA(dst, b, h) do { _Pragma("unroll") for (int m = 0; m < 4; ++m) _Pragma("unroll") for (int k = 0; k < 2; ++k) dst[m][k] = *(const LAS bf16x8*)(lds + PG8_SA(b, h) + aoff + m * 2048 + k * 1024); } while (0)
; #define PG8_LDB(dst, b, h) do { _Pragma("unroll") for (int n = 0; n < 2; ++n) _Pragma("unroll") for (int k = 0; k < 2; ++k) dst[n][k] = *(const LAS bf16x8*)(lds + PG8_SB(b, h) + boff + n * 2048 + k * 1024); } while (0)
; #define PG8_MMA(ai, bj, At, Bt) do { __builtin_amdgcn_s_setprio(1); _Pragma("unroll") for (int m = 0; m < 4; ++m) _Pragma("unroll") for (int n = 0; n < 2; ++n) _Pragma("unroll") for (int k = 0; k < 2; ++k) \
;         acc[ai][bj][m][n] = __builtin_amdgcn_mfma_f32_16x16x32_bf16(Bt[n][k], At[m][k], acc[ai][bj][m][n], 0, 0, 0); __builtin_amdgcn_s_setprio(0); } while (0)
; #define PG8_WAIT_V(n) asm volatile("s_waitcnt vmcnt(" #n ")" ::: "memory")
; #define PG8_WAIT_L(n) asm volatile("s_waitcnt lgkmcnt(" #n ")" ::: "memory")
; #define PG8_BAR __builtin_amdgcn_s_barrier()
; #define PG8_SCHED __builtin_amdgcn_sched_barrier(0)
; template <class Epi, bool ALIGN_EPI>
; __device__ __forceinline__ void gemm_phase(LAS unsigned char* lds, const Gemm g, const StaticOrder& S, const Epi& E) {
;     ...
;         for (int t = 0; t < nt; t += 2) {
;             const bool last = (t == nt - 2);
;             const char* a1 = cA + (size_t)(t + 1) * kstep;
;             const char* a2 = last ? nA : cA + (size_t)(t + 2) * kstep; const char* b2 = last ? nB : cB + (size_t)(t + 2) * kstep;
;             const char* a3 = a2 + kstep; const char* b3 = b2 + kstep;
;             PG8_LDB(B0, 0, 0); PG8_LDB(B1, 0, 1); PG8_SCHED; PG8_LDA(At, 0, 0); PG8_STAGE(PG8_SA(1, 1), a1 + hA, voffA);
;             PG8_WAIT_V(8); PG8_WAIT_L(0); PG8_BAR; PG8_MMA(0, 0, At, B0); PG8_MMA(0, 1, At, B1); PG8_BAR; PG8_SCHED;
;             PG8_LDA(At, 0, 1); PG8_STAGE(PG8_SB(0, 0), b2, voffB); PG8_STAGE(PG8_SB(0, 1), b2 + hB, voffB); PG8_STAGE(PG8_SA(0, 0), a2, voffA);
;             PG8_WAIT_V(8); PG8_WAIT_L(0); PG8_BAR; PG8_MMA(1, 0, At, B0); PG8_MMA(1, 1, At, B1); PG8_BAR; PG8_SCHED;
.LBB0_1094:
	ds_read_b128 v[146:149], v153
	ds_read_b128 v[174:177], v153 offset:1024
	ds_read_b128 v[178:181], v153 offset:2048
	ds_read_b128 v[182:185], v153 offset:3072
	ds_read_b128 v[186:189], v154
	ds_read_b128 v[194:197], v154 offset:1024
	ds_read_b128 v[198:201], v154 offset:2048
	ds_read_b128 v[202:205], v154 offset:3072
	s_add_u32 s36, s4, 0xfff80080
	s_addc_u32 s37, s5, -1
	s_cmp_eq_u32 s38, 28
	s_cselect_b32 s45, s0, s37
	s_cselect_b32 s44, s1, s36
	s_cselect_b32 s37, s2, s29
	s_cselect_b32 s36, s3, s27
	v_lshl_add_u64 v[190:191], s[4:5], 0, v[136:137]
	s_add_i32 m0, s41, 0xc000
	ds_read_b128 v[206:209], v155
	ds_read_b128 v[210:213], v155 offset:1024
	ds_read_b128 v[214:217], v155 offset:2048
	ds_read_b128 v[218:221], v155 offset:3072
	ds_read_b128 v[222:225], v155 offset:4096
	ds_read_b128 v[226:229], v155 offset:5120
	ds_read_b128 v[230:233], v155 offset:6144
	ds_read_b128 v[234:237], v155 offset:7168
	global_load_lds_dwordx4 v[190:191], off
	v_lshl_add_u64 v[190:191], s[4:5], 0, v[138:139]
	s_add_i32 m0, s41, 0xe000
	s_nop 0
	global_load_lds_dwordx4 v[190:191], off
	s_waitcnt vmcnt(8)
	s_waitcnt lgkmcnt(0)
	s_setprio 1
	s_barrier
	v_mfma_f32_16x16x32_bf16 v[124:127], v[146:149], v[206:209], v[124:127]
	v_mfma_f32_16x16x32_bf16 v[124:127], v[174:177], v[210:213], v[124:127]
	v_mfma_f32_16x16x32_bf16 v[120:123], v[178:181], v[206:209], v[120:123]
	v_mfma_f32_16x16x32_bf16 v[120:123], v[182:185], v[210:213], v[120:123]
	v_mfma_f32_16x16x32_bf16 v[108:111], v[146:149], v[214:217], v[108:111]
	v_mfma_f32_16x16x32_bf16 v[108:111], v[174:177], v[218:221], v[108:111]
	v_mfma_f32_16x16x32_bf16 v[104:107], v[178:181], v[214:217], v[104:107]
	v_mfma_f32_16x16x32_bf16 v[104:107], v[182:185], v[218:221], v[104:107]
	v_mfma_f32_16x16x32_bf16 v[92:95], v[146:149], v[222:225], v[92:95]
	v_mfma_f32_16x16x32_bf16 v[92:95], v[174:177], v[226:229], v[92:95]
	v_mfma_f32_16x16x32_bf16 v[88:91], v[178:181], v[222:225], v[88:91]
	v_mfma_f32_16x16x32_bf16 v[88:91], v[182:185], v[226:229], v[88:91]
	v_mfma_f32_16x16x32_bf16 v[76:79], v[146:149], v[230:233], v[76:79]
	v_mfma_f32_16x16x32_bf16 v[76:79], v[174:177], v[234:237], v[76:79]
	v_mfma_f32_16x16x32_bf16 v[72:75], v[178:181], v[230:233], v[72:75]
	v_mfma_f32_16x16x32_bf16 v[72:75], v[182:185], v[234:237], v[72:75]
	s_setprio 0
	s_setprio 1
	v_mfma_f32_16x16x32_bf16 v[116:119], v[186:189], v[206:209], v[116:119]
	v_mfma_f32_16x16x32_bf16 v[116:119], v[194:197], v[210:213], v[116:119]
	v_mfma_f32_16x16x32_bf16 v[112:115], v[198:201], v[206:209], v[112:115]
	v_mfma_f32_16x16x32_bf16 v[112:115], v[202:205], v[210:213], v[112:115]
	v_mfma_f32_16x16x32_bf16 v[100:103], v[186:189], v[214:217], v[100:103]
	v_mfma_f32_16x16x32_bf16 v[100:103], v[194:197], v[218:221], v[100:103]
	v_mfma_f32_16x16x32_bf16 v[96:99], v[198:201], v[214:217], v[96:99]
	v_mfma_f32_16x16x32_bf16 v[96:99], v[202:205], v[218:221], v[96:99]
	v_mfma_f32_16x16x32_bf16 v[84:87], v[186:189], v[222:225], v[84:87]
	v_mfma_f32_16x16x32_bf16 v[84:87], v[194:197], v[226:229], v[84:87]
	v_mfma_f32_16x16x32_bf16 v[80:83], v[198:201], v[222:225], v[80:83]
	v_mfma_f32_16x16x32_bf16 v[80:83], v[202:205], v[226:229], v[80:83]
	v_mfma_f32_16x16x32_bf16 v[68:71], v[186:189], v[230:233], v[68:71]
	v_mfma_f32_16x16x32_bf16 v[68:71], v[194:197], v[234:237], v[68:71]
	v_mfma_f32_16x16x32_bf16 v[64:67], v[198:201], v[230:233], v[64:67]
	v_mfma_f32_16x16x32_bf16 v[64:67], v[202:205], v[234:237], v[64:67]
	s_barrier
	s_setprio 0
	s_add_i32 s39, s61, s51
	v_lshl_add_u64 v[190:191], s[36:37], 0, v[130:131]
	s_mov_b32 m0, s39
	ds_read_b128 v[206:209], v155 offset:16384
	ds_read_b128 v[210:213], v155 offset:17408
	ds_read_b128 v[214:217], v155 offset:18432
	ds_read_b128 v[218:221], v155 offset:19456
	ds_read_b128 v[222:225], v155 offset:20480
	ds_read_b128 v[226:229], v155 offset:21504
	ds_read_b128 v[230:233], v155 offset:22528
	ds_read_b128 v[234:237], v155 offset:23552
	global_load_lds_dwordx4 v[190:191], off
	s_add_i32 m0, s39, 0x2000
	s_add_u32 s46, s36, 0x80000
	v_lshl_add_u64 v[238:239], s[36:37], 0, v[134:135]
	s_addc_u32 s47, s37, 0
	s_add_i32 s39, s62, s51
	global_load_lds_dwordx4 v[238:239], off
	v_lshl_add_u64 v[240:241], s[46:47], 0, v[130:131]
	s_mov_b32 m0, s39
	v_lshl_add_u64 v[242:243], s[44:45], 0, v[132:133]
	global_load_lds_dwordx4 v[240:241], off
	v_lshl_add_u64 v[240:241], s[46:47], 0, v[134:135]
	s_add_i32 m0, s39, 0x2000
	s_nop 0
	global_load_lds_dwordx4 v[240:241], off
	v_lshl_add_u64 v[240:241], s[44:45], 0, v[128:129]
	s_mov_b32 m0, s41
	s_nop 0
	global_load_lds_dwordx4 v[240:241], off
	s_mov_b32 m0, s43
	s_nop 0
	global_load_lds_dwordx4 v[242:243], off
	s_waitcnt vmcnt(8)
	s_waitcnt lgkmcnt(0)
	s_setprio 1
	s_barrier
; #define PG8_STAGE(bufoff, gbase, voff) do { _Pragma("unroll") for (int _i = 0; _i < 2; ++_i) \
;         __builtin_amdgcn_global_load_lds((const unsigned*)((const char*)(gbase) + (voff)[_i]), (LAS unsigned*)(lds + (bufoff) + ldsw + _i * 8192), 16, 0, 0); } while (0)
; #define PG8_LDA(dst, b, h) do { _Pragma("unroll") for (int m = 0; m < 4; ++m) _Pragma("unroll") for (int k = 0; k < 2; ++k) dst[m][k] = *(const LAS bf16x8*)(lds + PG8_SA(b, h) + aoff + m * 2048 + k * 1024); } while (0)
; #define PG8_LDB(dst, b, h) do { _Pragma("unroll") for (int n = 0; n < 2; ++n) _Pragma("unroll") for (int k = 0; k < 2; ++k) dst[n][k] = *(const LAS bf16x8*)(lds + PG8_SB(b, h) + boff + n * 2048 + k * 1024); } while (0)
; #define PG8_MMA(ai, bj, At, Bt) do { __builtin_amdgcn_s_setprio(1); _Pragma("unroll") for (int m = 0; m < 4; ++m) _Pragma("unroll") for (int n = 0; n < 2; ++n) _Pragma("unroll") for (int k = 0; k < 2; ++k) \
;         acc[ai][bj][m][n] = __builtin_amdgcn_mfma_f32_16x16x32_bf16(Bt[n][k], At[m][k], acc[ai][bj][m][n], 0, 0, 0); __builtin_amdgcn_s_setprio(0); } while (0)
; #define PG8_WAIT_V(n) asm volatile("s_waitcnt vmcnt(" #n ")" ::: "memory")
; #define PG8_WAIT_L(n) asm volatile("s_waitcnt lgkmcnt(" #n ")" ::: "memory")
; #define PG8_BAR __builtin_amdgcn_s_barrier()
; #define PG8_SCHED __builtin_amdgcn_sched_barrier(0)
; template <class Epi, bool ALIGN_EPI>
; __device__ __forceinline__ void gemm_phase(LAS unsigned char* lds, const Gemm g, const StaticOrder& S, const Epi& E) {
;     ...
;             PG8_WAIT_V(8); PG8_WAIT_L(0); PG8_BAR; PG8_MMA(1, 0, At, B0); PG8_MMA(1, 1, At, B1); PG8_BAR; PG8_SCHED;
;             PG8_LDB(B0, 1, 0); PG8_LDB(B1, 1, 1); PG8_SCHED; PG8_LDA(At, 1, 0); PG8_STAGE(PG8_SA(0, 1), a2 + hA, voffA);
;             PG8_WAIT_V(8); PG8_WAIT_L(0); PG8_BAR; PG8_MMA(0, 0, At, B0); PG8_MMA(0, 1, At, B1); PG8_BAR; PG8_SCHED;
	v_mfma_f32_16x16x32_bf16 v[60:63], v[146:149], v[206:209], v[60:63]
	v_mfma_f32_16x16x32_bf16 v[60:63], v[174:177], v[210:213], v[60:63]
	v_mfma_f32_16x16x32_bf16 v[56:59], v[178:181], v[206:209], v[56:59]
	v_mfma_f32_16x16x32_bf16 v[56:59], v[182:185], v[210:213], v[56:59]
	v_mfma_f32_16x16x32_bf16 v[44:47], v[146:149], v[214:217], v[44:47]
	v_mfma_f32_16x16x32_bf16 v[44:47], v[174:177], v[218:221], v[44:47]
	v_mfma_f32_16x16x32_bf16 v[40:43], v[178:181], v[214:217], v[40:43]
	v_mfma_f32_16x16x32_bf16 v[40:43], v[182:185], v[218:221], v[40:43]
	v_mfma_f32_16x16x32_bf16 v[28:31], v[146:149], v[222:225], v[28:31]
	v_mfma_f32_16x16x32_bf16 v[28:31], v[174:177], v[226:229], v[28:31]
	v_mfma_f32_16x16x32_bf16 v[24:27], v[178:181], v[222:225], v[24:27]
	v_mfma_f32_16x16x32_bf16 v[24:27], v[182:185], v[226:229], v[24:27]
	v_mfma_f32_16x16x32_bf16 v[12:15], v[146:149], v[230:233], v[12:15]
	v_mfma_f32_16x16x32_bf16 v[12:15], v[174:177], v[234:237], v[12:15]
	v_mfma_f32_16x16x32_bf16 v[8:11], v[178:181], v[230:233], v[8:11]
	v_mfma_f32_16x16x32_bf16 v[8:11], v[182:185], v[234:237], v[8:11]
	s_setprio 0
	s_setprio 1
	v_mfma_f32_16x16x32_bf16 v[52:55], v[186:189], v[206:209], v[52:55]
	v_mfma_f32_16x16x32_bf16 v[52:55], v[194:197], v[210:213], v[52:55]
	v_mfma_f32_16x16x32_bf16 v[48:51], v[198:201], v[206:209], v[48:51]
	v_mfma_f32_16x16x32_bf16 v[48:51], v[202:205], v[210:213], v[48:51]
	v_mfma_f32_16x16x32_bf16 v[36:39], v[186:189], v[214:217], v[36:39]
	v_mfma_f32_16x16x32_bf16 v[36:39], v[194:197], v[218:221], v[36:39]
	v_mfma_f32_16x16x32_bf16 v[32:35], v[198:201], v[214:217], v[32:35]
	v_mfma_f32_16x16x32_bf16 v[32:35], v[202:205], v[218:221], v[32:35]
	v_mfma_f32_16x16x32_bf16 v[20:23], v[186:189], v[222:225], v[20:23]
	v_mfma_f32_16x16x32_bf16 v[20:23], v[194:197], v[226:229], v[20:23]
	v_mfma_f32_16x16x32_bf16 v[16:19], v[198:201], v[222:225], v[16:19]
	v_mfma_f32_16x16x32_bf16 v[16:19], v[202:205], v[226:229], v[16:19]
	v_mfma_f32_16x16x32_bf16 v[4:7], v[186:189], v[230:233], v[4:7]
	v_mfma_f32_16x16x32_bf16 v[4:7], v[194:197], v[234:237], v[4:7]
	v_mfma_f32_16x16x32_bf16 v[0:3], v[198:201], v[230:233], v[0:3]
	v_mfma_f32_16x16x32_bf16 v[0:3], v[202:205], v[234:237], v[0:3]
	s_barrier
	s_setprio 0
	s_add_i32 s39, 0, 0x18000
	v_add_u32_e32 v145, s39, v151
	s_add_i32 s46, 0, 0x1c000
	ds_read_b128 v[146:149], v145
	ds_read_b128 v[174:177], v145 offset:1024
	ds_read_b128 v[178:181], v145 offset:2048
	ds_read_b128 v[182:185], v145 offset:3072
	v_add_u32_e32 v145, s46, v151
	ds_read_b128 v[186:189], v145
	ds_read_b128 v[194:197], v145 offset:1024
	ds_read_b128 v[198:201], v145 offset:2048
	ds_read_b128 v[202:205], v145 offset:3072
	s_add_u32 s44, s44, 0x80000
	s_addc_u32 s45, s45, 0
	s_mov_b32 m0, s52
	v_lshl_add_u64 v[244:245], s[44:45], 0, v[128:129]
	ds_read_b128 v[206:209], v155 offset:32768
	ds_read_b128 v[210:213], v155 offset:33792
	ds_read_b128 v[214:217], v155 offset:34816
	ds_read_b128 v[218:221], v155 offset:35840
	ds_read_b128 v[222:225], v155 offset:36864
	ds_read_b128 v[226:229], v155 offset:37888
	ds_read_b128 v[230:233], v155 offset:38912
	ds_read_b128 v[234:237], v155 offset:39936
	global_load_lds_dwordx4 v[244:245], off
	v_lshl_add_u64 v[244:245], s[44:45], 0, v[132:133]
	s_mov_b32 m0, s53
	s_nop 0
	global_load_lds_dwordx4 v[244:245], off
	s_waitcnt vmcnt(8)
	s_waitcnt lgkmcnt(0)
	s_setprio 1
	s_barrier
	v_mfma_f32_16x16x32_bf16 v[124:127], v[146:149], v[206:209], v[124:127]
	v_mfma_f32_16x16x32_bf16 v[124:127], v[174:177], v[210:213], v[124:127]
	v_mfma_f32_16x16x32_bf16 v[120:123], v[178:181], v[206:209], v[120:123]
	v_mfma_f32_16x16x32_bf16 v[120:123], v[182:185], v[210:213], v[120:123]
	v_mfma_f32_16x16x32_bf16 v[108:111], v[146:149], v[214:217], v[108:111]
	v_mfma_f32_16x16x32_bf16 v[108:111], v[174:177], v[218:221], v[108:111]
	v_mfma_f32_16x16x32_bf16 v[104:107], v[178:181], v[214:217], v[104:107]
	v_mfma_f32_16x16x32_bf16 v[104:107], v[182:185], v[218:221], v[104:107]
	v_mfma_f32_16x16x32_bf16 v[92:95], v[146:149], v[222:225], v[92:95]
	v_mfma_f32_16x16x32_bf16 v[92:95], v[174:177], v[226:229], v[92:95]
	v_mfma_f32_16x16x32_bf16 v[88:91], v[178:181], v[222:225], v[88:91]
	v_mfma_f32_16x16x32_bf16 v[88:91], v[182:185], v[226:229], v[88:91]
	v_mfma_f32_16x16x32_bf16 v[76:79], v[146:149], v[230:233], v[76:79]
	v_mfma_f32_16x16x32_bf16 v[76:79], v[174:177], v[234:237], v[76:79]
	v_mfma_f32_16x16x32_bf16 v[72:75], v[178:181], v[230:233], v[72:75]
	v_mfma_f32_16x16x32_bf16 v[72:75], v[182:185], v[234:237], v[72:75]
	s_setprio 0
	s_setprio 1
	v_mfma_f32_16x16x32_bf16 v[116:119], v[186:189], v[206:209], v[116:119]
	v_mfma_f32_16x16x32_bf16 v[116:119], v[194:197], v[210:213], v[116:119]
	v_mfma_f32_16x16x32_bf16 v[112:115], v[198:201], v[206:209], v[112:115]
	v_mfma_f32_16x16x32_bf16 v[112:115], v[202:205], v[210:213], v[112:115]
	v_mfma_f32_16x16x32_bf16 v[100:103], v[186:189], v[214:217], v[100:103]
	v_mfma_f32_16x16x32_bf16 v[100:103], v[194:197], v[218:221], v[100:103]
	v_mfma_f32_16x16x32_bf16 v[96:99], v[198:201], v[214:217], v[96:99]
	v_mfma_f32_16x16x32_bf16 v[96:99], v[202:205], v[218:221], v[96:99]
	v_mfma_f32_16x16x32_bf16 v[84:87], v[186:189], v[222:225], v[84:87]
	v_mfma_f32_16x16x32_bf16 v[84:87], v[194:197], v[226:229], v[84:87]
	v_mfma_f32_16x16x32_bf16 v[80:83], v[198:201], v[222:225], v[80:83]
	v_mfma_f32_16x16x32_bf16 v[80:83], v[202:205], v[226:229], v[80:83]
	v_mfma_f32_16x16x32_bf16 v[68:71], v[186:189], v[230:233], v[68:71]
	v_mfma_f32_16x16x32_bf16 v[68:71], v[194:197], v[234:237], v[68:71]
	v_mfma_f32_16x16x32_bf16 v[64:67], v[198:201], v[230:233], v[64:67]
	v_mfma_f32_16x16x32_bf16 v[64:67], v[202:205], v[234:237], v[64:67]
	s_barrier
; #define PG8_STAGE(bufoff, gbase, voff) do { _Pragma("unroll") for (int _i = 0; _i < 2; ++_i) \
;         __builtin_amdgcn_global_load_lds((const unsigned*)((const char*)(gbase) + (voff)[_i]), (LAS unsigned*)(lds + (bufoff) + ldsw + _i * 8192), 16, 0, 0); } while (0)
; #define PG8_LDA(dst, b, h) do { _Pragma("unroll") for (int m = 0; m < 4; ++m) _Pragma("unroll") for (int k = 0; k < 2; ++k) dst[m][k] = *(const LAS bf16x8*)(lds + PG8_SA(b, h) + aoff + m * 2048 + k * 1024); } while (0)
; #define PG8_MMA(ai, bj, At, Bt) do { __builtin_amdgcn_s_setprio(1); _Pragma("unroll") for (int m = 0; m < 4; ++m) _Pragma("unroll") for (int n = 0; n < 2; ++n) _Pragma("unroll") for (int k = 0; k < 2; ++k) \
;         acc[ai][bj][m][n] = __builtin_amdgcn_mfma_f32_16x16x32_bf16(Bt[n][k], At[m][k], acc[ai][bj][m][n], 0, 0, 0); __builtin_amdgcn_s_setprio(0); } while (0)
; #define PG8_WAIT_V(n) asm volatile("s_waitcnt vmcnt(" #n ")" ::: "memory")
; #define PG8_WAIT_L(n) asm volatile("s_waitcnt lgkmcnt(" #n ")" ::: "memory")
; #define PG8_BAR __builtin_amdgcn_s_barrier()
; #define PG8_SCHED __builtin_amdgcn_sched_barrier(0)
; template <class Epi, bool ALIGN_EPI>
; __device__ __forceinline__ void gemm_phase(LAS unsigned char* lds, const Gemm g, const StaticOrder& S, const Epi& E) {
;     ...
;             PG8_WAIT_V(8); PG8_WAIT_L(0); PG8_BAR; PG8_MMA(0, 0, At, B0); PG8_MMA(0, 1, At, B1); PG8_BAR; PG8_SCHED;
;             PG8_LDA(At, 1, 1); PG8_STAGE(PG8_SB(1, 0), b3, voffB); PG8_STAGE(PG8_SB(1, 1), b3 + hB, voffB); PG8_STAGE(PG8_SA(1, 0), a3, voffA);
;             PG8_WAIT_V(8); PG8_WAIT_L(0); PG8_BAR; PG8_MMA(1, 0, At, B0); PG8_MMA(1, 1, At, B1); PG8_BAR; PG8_SCHED;
;         }
;         if constexpr (ALIGN_EPI) { if (wr == 0) PG8_BAR; }
	s_setprio 0
	s_add_i32 s39, s39, s51
	v_lshl_add_u64 v[190:191], v[190:191], 0, s[20:21]
	s_mov_b32 m0, s39
	ds_read_b128 v[206:209], v155 offset:49152
	ds_read_b128 v[210:213], v155 offset:50176
	ds_read_b128 v[214:217], v155 offset:51200
	ds_read_b128 v[218:221], v155 offset:52224
	ds_read_b128 v[222:225], v155 offset:53248
	ds_read_b128 v[226:229], v155 offset:54272
	ds_read_b128 v[230:233], v155 offset:55296
	ds_read_b128 v[234:237], v155 offset:56320
	global_load_lds_dwordx4 v[190:191], off
	s_add_i32 m0, s39, 0x2000
	s_add_u32 s36, s36, 0x80080
	v_lshl_add_u64 v[190:191], v[238:239], 0, s[20:21]
	s_addc_u32 s37, s37, 0
	s_add_i32 s39, s46, s51
	global_load_lds_dwordx4 v[190:191], off
	v_lshl_add_u64 v[190:191], s[36:37], 0, v[130:131]
	s_mov_b32 m0, s39
	s_nop 0
	global_load_lds_dwordx4 v[190:191], off
	v_lshl_add_u64 v[190:191], s[36:37], 0, v[134:135]
	s_add_i32 m0, s39, 0x2000
	s_nop 0
	global_load_lds_dwordx4 v[190:191], off
	v_lshl_add_u64 v[190:191], v[240:241], 0, s[20:21]
	s_mov_b32 m0, s57
	s_nop 0
	global_load_lds_dwordx4 v[190:191], off
	v_lshl_add_u64 v[190:191], v[242:243], 0, s[20:21]
	s_mov_b32 m0, s58
	s_nop 0
	global_load_lds_dwordx4 v[190:191], off
	s_waitcnt vmcnt(8)
	s_waitcnt lgkmcnt(0)
	s_setprio 1
	s_barrier
	v_mfma_f32_16x16x32_bf16 v[60:63], v[146:149], v[206:209], v[60:63]
	v_mfma_f32_16x16x32_bf16 v[60:63], v[174:177], v[210:213], v[60:63]
	v_mfma_f32_16x16x32_bf16 v[56:59], v[178:181], v[206:209], v[56:59]
	v_mfma_f32_16x16x32_bf16 v[56:59], v[182:185], v[210:213], v[56:59]
	v_mfma_f32_16x16x32_bf16 v[44:47], v[146:149], v[214:217], v[44:47]
	v_mfma_f32_16x16x32_bf16 v[44:47], v[174:177], v[218:221], v[44:47]
	v_mfma_f32_16x16x32_bf16 v[40:43], v[178:181], v[214:217], v[40:43]
	v_mfma_f32_16x16x32_bf16 v[40:43], v[182:185], v[218:221], v[40:43]
	v_mfma_f32_16x16x32_bf16 v[28:31], v[146:149], v[222:225], v[28:31]
	v_mfma_f32_16x16x32_bf16 v[28:31], v[174:177], v[226:229], v[28:31]
	v_mfma_f32_16x16x32_bf16 v[24:27], v[178:181], v[222:225], v[24:27]
	v_mfma_f32_16x16x32_bf16 v[24:27], v[182:185], v[226:229], v[24:27]
	v_mfma_f32_16x16x32_bf16 v[12:15], v[146:149], v[230:233], v[12:15]
	v_mfma_f32_16x16x32_bf16 v[12:15], v[174:177], v[234:237], v[12:15]
	v_mfma_f32_16x16x32_bf16 v[8:11], v[178:181], v[230:233], v[8:11]
	v_mfma_f32_16x16x32_bf16 v[8:11], v[182:185], v[234:237], v[8:11]
	s_setprio 0
	s_setprio 1
	v_mfma_f32_16x16x32_bf16 v[52:55], v[186:189], v[206:209], v[52:55]
	v_mfma_f32_16x16x32_bf16 v[52:55], v[194:197], v[210:213], v[52:55]
	v_mfma_f32_16x16x32_bf16 v[48:51], v[198:201], v[206:209], v[48:51]
	v_mfma_f32_16x16x32_bf16 v[48:51], v[202:205], v[210:213], v[48:51]
	v_mfma_f32_16x16x32_bf16 v[36:39], v[186:189], v[214:217], v[36:39]
	v_mfma_f32_16x16x32_bf16 v[36:39], v[194:197], v[218:221], v[36:39]
	v_mfma_f32_16x16x32_bf16 v[32:35], v[198:201], v[214:217], v[32:35]
	v_mfma_f32_16x16x32_bf16 v[32:35], v[202:205], v[218:221], v[32:35]
	v_mfma_f32_16x16x32_bf16 v[20:23], v[186:189], v[222:225], v[20:23]
	v_mfma_f32_16x16x32_bf16 v[20:23], v[194:197], v[226:229], v[20:23]
	v_mfma_f32_16x16x32_bf16 v[16:19], v[198:201], v[222:225], v[16:19]
	v_mfma_f32_16x16x32_bf16 v[16:19], v[202:205], v[226:229], v[16:19]
	v_mfma_f32_16x16x32_bf16 v[4:7], v[186:189], v[230:233], v[4:7]
	v_mfma_f32_16x16x32_bf16 v[4:7], v[194:197], v[234:237], v[4:7]
	v_mfma_f32_16x16x32_bf16 v[0:3], v[198:201], v[230:233], v[0:3]
	v_mfma_f32_16x16x32_bf16 v[0:3], v[202:205], v[234:237], v[0:3]
	s_barrier
	s_setprio 0
	s_add_i32 s38, s38, 2
	s_add_u32 s4, s4, 0x100
	s_addc_u32 s5, s5, 0
	s_add_u32 s27, s27, 0x100
	s_addc_u32 s29, s29, 0
	s_cmp_gt_u32 s38, 29
	s_cbranch_scc0 .LBB0_1094
	s_and_b64 vcc, exec, s[22:23]
	s_cbranch_vccz .LBB0_1097
	s_barrier

; #define PG8_STAGE(bufoff, gbase, voff) do { _Pragma("unroll") for (int _i = 0; _i < 2; ++_i) \
;         __builtin_amdgcn_global_load_lds((const unsigned*)((const char*)(gbase) + (voff)[_i]), (LAS unsigned*)(lds + (bufoff) + ldsw + _i * 8192), 16, 0, 0); } while (0)
; #define PG8_LDA(dst, b, h) do { _Pragma("unroll") for (int m = 0; m < 4; ++m) _Pragma("unroll") for (int k = 0; k < 2; ++k) dst[m][k] = *(const LAS bf16x8*)(lds + PG8_SA(b, h) + aoff + m * 2048 + k * 1024); } while (0)
; #define PG8_LDB(dst, b, h) do { _Pragma("unroll") for (int n = 0; n < 2; ++n) _Pragma("unroll") for (int k = 0; k < 2; ++k) dst[n][k] = *(const LAS bf16x8*)(lds + PG8_SB(b, h) + boff + n * 2048 + k * 1024); } while (0)
; #define PG8_MMA(ai, bj, At, Bt) do { __builtin_amdgcn_s_setprio(1); _Pragma("unroll") for (int m = 0; m < 4; ++m) _Pragma("unroll") for (int n = 0; n < 2; ++n) _Pragma("unroll") for (int k = 0; k < 2; ++k) \
;         acc[ai][bj][m][n] = __builtin_amdgcn_mfma_f32_16x16x32_bf16(Bt[n][k], At[m][k], acc[ai][bj][m][n], 0, 0, 0); __builtin_amdgcn_s_setprio(0); } while (0)
; #define PG8_WAIT_V(n) asm volatile("s_waitcnt vmcnt(" #n ")" ::: "memory")
; #define PG8_WAIT_L(n) asm volatile("s_waitcnt lgkmcnt(" #n ")" ::: "memory")
; #define PG8_BAR __builtin_amdgcn_s_barrier()
; #define PG8_SCHED __builtin_amdgcn_sched_barrier(0)
; template <class Epi, bool ALIGN_EPI>
; __device__ __forceinline__ void gemm_phase(LAS unsigned char* lds, const Gemm g, const StaticOrder& S, const Epi& E) {
;     ...
;         for (int t = 0; t < nt; t += 2) {
;             const bool last = (t == nt - 2);
;             const char* a1 = cA + (size_t)(t + 1) * kstep;
;             const char* a2 = last ? nA : cA + (size_t)(t + 2) * kstep; const char* b2 = last ? nB : cB + (size_t)(t + 2) * kstep;
;             const char* a3 = a2 + kstep; const char* b3 = b2 + kstep;
;             PG8_LDB(B0, 0, 0); PG8_LDB(B1, 0, 1); PG8_SCHED; PG8_LDA(At, 0, 0); PG8_STAGE(PG8_SA(1, 1), a1 + hA, voffA);
;             PG8_WAIT_V(8); PG8_WAIT_L(0); PG8_BAR; PG8_MMA(0, 0, At, B0); PG8_MMA(0, 1, At, B1); PG8_BAR; PG8_SCHED;
;             PG8_LDA(At, 0, 1); PG8_STAGE(PG8_SB(0, 0), b2, voffB); PG8_STAGE(PG8_SB(0, 1), b2 + hB, voffB); PG8_STAGE(PG8_SA(0, 0), a2, voffA);
;             PG8_WAIT_V(8); PG8_WAIT_L(0); PG8_BAR; PG8_MMA(1, 0, At, B0); PG8_MMA(1, 1, At, B1); PG8_BAR; PG8_SCHED;
.LBB0_1585:
	ds_read_b128 v[128:131], v175
	ds_read_b128 v[132:135], v175 offset:1024
	ds_read_b128 v[136:139], v175 offset:2048
	ds_read_b128 v[140:143], v175 offset:3072
	ds_read_b128 v[160:163], v176
	ds_read_b128 v[164:167], v176 offset:1024
	ds_read_b128 v[168:171], v176 offset:2048
	ds_read_b128 v[180:183], v176 offset:3072
	s_add_u32 s40, s36, 0xfff80080
	s_addc_u32 s41, s37, -1
	s_cmp_eq_u32 s57, 28
	s_cselect_b32 s43, s25, s41
	s_cselect_b32 s42, s31, s40
	s_cselect_b32 s41, s23, s56
	s_cselect_b32 s40, s54, s55
	v_lshl_add_u64 v[218:219], s[36:37], 0, v[152:153]
	s_add_i32 m0, s35, 0xc000
	ds_read_b128 v[184:187], v177
	ds_read_b128 v[188:191], v177 offset:1024
	ds_read_b128 v[194:197], v177 offset:2048
	ds_read_b128 v[198:201], v177 offset:3072
	ds_read_b128 v[202:205], v177 offset:4096
	ds_read_b128 v[206:209], v177 offset:5120
	ds_read_b128 v[210:213], v177 offset:6144
	ds_read_b128 v[214:217], v177 offset:7168
	global_load_lds_dwordx4 v[218:219], off
	v_lshl_add_u64 v[218:219], s[36:37], 0, v[154:155]
	s_add_i32 m0, s35, 0xe000
	s_nop 0
	global_load_lds_dwordx4 v[218:219], off
	s_waitcnt vmcnt(8)
	s_waitcnt lgkmcnt(0)
	s_setprio 1
	s_barrier
	v_mfma_f32_16x16x32_bf16 v[124:127], v[128:131], v[184:187], v[124:127]
	v_mfma_f32_16x16x32_bf16 v[124:127], v[132:135], v[188:191], v[124:127]
	v_mfma_f32_16x16x32_bf16 v[120:123], v[136:139], v[184:187], v[120:123]
	v_mfma_f32_16x16x32_bf16 v[120:123], v[140:143], v[188:191], v[120:123]
	v_mfma_f32_16x16x32_bf16 v[112:115], v[128:131], v[194:197], v[112:115]
	v_mfma_f32_16x16x32_bf16 v[112:115], v[132:135], v[198:201], v[112:115]
	v_mfma_f32_16x16x32_bf16 v[104:107], v[136:139], v[194:197], v[104:107]
	v_mfma_f32_16x16x32_bf16 v[104:107], v[140:143], v[198:201], v[104:107]
	v_mfma_f32_16x16x32_bf16 v[92:95], v[128:131], v[202:205], v[92:95]
	v_mfma_f32_16x16x32_bf16 v[92:95], v[132:135], v[206:209], v[92:95]
	v_mfma_f32_16x16x32_bf16 v[88:91], v[136:139], v[202:205], v[88:91]
	v_mfma_f32_16x16x32_bf16 v[88:91], v[140:143], v[206:209], v[88:91]
	v_mfma_f32_16x16x32_bf16 v[76:79], v[128:131], v[210:213], v[76:79]
	v_mfma_f32_16x16x32_bf16 v[76:79], v[132:135], v[214:217], v[76:79]
	v_mfma_f32_16x16x32_bf16 v[72:75], v[136:139], v[210:213], v[72:75]
	v_mfma_f32_16x16x32_bf16 v[72:75], v[140:143], v[214:217], v[72:75]
	s_setprio 0
	s_setprio 1
	v_mfma_f32_16x16x32_bf16 v[116:119], v[160:163], v[184:187], v[116:119]
	v_mfma_f32_16x16x32_bf16 v[116:119], v[164:167], v[188:191], v[116:119]
	v_mfma_f32_16x16x32_bf16 v[108:111], v[168:171], v[184:187], v[108:111]
	v_mfma_f32_16x16x32_bf16 v[108:111], v[180:183], v[188:191], v[108:111]
	v_mfma_f32_16x16x32_bf16 v[100:103], v[160:163], v[194:197], v[100:103]
	v_mfma_f32_16x16x32_bf16 v[100:103], v[164:167], v[198:201], v[100:103]
	v_mfma_f32_16x16x32_bf16 v[96:99], v[168:171], v[194:197], v[96:99]
	v_mfma_f32_16x16x32_bf16 v[96:99], v[180:183], v[198:201], v[96:99]
	v_mfma_f32_16x16x32_bf16 v[84:87], v[160:163], v[202:205], v[84:87]
	v_mfma_f32_16x16x32_bf16 v[84:87], v[164:167], v[206:209], v[84:87]
	v_mfma_f32_16x16x32_bf16 v[80:83], v[168:171], v[202:205], v[80:83]
	v_mfma_f32_16x16x32_bf16 v[80:83], v[180:183], v[206:209], v[80:83]
	v_mfma_f32_16x16x32_bf16 v[68:71], v[160:163], v[210:213], v[68:71]
	v_mfma_f32_16x16x32_bf16 v[68:71], v[164:167], v[214:217], v[68:71]
	v_mfma_f32_16x16x32_bf16 v[64:67], v[168:171], v[210:213], v[64:67]
	v_mfma_f32_16x16x32_bf16 v[64:67], v[180:183], v[214:217], v[64:67]
	s_barrier
	s_setprio 0
	s_add_i32 s58, s51, s33
	v_lshl_add_u64 v[218:219], s[40:41], 0, v[146:147]
	s_mov_b32 m0, s58
	ds_read_b128 v[184:187], v177 offset:16384
	ds_read_b128 v[188:191], v177 offset:17408
	ds_read_b128 v[194:197], v177 offset:18432
	ds_read_b128 v[198:201], v177 offset:19456
	ds_read_b128 v[202:205], v177 offset:20480
	ds_read_b128 v[206:209], v177 offset:21504
	ds_read_b128 v[210:213], v177 offset:22528
	ds_read_b128 v[214:217], v177 offset:23552
	global_load_lds_dwordx4 v[218:219], off
	s_add_i32 m0, s58, 0x2000
	s_add_u32 s58, s40, 0x80000
	v_lshl_add_u64 v[220:221], s[40:41], 0, v[150:151]
	s_addc_u32 s59, s41, 0
	s_add_i32 s60, s52, s33
	global_load_lds_dwordx4 v[220:221], off
	v_lshl_add_u64 v[222:223], s[58:59], 0, v[146:147]
	s_mov_b32 m0, s60
	v_lshl_add_u64 v[224:225], s[42:43], 0, v[148:149]
	global_load_lds_dwordx4 v[222:223], off
	v_lshl_add_u64 v[222:223], s[58:59], 0, v[150:151]
	s_add_i32 m0, s60, 0x2000
	s_nop 0
	global_load_lds_dwordx4 v[222:223], off
	v_lshl_add_u64 v[222:223], s[42:43], 0, v[144:145]
	s_mov_b32 m0, s35
	s_nop 0
	global_load_lds_dwordx4 v[222:223], off
	s_mov_b32 m0, s38
	s_nop 0
	global_load_lds_dwordx4 v[224:225], off
	s_waitcnt vmcnt(8)
	s_waitcnt lgkmcnt(0)
	s_setprio 1
	s_barrier
; #define PG8_STAGE(bufoff, gbase, voff) do { _Pragma("unroll") for (int _i = 0; _i < 2; ++_i) \
;         __builtin_amdgcn_global_load_lds((const unsigned*)((const char*)(gbase) + (voff)[_i]), (LAS unsigned*)(lds + (bufoff) + ldsw + _i * 8192), 16, 0, 0); } while (0)
; #define PG8_LDA(dst, b, h) do { _Pragma("unroll") for (int m = 0; m < 4; ++m) _Pragma("unroll") for (int k = 0; k < 2; ++k) dst[m][k] = *(const LAS bf16x8*)(lds + PG8_SA(b, h) + aoff + m * 2048 + k * 1024); } while (0)
; #define PG8_LDB(dst, b, h) do { _Pragma("unroll") for (int n = 0; n < 2; ++n) _Pragma("unroll") for (int k = 0; k < 2; ++k) dst[n][k] = *(const LAS bf16x8*)(lds + PG8_SB(b, h) + boff + n * 2048 + k * 1024); } while (0)
; #define PG8_MMA(ai, bj, At, Bt) do { __builtin_amdgcn_s_setprio(1); _Pragma("unroll") for (int m = 0; m < 4; ++m) _Pragma("unroll") for (int n = 0; n < 2; ++n) _Pragma("unroll") for (int k = 0; k < 2; ++k) \
;         acc[ai][bj][m][n] = __builtin_amdgcn_mfma_f32_16x16x32_bf16(Bt[n][k], At[m][k], acc[ai][bj][m][n], 0, 0, 0); __builtin_amdgcn_s_setprio(0); } while (0)
; #define PG8_WAIT_V(n) asm volatile("s_waitcnt vmcnt(" #n ")" ::: "memory")
; #define PG8_WAIT_L(n) asm volatile("s_waitcnt lgkmcnt(" #n ")" ::: "memory")
; #define PG8_BAR __builtin_amdgcn_s_barrier()
; #define PG8_SCHED __builtin_amdgcn_sched_barrier(0)
; template <class Epi, bool ALIGN_EPI>
; __device__ __forceinline__ void gemm_phase(LAS unsigned char* lds, const Gemm g, const StaticOrder& S, const Epi& E) {
;     ...
;             PG8_WAIT_V(8); PG8_WAIT_L(0); PG8_BAR; PG8_MMA(1, 0, At, B0); PG8_MMA(1, 1, At, B1); PG8_BAR; PG8_SCHED;
;             PG8_LDB(B0, 1, 0); PG8_LDB(B1, 1, 1); PG8_SCHED; PG8_LDA(At, 1, 0); PG8_STAGE(PG8_SA(0, 1), a2 + hA, voffA);
;             PG8_WAIT_V(8); PG8_WAIT_L(0); PG8_BAR; PG8_MMA(0, 0, At, B0); PG8_MMA(0, 1, At, B1); PG8_BAR; PG8_SCHED;
	v_mfma_f32_16x16x32_bf16 v[60:63], v[128:131], v[184:187], v[60:63]
	v_mfma_f32_16x16x32_bf16 v[60:63], v[132:135], v[188:191], v[60:63]
	v_mfma_f32_16x16x32_bf16 v[56:59], v[136:139], v[184:187], v[56:59]
	v_mfma_f32_16x16x32_bf16 v[56:59], v[140:143], v[188:191], v[56:59]
	v_mfma_f32_16x16x32_bf16 v[44:47], v[128:131], v[194:197], v[44:47]
	v_mfma_f32_16x16x32_bf16 v[44:47], v[132:135], v[198:201], v[44:47]
	v_mfma_f32_16x16x32_bf16 v[40:43], v[136:139], v[194:197], v[40:43]
	v_mfma_f32_16x16x32_bf16 v[40:43], v[140:143], v[198:201], v[40:43]
	v_mfma_f32_16x16x32_bf16 v[28:31], v[128:131], v[202:205], v[28:31]
	v_mfma_f32_16x16x32_bf16 v[28:31], v[132:135], v[206:209], v[28:31]
	v_mfma_f32_16x16x32_bf16 v[24:27], v[136:139], v[202:205], v[24:27]
	v_mfma_f32_16x16x32_bf16 v[24:27], v[140:143], v[206:209], v[24:27]
	v_mfma_f32_16x16x32_bf16 v[12:15], v[128:131], v[210:213], v[12:15]
	v_mfma_f32_16x16x32_bf16 v[12:15], v[132:135], v[214:217], v[12:15]
	v_mfma_f32_16x16x32_bf16 v[8:11], v[136:139], v[210:213], v[8:11]
	v_mfma_f32_16x16x32_bf16 v[8:11], v[140:143], v[214:217], v[8:11]
	s_setprio 0
	s_setprio 1
	v_mfma_f32_16x16x32_bf16 v[52:55], v[160:163], v[184:187], v[52:55]
	v_mfma_f32_16x16x32_bf16 v[52:55], v[164:167], v[188:191], v[52:55]
	v_mfma_f32_16x16x32_bf16 v[48:51], v[168:171], v[184:187], v[48:51]
	v_mfma_f32_16x16x32_bf16 v[48:51], v[180:183], v[188:191], v[48:51]
	v_mfma_f32_16x16x32_bf16 v[36:39], v[160:163], v[194:197], v[36:39]
	v_mfma_f32_16x16x32_bf16 v[36:39], v[164:167], v[198:201], v[36:39]
	v_mfma_f32_16x16x32_bf16 v[32:35], v[168:171], v[194:197], v[32:35]
	v_mfma_f32_16x16x32_bf16 v[32:35], v[180:183], v[198:201], v[32:35]
	v_mfma_f32_16x16x32_bf16 v[20:23], v[160:163], v[202:205], v[20:23]
	v_mfma_f32_16x16x32_bf16 v[20:23], v[164:167], v[206:209], v[20:23]
	v_mfma_f32_16x16x32_bf16 v[16:19], v[168:171], v[202:205], v[16:19]
	v_mfma_f32_16x16x32_bf16 v[16:19], v[180:183], v[206:209], v[16:19]
	v_mfma_f32_16x16x32_bf16 v[4:7], v[160:163], v[210:213], v[4:7]
	v_mfma_f32_16x16x32_bf16 v[4:7], v[164:167], v[214:217], v[4:7]
	v_mfma_f32_16x16x32_bf16 v[0:3], v[168:171], v[210:213], v[0:3]
	v_mfma_f32_16x16x32_bf16 v[0:3], v[180:183], v[214:217], v[0:3]
	s_barrier
	s_setprio 0
	s_add_i32 s58, 0, 0x18000
	s_add_i32 s59, 0, 0x1c000
	v_add_u32_e32 v140, s58, v173
	v_add_u32_e32 v179, s59, v173
	ds_read_b128 v[128:131], v140
	ds_read_b128 v[132:135], v140 offset:1024
	ds_read_b128 v[136:139], v140 offset:2048
	ds_read_b128 v[140:143], v140 offset:3072
	ds_read_b128 v[160:163], v179
	ds_read_b128 v[164:167], v179 offset:1024
	ds_read_b128 v[168:171], v179 offset:2048
	ds_read_b128 v[180:183], v179 offset:3072
	s_add_u32 s42, s42, 0x80000
	s_addc_u32 s43, s43, 0
	s_mov_b32 m0, s39
	v_lshl_add_u64 v[226:227], s[42:43], 0, v[144:145]
	ds_read_b128 v[184:187], v177 offset:32768
	ds_read_b128 v[188:191], v177 offset:33792
	ds_read_b128 v[194:197], v177 offset:34816
	ds_read_b128 v[198:201], v177 offset:35840
	ds_read_b128 v[202:205], v177 offset:36864
	ds_read_b128 v[206:209], v177 offset:37888
	ds_read_b128 v[210:213], v177 offset:38912
	ds_read_b128 v[214:217], v177 offset:39936
	global_load_lds_dwordx4 v[226:227], off
	v_lshl_add_u64 v[226:227], s[42:43], 0, v[148:149]
	s_mov_b32 m0, s44
	s_nop 0
	global_load_lds_dwordx4 v[226:227], off
	s_waitcnt vmcnt(8)
	s_waitcnt lgkmcnt(0)
	s_setprio 1
	s_barrier
	v_mfma_f32_16x16x32_bf16 v[124:127], v[128:131], v[184:187], v[124:127]
	v_mfma_f32_16x16x32_bf16 v[124:127], v[132:135], v[188:191], v[124:127]
	v_mfma_f32_16x16x32_bf16 v[120:123], v[136:139], v[184:187], v[120:123]
	v_mfma_f32_16x16x32_bf16 v[120:123], v[140:143], v[188:191], v[120:123]
	v_mfma_f32_16x16x32_bf16 v[112:115], v[128:131], v[194:197], v[112:115]
	v_mfma_f32_16x16x32_bf16 v[112:115], v[132:135], v[198:201], v[112:115]
	v_mfma_f32_16x16x32_bf16 v[104:107], v[136:139], v[194:197], v[104:107]
	v_mfma_f32_16x16x32_bf16 v[104:107], v[140:143], v[198:201], v[104:107]
	v_mfma_f32_16x16x32_bf16 v[92:95], v[128:131], v[202:205], v[92:95]
	v_mfma_f32_16x16x32_bf16 v[92:95], v[132:135], v[206:209], v[92:95]
	v_mfma_f32_16x16x32_bf16 v[88:91], v[136:139], v[202:205], v[88:91]
	v_mfma_f32_16x16x32_bf16 v[88:91], v[140:143], v[206:209], v[88:91]
	v_mfma_f32_16x16x32_bf16 v[76:79], v[128:131], v[210:213], v[76:79]
	v_mfma_f32_16x16x32_bf16 v[76:79], v[132:135], v[214:217], v[76:79]
	v_mfma_f32_16x16x32_bf16 v[72:75], v[136:139], v[210:213], v[72:75]
	v_mfma_f32_16x16x32_bf16 v[72:75], v[140:143], v[214:217], v[72:75]
	s_setprio 0
	s_setprio 1
	v_mfma_f32_16x16x32_bf16 v[116:119], v[160:163], v[184:187], v[116:119]
	v_mfma_f32_16x16x32_bf16 v[116:119], v[164:167], v[188:191], v[116:119]
	v_mfma_f32_16x16x32_bf16 v[108:111], v[168:171], v[184:187], v[108:111]
	v_mfma_f32_16x16x32_bf16 v[108:111], v[180:183], v[188:191], v[108:111]
	v_mfma_f32_16x16x32_bf16 v[100:103], v[160:163], v[194:197], v[100:103]
	v_mfma_f32_16x16x32_bf16 v[100:103], v[164:167], v[198:201], v[100:103]
	v_mfma_f32_16x16x32_bf16 v[96:99], v[168:171], v[194:197], v[96:99]
	v_mfma_f32_16x16x32_bf16 v[96:99], v[180:183], v[198:201], v[96:99]
	v_mfma_f32_16x16x32_bf16 v[84:87], v[160:163], v[202:205], v[84:87]
	v_mfma_f32_16x16x32_bf16 v[84:87], v[164:167], v[206:209], v[84:87]
	v_mfma_f32_16x16x32_bf16 v[80:83], v[168:171], v[202:205], v[80:83]
	v_mfma_f32_16x16x32_bf16 v[80:83], v[180:183], v[206:209], v[80:83]
	v_mfma_f32_16x16x32_bf16 v[68:71], v[160:163], v[210:213], v[68:71]
	v_mfma_f32_16x16x32_bf16 v[68:71], v[164:167], v[214:217], v[68:71]
	v_mfma_f32_16x16x32_bf16 v[64:67], v[168:171], v[210:213], v[64:67]
	v_mfma_f32_16x16x32_bf16 v[64:67], v[180:183], v[214:217], v[64:67]
	s_barrier
; #define PG8_STAGE(bufoff, gbase, voff) do { _Pragma("unroll") for (int _i = 0; _i < 2; ++_i) \
;         __builtin_amdgcn_global_load_lds((const unsigned*)((const char*)(gbase) + (voff)[_i]), (LAS unsigned*)(lds + (bufoff) + ldsw + _i * 8192), 16, 0, 0); } while (0)
; #define PG8_LDA(dst, b, h) do { _Pragma("unroll") for (int m = 0; m < 4; ++m) _Pragma("unroll") for (int k = 0; k < 2; ++k) dst[m][k] = *(const LAS bf16x8*)(lds + PG8_SA(b, h) + aoff + m * 2048 + k * 1024); } while (0)
; #define PG8_MMA(ai, bj, At, Bt) do { __builtin_amdgcn_s_setprio(1); _Pragma("unroll") for (int m = 0; m < 4; ++m) _Pragma("unroll") for (int n = 0; n < 2; ++n) _Pragma("unroll") for (int k = 0; k < 2; ++k) \
;         acc[ai][bj][m][n] = __builtin_amdgcn_mfma_f32_16x16x32_bf16(Bt[n][k], At[m][k], acc[ai][bj][m][n], 0, 0, 0); __builtin_amdgcn_s_setprio(0); } while (0)
; #define PG8_WAIT_V(n) asm volatile("s_waitcnt vmcnt(" #n ")" ::: "memory")
; #define PG8_WAIT_L(n) asm volatile("s_waitcnt lgkmcnt(" #n ")" ::: "memory")
; #define PG8_BAR __builtin_amdgcn_s_barrier()
; #define PG8_SCHED __builtin_amdgcn_sched_barrier(0)
; template <class Epi, bool ALIGN_EPI>
; __device__ __forceinline__ void gemm_phase(LAS unsigned char* lds, const Gemm g, const StaticOrder& S, const Epi& E) {
;     ...
;             PG8_WAIT_V(8); PG8_WAIT_L(0); PG8_BAR; PG8_MMA(0, 0, At, B0); PG8_MMA(0, 1, At, B1); PG8_BAR; PG8_SCHED;
;             PG8_LDA(At, 1, 1); PG8_STAGE(PG8_SB(1, 0), b3, voffB); PG8_STAGE(PG8_SB(1, 1), b3 + hB, voffB); PG8_STAGE(PG8_SA(1, 0), a3, voffA);
;             PG8_WAIT_V(8); PG8_WAIT_L(0); PG8_BAR; PG8_MMA(1, 0, At, B0); PG8_MMA(1, 1, At, B1); PG8_BAR; PG8_SCHED;
;         }
;         if constexpr (ALIGN_EPI) { if (wr == 0) PG8_BAR; }
	s_setprio 0
	s_add_i32 s42, s58, s33
	v_lshl_add_u64 v[218:219], v[218:219], 0, s[18:19]
	s_mov_b32 m0, s42
	ds_read_b128 v[184:187], v177 offset:49152
	ds_read_b128 v[188:191], v177 offset:50176
	ds_read_b128 v[194:197], v177 offset:51200
	ds_read_b128 v[198:201], v177 offset:52224
	ds_read_b128 v[202:205], v177 offset:53248
	ds_read_b128 v[206:209], v177 offset:54272
	ds_read_b128 v[210:213], v177 offset:55296
	ds_read_b128 v[214:217], v177 offset:56320
	global_load_lds_dwordx4 v[218:219], off
	s_add_i32 m0, s42, 0x2000
	s_add_u32 s40, s40, 0x80080
	v_lshl_add_u64 v[218:219], v[220:221], 0, s[18:19]
	s_addc_u32 s41, s41, 0
	s_add_i32 s42, s59, s33
	global_load_lds_dwordx4 v[218:219], off
	v_lshl_add_u64 v[218:219], s[40:41], 0, v[146:147]
	s_mov_b32 m0, s42
	s_nop 0
	global_load_lds_dwordx4 v[218:219], off
	v_lshl_add_u64 v[218:219], s[40:41], 0, v[150:151]
	s_add_i32 m0, s42, 0x2000
	s_nop 0
	global_load_lds_dwordx4 v[218:219], off
	v_lshl_add_u64 v[218:219], v[222:223], 0, s[18:19]
	s_mov_b32 m0, s48
	s_nop 0
	global_load_lds_dwordx4 v[218:219], off
	v_lshl_add_u64 v[218:219], v[224:225], 0, s[18:19]
	s_mov_b32 m0, s49
	s_nop 0
	global_load_lds_dwordx4 v[218:219], off
	s_waitcnt vmcnt(8)
	s_waitcnt lgkmcnt(0)
	s_setprio 1
	s_barrier
	v_mfma_f32_16x16x32_bf16 v[60:63], v[128:131], v[184:187], v[60:63]
	v_mfma_f32_16x16x32_bf16 v[60:63], v[132:135], v[188:191], v[60:63]
	v_mfma_f32_16x16x32_bf16 v[56:59], v[136:139], v[184:187], v[56:59]
	v_mfma_f32_16x16x32_bf16 v[56:59], v[140:143], v[188:191], v[56:59]
	v_mfma_f32_16x16x32_bf16 v[44:47], v[128:131], v[194:197], v[44:47]
	v_mfma_f32_16x16x32_bf16 v[44:47], v[132:135], v[198:201], v[44:47]
	v_mfma_f32_16x16x32_bf16 v[40:43], v[136:139], v[194:197], v[40:43]
	v_mfma_f32_16x16x32_bf16 v[40:43], v[140:143], v[198:201], v[40:43]
	v_mfma_f32_16x16x32_bf16 v[28:31], v[128:131], v[202:205], v[28:31]
	v_mfma_f32_16x16x32_bf16 v[28:31], v[132:135], v[206:209], v[28:31]
	v_mfma_f32_16x16x32_bf16 v[24:27], v[136:139], v[202:205], v[24:27]
	v_mfma_f32_16x16x32_bf16 v[24:27], v[140:143], v[206:209], v[24:27]
	v_mfma_f32_16x16x32_bf16 v[12:15], v[128:131], v[210:213], v[12:15]
	v_mfma_f32_16x16x32_bf16 v[12:15], v[132:135], v[214:217], v[12:15]
	v_mfma_f32_16x16x32_bf16 v[8:11], v[136:139], v[210:213], v[8:11]
	v_mfma_f32_16x16x32_bf16 v[8:11], v[140:143], v[214:217], v[8:11]
	s_setprio 0
	s_setprio 1
	v_mfma_f32_16x16x32_bf16 v[52:55], v[160:163], v[184:187], v[52:55]
	v_mfma_f32_16x16x32_bf16 v[52:55], v[164:167], v[188:191], v[52:55]
	v_mfma_f32_16x16x32_bf16 v[48:51], v[168:171], v[184:187], v[48:51]
	v_mfma_f32_16x16x32_bf16 v[48:51], v[180:183], v[188:191], v[48:51]
	v_mfma_f32_16x16x32_bf16 v[36:39], v[160:163], v[194:197], v[36:39]
	v_mfma_f32_16x16x32_bf16 v[36:39], v[164:167], v[198:201], v[36:39]
	v_mfma_f32_16x16x32_bf16 v[32:35], v[168:171], v[194:197], v[32:35]
	v_mfma_f32_16x16x32_bf16 v[32:35], v[180:183], v[198:201], v[32:35]
	v_mfma_f32_16x16x32_bf16 v[20:23], v[160:163], v[202:205], v[20:23]
	v_mfma_f32_16x16x32_bf16 v[20:23], v[164:167], v[206:209], v[20:23]
	v_mfma_f32_16x16x32_bf16 v[16:19], v[168:171], v[202:205], v[16:19]
	v_mfma_f32_16x16x32_bf16 v[16:19], v[180:183], v[206:209], v[16:19]
	v_mfma_f32_16x16x32_bf16 v[4:7], v[160:163], v[210:213], v[4:7]
	v_mfma_f32_16x16x32_bf16 v[4:7], v[164:167], v[214:217], v[4:7]
	v_mfma_f32_16x16x32_bf16 v[0:3], v[168:171], v[210:213], v[0:3]
	v_mfma_f32_16x16x32_bf16 v[0:3], v[180:183], v[214:217], v[0:3]
	s_barrier
	s_setprio 0
	s_add_i32 s57, s57, 2
	s_add_u32 s36, s36, 0x100
	s_addc_u32 s37, s37, 0
	s_add_u32 s55, s55, 0x100
	s_addc_u32 s56, s56, 0
	s_cmp_gt_u32 s57, 29
	s_cbranch_scc0 .LBB0_1585
	s_and_b64 vcc, exec, s[20:21]
	s_cbranch_vccz .LBB0_1588
	s_barrier

; #define PG8_STAGE(bufoff, gbase, voff) do { _Pragma("unroll") for (int _i = 0; _i < 2; ++_i) \
;         __builtin_amdgcn_global_load_lds((const unsigned*)((const char*)(gbase) + (voff)[_i]), (LAS unsigned*)(lds + (bufoff) + ldsw + _i * 8192), 16, 0, 0); } while (0)
; #define PG8_LDA(dst, b, h) do { _Pragma("unroll") for (int m = 0; m < 4; ++m) _Pragma("unroll") for (int k = 0; k < 2; ++k) dst[m][k] = *(const LAS bf16x8*)(lds + PG8_SA(b, h) + aoff + m * 2048 + k * 1024); } while (0)
; #define PG8_LDB(dst, b, h) do { _Pragma("unroll") for (int n = 0; n < 2; ++n) _Pragma("unroll") for (int k = 0; k < 2; ++k) dst[n][k] = *(const LAS bf16x8*)(lds + PG8_SB(b, h) + boff + n * 2048 + k * 1024); } while (0)
; #define PG8_MMA(ai, bj, At, Bt) do { __builtin_amdgcn_s_setprio(1); _Pragma("unroll") for (int m = 0; m < 4; ++m) _Pragma("unroll") for (int n = 0; n < 2; ++n) _Pragma("unroll") for (int k = 0; k < 2; ++k) \
;         acc[ai][bj][m][n] = __builtin_amdgcn_mfma_f32_16x16x32_bf16(Bt[n][k], At[m][k], acc[ai][bj][m][n], 0, 0, 0); __builtin_amdgcn_s_setprio(0); } while (0)
; #define PG8_WAIT_V(n) asm volatile("s_waitcnt vmcnt(" #n ")" ::: "memory")
; #define PG8_WAIT_L(n) asm volatile("s_waitcnt lgkmcnt(" #n ")" ::: "memory")
; #define PG8_BAR __builtin_amdgcn_s_barrier()
; #define PG8_SCHED __builtin_amdgcn_sched_barrier(0)
; template <class Epi, bool ALIGN_EPI>
; __device__ __forceinline__ void gemm_phase(LAS unsigned char* lds, const Gemm g, const StaticOrder& S, const Epi& E) {
;     ...
;         for (int t = 0; t < nt; t += 2) {
;             const bool last = (t == nt - 2);
;             const char* a1 = cA + (size_t)(t + 1) * kstep;
;             const char* a2 = last ? nA : cA + (size_t)(t + 2) * kstep; const char* b2 = last ? nB : cB + (size_t)(t + 2) * kstep;
;             const char* a3 = a2 + kstep; const char* b3 = b2 + kstep;
;             PG8_LDB(B0, 0, 0); PG8_LDB(B1, 0, 1); PG8_SCHED; PG8_LDA(At, 0, 0); PG8_STAGE(PG8_SA(1, 1), a1 + hA, voffA);
;             PG8_WAIT_V(8); PG8_WAIT_L(0); PG8_BAR; PG8_MMA(0, 0, At, B0); PG8_MMA(0, 1, At, B1); PG8_BAR; PG8_SCHED;
;             PG8_LDA(At, 0, 1); PG8_STAGE(PG8_SB(0, 0), b2, voffB); PG8_STAGE(PG8_SB(0, 1), b2 + hB, voffB); PG8_STAGE(PG8_SA(0, 0), a2, voffA);
;             PG8_WAIT_V(8); PG8_WAIT_L(0); PG8_BAR; PG8_MMA(1, 0, At, B0); PG8_MMA(1, 1, At, B1); PG8_BAR; PG8_SCHED;
.LBB0_1755:
	ds_read_b128 v[128:131], v183
	ds_read_b128 v[132:135], v183 offset:1024
	ds_read_b128 v[152:155], v183 offset:2048
	ds_read_b128 v[156:159], v183 offset:3072
	ds_read_b128 v[160:163], v184
	ds_read_b128 v[164:167], v184 offset:1024
	ds_read_b128 v[168:171], v184 offset:2048
	ds_read_b128 v[172:175], v184 offset:3072
	s_add_u32 s30, s28, 0xffe00080
	s_addc_u32 s31, s29, -1
	s_cmpk_eq_i32 s51, 0x7c
	s_cselect_b32 s35, s5, s31
	s_cselect_b32 s34, s21, s30
	s_cselect_b32 s31, s19, s50
	s_cselect_b32 s30, s48, s49
	v_lshl_add_u64 v[214:215], s[28:29], 0, v[144:145]
	s_add_i32 m0, s27, 0xc000
	ds_read_b128 v[176:179], v185
	ds_read_b128 v[186:189], v185 offset:1024
	ds_read_b128 v[190:193], v185 offset:2048
	ds_read_b128 v[194:197], v185 offset:3072
	ds_read_b128 v[198:201], v185 offset:4096
	ds_read_b128 v[202:205], v185 offset:5120
	ds_read_b128 v[206:209], v185 offset:6144
	ds_read_b128 v[210:213], v185 offset:7168
	global_load_lds_dwordx4 v[214:215], off
	v_lshl_add_u64 v[214:215], s[28:29], 0, v[146:147]
	s_add_i32 m0, s27, 0xe000
	s_nop 0
	global_load_lds_dwordx4 v[214:215], off
	s_waitcnt vmcnt(8)
	s_waitcnt lgkmcnt(0)
	s_setprio 1
	s_barrier
	v_mfma_f32_16x16x32_bf16 v[120:123], v[128:131], v[176:179], v[120:123]
	v_mfma_f32_16x16x32_bf16 v[120:123], v[132:135], v[186:189], v[120:123]
	v_mfma_f32_16x16x32_bf16 v[124:127], v[152:155], v[176:179], v[124:127]
	v_mfma_f32_16x16x32_bf16 v[124:127], v[156:159], v[186:189], v[124:127]
	v_mfma_f32_16x16x32_bf16 v[104:107], v[128:131], v[190:193], v[104:107]
	v_mfma_f32_16x16x32_bf16 v[104:107], v[132:135], v[194:197], v[104:107]
	v_mfma_f32_16x16x32_bf16 v[108:111], v[152:155], v[190:193], v[108:111]
	v_mfma_f32_16x16x32_bf16 v[108:111], v[156:159], v[194:197], v[108:111]
	v_mfma_f32_16x16x32_bf16 v[88:91], v[128:131], v[198:201], v[88:91]
	v_mfma_f32_16x16x32_bf16 v[88:91], v[132:135], v[202:205], v[88:91]
	v_mfma_f32_16x16x32_bf16 v[92:95], v[152:155], v[198:201], v[92:95]
	v_mfma_f32_16x16x32_bf16 v[92:95], v[156:159], v[202:205], v[92:95]
	v_mfma_f32_16x16x32_bf16 v[72:75], v[128:131], v[206:209], v[72:75]
	v_mfma_f32_16x16x32_bf16 v[72:75], v[132:135], v[210:213], v[72:75]
	v_mfma_f32_16x16x32_bf16 v[76:79], v[152:155], v[206:209], v[76:79]
	v_mfma_f32_16x16x32_bf16 v[76:79], v[156:159], v[210:213], v[76:79]
	s_setprio 0
	s_setprio 1
	v_mfma_f32_16x16x32_bf16 v[112:115], v[160:163], v[176:179], v[112:115]
	v_mfma_f32_16x16x32_bf16 v[112:115], v[164:167], v[186:189], v[112:115]
	v_mfma_f32_16x16x32_bf16 v[116:119], v[168:171], v[176:179], v[116:119]
	v_mfma_f32_16x16x32_bf16 v[116:119], v[172:175], v[186:189], v[116:119]
	v_mfma_f32_16x16x32_bf16 v[96:99], v[160:163], v[190:193], v[96:99]
	v_mfma_f32_16x16x32_bf16 v[96:99], v[164:167], v[194:197], v[96:99]
	v_mfma_f32_16x16x32_bf16 v[100:103], v[168:171], v[190:193], v[100:103]
	v_mfma_f32_16x16x32_bf16 v[100:103], v[172:175], v[194:197], v[100:103]
	v_mfma_f32_16x16x32_bf16 v[80:83], v[160:163], v[198:201], v[80:83]
	v_mfma_f32_16x16x32_bf16 v[80:83], v[164:167], v[202:205], v[80:83]
	v_mfma_f32_16x16x32_bf16 v[84:87], v[168:171], v[198:201], v[84:87]
	v_mfma_f32_16x16x32_bf16 v[84:87], v[172:175], v[202:205], v[84:87]
	v_mfma_f32_16x16x32_bf16 v[64:67], v[160:163], v[206:209], v[64:67]
	v_mfma_f32_16x16x32_bf16 v[64:67], v[164:167], v[210:213], v[64:67]
	v_mfma_f32_16x16x32_bf16 v[68:71], v[168:171], v[206:209], v[68:71]
	v_mfma_f32_16x16x32_bf16 v[68:71], v[172:175], v[210:213], v[68:71]
	s_barrier
	s_setprio 0
	s_add_i32 s52, s46, s37
	v_lshl_add_u64 v[214:215], s[30:31], 0, v[138:139]
	s_mov_b32 m0, s52
	ds_read_b128 v[176:179], v185 offset:16384
	ds_read_b128 v[186:189], v185 offset:17408
	ds_read_b128 v[190:193], v185 offset:18432
	ds_read_b128 v[194:197], v185 offset:19456
	ds_read_b128 v[198:201], v185 offset:20480
	ds_read_b128 v[202:205], v185 offset:21504
	ds_read_b128 v[206:209], v185 offset:22528
	ds_read_b128 v[210:213], v185 offset:23552
	global_load_lds_dwordx4 v[214:215], off
	s_add_i32 m0, s52, 0x2000
	s_add_u32 s52, s30, 0x200000
	v_lshl_add_u64 v[216:217], s[30:31], 0, v[142:143]
	s_addc_u32 s53, s31, 0
	s_add_i32 s54, s47, s37
	global_load_lds_dwordx4 v[216:217], off
	v_lshl_add_u64 v[218:219], s[52:53], 0, v[138:139]
	s_mov_b32 m0, s54
	v_lshl_add_u64 v[220:221], s[34:35], 0, v[140:141]
	global_load_lds_dwordx4 v[218:219], off
	v_lshl_add_u64 v[218:219], s[52:53], 0, v[142:143]
	s_add_i32 m0, s54, 0x2000
	s_nop 0
	global_load_lds_dwordx4 v[218:219], off
	v_lshl_add_u64 v[218:219], s[34:35], 0, v[136:137]
	s_mov_b32 m0, s27
	s_nop 0
	global_load_lds_dwordx4 v[218:219], off
	s_mov_b32 m0, s38
	s_nop 0
	global_load_lds_dwordx4 v[220:221], off
	s_waitcnt vmcnt(8)
	s_waitcnt lgkmcnt(0)
	s_setprio 1
	s_barrier
; #define PG8_STAGE(bufoff, gbase, voff) do { _Pragma("unroll") for (int _i = 0; _i < 2; ++_i) \
;         __builtin_amdgcn_global_load_lds((const unsigned*)((const char*)(gbase) + (voff)[_i]), (LAS unsigned*)(lds + (bufoff) + ldsw + _i * 8192), 16, 0, 0); } while (0)
; #define PG8_LDA(dst, b, h) do { _Pragma("unroll") for (int m = 0; m < 4; ++m) _Pragma("unroll") for (int k = 0; k < 2; ++k) dst[m][k] = *(const LAS bf16x8*)(lds + PG8_SA(b, h) + aoff + m * 2048 + k * 1024); } while (0)
; #define PG8_LDB(dst, b, h) do { _Pragma("unroll") for (int n = 0; n < 2; ++n) _Pragma("unroll") for (int k = 0; k < 2; ++k) dst[n][k] = *(const LAS bf16x8*)(lds + PG8_SB(b, h) + boff + n * 2048 + k * 1024); } while (0)
; #define PG8_MMA(ai, bj, At, Bt) do { __builtin_amdgcn_s_setprio(1); _Pragma("unroll") for (int m = 0; m < 4; ++m) _Pragma("unroll") for (int n = 0; n < 2; ++n) _Pragma("unroll") for (int k = 0; k < 2; ++k) \
;         acc[ai][bj][m][n] = __builtin_amdgcn_mfma_f32_16x16x32_bf16(Bt[n][k], At[m][k], acc[ai][bj][m][n], 0, 0, 0); __builtin_amdgcn_s_setprio(0); } while (0)
; #define PG8_WAIT_V(n) asm volatile("s_waitcnt vmcnt(" #n ")" ::: "memory")
; #define PG8_WAIT_L(n) asm volatile("s_waitcnt lgkmcnt(" #n ")" ::: "memory")
; #define PG8_BAR __builtin_amdgcn_s_barrier()
; #define PG8_SCHED __builtin_amdgcn_sched_barrier(0)
; template <class Epi, bool ALIGN_EPI>
; __device__ __forceinline__ void gemm_phase(LAS unsigned char* lds, const Gemm g, const StaticOrder& S, const Epi& E) {
;     ...
;             PG8_WAIT_V(8); PG8_WAIT_L(0); PG8_BAR; PG8_MMA(1, 0, At, B0); PG8_MMA(1, 1, At, B1); PG8_BAR; PG8_SCHED;
;             PG8_LDB(B0, 1, 0); PG8_LDB(B1, 1, 1); PG8_SCHED; PG8_LDA(At, 1, 0); PG8_STAGE(PG8_SA(0, 1), a2 + hA, voffA);
;             PG8_WAIT_V(8); PG8_WAIT_L(0); PG8_BAR; PG8_MMA(0, 0, At, B0); PG8_MMA(0, 1, At, B1); PG8_BAR; PG8_SCHED;
	v_mfma_f32_16x16x32_bf16 v[56:59], v[128:131], v[176:179], v[56:59]
	v_mfma_f32_16x16x32_bf16 v[56:59], v[132:135], v[186:189], v[56:59]
	v_mfma_f32_16x16x32_bf16 v[60:63], v[152:155], v[176:179], v[60:63]
	v_mfma_f32_16x16x32_bf16 v[60:63], v[156:159], v[186:189], v[60:63]
	v_mfma_f32_16x16x32_bf16 v[40:43], v[128:131], v[190:193], v[40:43]
	v_mfma_f32_16x16x32_bf16 v[40:43], v[132:135], v[194:197], v[40:43]
	v_mfma_f32_16x16x32_bf16 v[44:47], v[152:155], v[190:193], v[44:47]
	v_mfma_f32_16x16x32_bf16 v[44:47], v[156:159], v[194:197], v[44:47]
	v_mfma_f32_16x16x32_bf16 v[24:27], v[128:131], v[198:201], v[24:27]
	v_mfma_f32_16x16x32_bf16 v[24:27], v[132:135], v[202:205], v[24:27]
	v_mfma_f32_16x16x32_bf16 v[28:31], v[152:155], v[198:201], v[28:31]
	v_mfma_f32_16x16x32_bf16 v[28:31], v[156:159], v[202:205], v[28:31]
	v_mfma_f32_16x16x32_bf16 v[8:11], v[128:131], v[206:209], v[8:11]
	v_mfma_f32_16x16x32_bf16 v[8:11], v[132:135], v[210:213], v[8:11]
	v_mfma_f32_16x16x32_bf16 v[12:15], v[152:155], v[206:209], v[12:15]
	v_mfma_f32_16x16x32_bf16 v[12:15], v[156:159], v[210:213], v[12:15]
	s_setprio 0
	s_setprio 1
	v_mfma_f32_16x16x32_bf16 v[48:51], v[160:163], v[176:179], v[48:51]
	v_mfma_f32_16x16x32_bf16 v[48:51], v[164:167], v[186:189], v[48:51]
	v_mfma_f32_16x16x32_bf16 v[52:55], v[168:171], v[176:179], v[52:55]
	v_mfma_f32_16x16x32_bf16 v[52:55], v[172:175], v[186:189], v[52:55]
	v_mfma_f32_16x16x32_bf16 v[32:35], v[160:163], v[190:193], v[32:35]
	v_mfma_f32_16x16x32_bf16 v[32:35], v[164:167], v[194:197], v[32:35]
	v_mfma_f32_16x16x32_bf16 v[36:39], v[168:171], v[190:193], v[36:39]
	v_mfma_f32_16x16x32_bf16 v[36:39], v[172:175], v[194:197], v[36:39]
	v_mfma_f32_16x16x32_bf16 v[16:19], v[160:163], v[198:201], v[16:19]
	v_mfma_f32_16x16x32_bf16 v[16:19], v[164:167], v[202:205], v[16:19]
	v_mfma_f32_16x16x32_bf16 v[20:23], v[168:171], v[198:201], v[20:23]
	v_mfma_f32_16x16x32_bf16 v[20:23], v[172:175], v[202:205], v[20:23]
	v_mfma_f32_16x16x32_bf16 v[4:7], v[160:163], v[206:209], v[4:7]
	v_mfma_f32_16x16x32_bf16 v[4:7], v[164:167], v[210:213], v[4:7]
	v_mfma_f32_16x16x32_bf16 v[0:3], v[168:171], v[206:209], v[0:3]
	v_mfma_f32_16x16x32_bf16 v[0:3], v[172:175], v[210:213], v[0:3]
	s_barrier
	s_setprio 0
	s_add_i32 s52, 0, 0x18000
	s_add_i32 s53, 0, 0x1c000
	v_add_u32_e32 v156, s52, v181
	v_add_u32_e32 v172, s53, v181
	ds_read_b128 v[128:131], v156
	ds_read_b128 v[132:135], v156 offset:1024
	ds_read_b128 v[152:155], v156 offset:2048
	ds_read_b128 v[156:159], v156 offset:3072
	ds_read_b128 v[160:163], v172
	ds_read_b128 v[164:167], v172 offset:1024
	ds_read_b128 v[168:171], v172 offset:2048
	ds_read_b128 v[172:175], v172 offset:3072
	s_add_u32 s34, s34, 0x200000
	s_addc_u32 s35, s35, 0
	s_mov_b32 m0, s39
	v_lshl_add_u64 v[222:223], s[34:35], 0, v[136:137]
	ds_read_b128 v[176:179], v185 offset:32768
	ds_read_b128 v[186:189], v185 offset:33792
	ds_read_b128 v[190:193], v185 offset:34816
	ds_read_b128 v[194:197], v185 offset:35840
	ds_read_b128 v[198:201], v185 offset:36864
	ds_read_b128 v[202:205], v185 offset:37888
	ds_read_b128 v[206:209], v185 offset:38912
	ds_read_b128 v[210:213], v185 offset:39936
	global_load_lds_dwordx4 v[222:223], off
	v_lshl_add_u64 v[222:223], s[34:35], 0, v[140:141]
	s_mov_b32 m0, s40
	s_nop 0
	global_load_lds_dwordx4 v[222:223], off
	s_waitcnt vmcnt(8)
	s_waitcnt lgkmcnt(0)
	s_setprio 1
	s_barrier
	v_mfma_f32_16x16x32_bf16 v[120:123], v[128:131], v[176:179], v[120:123]
	v_mfma_f32_16x16x32_bf16 v[120:123], v[132:135], v[186:189], v[120:123]
	v_mfma_f32_16x16x32_bf16 v[124:127], v[152:155], v[176:179], v[124:127]
	v_mfma_f32_16x16x32_bf16 v[124:127], v[156:159], v[186:189], v[124:127]
	v_mfma_f32_16x16x32_bf16 v[104:107], v[128:131], v[190:193], v[104:107]
	v_mfma_f32_16x16x32_bf16 v[104:107], v[132:135], v[194:197], v[104:107]
	v_mfma_f32_16x16x32_bf16 v[108:111], v[152:155], v[190:193], v[108:111]
	v_mfma_f32_16x16x32_bf16 v[108:111], v[156:159], v[194:197], v[108:111]
	v_mfma_f32_16x16x32_bf16 v[88:91], v[128:131], v[198:201], v[88:91]
	v_mfma_f32_16x16x32_bf16 v[88:91], v[132:135], v[202:205], v[88:91]
	v_mfma_f32_16x16x32_bf16 v[92:95], v[152:155], v[198:201], v[92:95]
	v_mfma_f32_16x16x32_bf16 v[92:95], v[156:159], v[202:205], v[92:95]
	v_mfma_f32_16x16x32_bf16 v[72:75], v[128:131], v[206:209], v[72:75]
	v_mfma_f32_16x16x32_bf16 v[72:75], v[132:135], v[210:213], v[72:75]
	v_mfma_f32_16x16x32_bf16 v[76:79], v[152:155], v[206:209], v[76:79]
	v_mfma_f32_16x16x32_bf16 v[76:79], v[156:159], v[210:213], v[76:79]
	s_setprio 0
	s_setprio 1
	v_mfma_f32_16x16x32_bf16 v[112:115], v[160:163], v[176:179], v[112:115]
	v_mfma_f32_16x16x32_bf16 v[112:115], v[164:167], v[186:189], v[112:115]
	v_mfma_f32_16x16x32_bf16 v[116:119], v[168:171], v[176:179], v[116:119]
	v_mfma_f32_16x16x32_bf16 v[116:119], v[172:175], v[186:189], v[116:119]
	v_mfma_f32_16x16x32_bf16 v[96:99], v[160:163], v[190:193], v[96:99]
	v_mfma_f32_16x16x32_bf16 v[96:99], v[164:167], v[194:197], v[96:99]
	v_mfma_f32_16x16x32_bf16 v[100:103], v[168:171], v[190:193], v[100:103]
	v_mfma_f32_16x16x32_bf16 v[100:103], v[172:175], v[194:197], v[100:103]
	v_mfma_f32_16x16x32_bf16 v[80:83], v[160:163], v[198:201], v[80:83]
	v_mfma_f32_16x16x32_bf16 v[80:83], v[164:167], v[202:205], v[80:83]
	v_mfma_f32_16x16x32_bf16 v[84:87], v[168:171], v[198:201], v[84:87]
	v_mfma_f32_16x16x32_bf16 v[84:87], v[172:175], v[202:205], v[84:87]
	v_mfma_f32_16x16x32_bf16 v[64:67], v[160:163], v[206:209], v[64:67]
	v_mfma_f32_16x16x32_bf16 v[64:67], v[164:167], v[210:213], v[64:67]
	v_mfma_f32_16x16x32_bf16 v[68:71], v[168:171], v[206:209], v[68:71]
	v_mfma_f32_16x16x32_bf16 v[68:71], v[172:175], v[210:213], v[68:71]
	s_barrier
; #define PG8_STAGE(bufoff, gbase, voff) do { _Pragma("unroll") for (int _i = 0; _i < 2; ++_i) \
;         __builtin_amdgcn_global_load_lds((const unsigned*)((const char*)(gbase) + (voff)[_i]), (LAS unsigned*)(lds + (bufoff) + ldsw + _i * 8192), 16, 0, 0); } while (0)
; #define PG8_LDA(dst, b, h) do { _Pragma("unroll") for (int m = 0; m < 4; ++m) _Pragma("unroll") for (int k = 0; k < 2; ++k) dst[m][k] = *(const LAS bf16x8*)(lds + PG8_SA(b, h) + aoff + m * 2048 + k * 1024); } while (0)
; #define PG8_MMA(ai, bj, At, Bt) do { __builtin_amdgcn_s_setprio(1); _Pragma("unroll") for (int m = 0; m < 4; ++m) _Pragma("unroll") for (int n = 0; n < 2; ++n) _Pragma("unroll") for (int k = 0; k < 2; ++k) \
;         acc[ai][bj][m][n] = __builtin_amdgcn_mfma_f32_16x16x32_bf16(Bt[n][k], At[m][k], acc[ai][bj][m][n], 0, 0, 0); __builtin_amdgcn_s_setprio(0); } while (0)
; #define PG8_WAIT_V(n) asm volatile("s_waitcnt vmcnt(" #n ")" ::: "memory")
; #define PG8_WAIT_L(n) asm volatile("s_waitcnt lgkmcnt(" #n ")" ::: "memory")
; #define PG8_BAR __builtin_amdgcn_s_barrier()
; #define PG8_SCHED __builtin_amdgcn_sched_barrier(0)
; template <class Epi, bool ALIGN_EPI>
; __device__ __forceinline__ void gemm_phase(LAS unsigned char* lds, const Gemm g, const StaticOrder& S, const Epi& E) {
;     ...
;             PG8_WAIT_V(8); PG8_WAIT_L(0); PG8_BAR; PG8_MMA(0, 0, At, B0); PG8_MMA(0, 1, At, B1); PG8_BAR; PG8_SCHED;
;             PG8_LDA(At, 1, 1); PG8_STAGE(PG8_SB(1, 0), b3, voffB); PG8_STAGE(PG8_SB(1, 1), b3 + hB, voffB); PG8_STAGE(PG8_SA(1, 0), a3, voffA);
;             PG8_WAIT_V(8); PG8_WAIT_L(0); PG8_BAR; PG8_MMA(1, 0, At, B0); PG8_MMA(1, 1, At, B1); PG8_BAR; PG8_SCHED;
;         }
;         if constexpr (ALIGN_EPI) { if (wr == 0) PG8_BAR; }
	s_setprio 0
	s_add_i32 s34, s52, s37
	v_lshl_add_u64 v[214:215], v[214:215], 0, s[12:13]
	s_mov_b32 m0, s34
	ds_read_b128 v[176:179], v185 offset:49152
	ds_read_b128 v[186:189], v185 offset:50176
	ds_read_b128 v[190:193], v185 offset:51200
	ds_read_b128 v[194:197], v185 offset:52224
	ds_read_b128 v[198:201], v185 offset:53248
	ds_read_b128 v[202:205], v185 offset:54272
	ds_read_b128 v[206:209], v185 offset:55296
	ds_read_b128 v[210:213], v185 offset:56320
	global_load_lds_dwordx4 v[214:215], off
	s_add_i32 m0, s34, 0x2000
	s_add_u32 s30, s30, 0x200080
	v_lshl_add_u64 v[214:215], v[216:217], 0, s[12:13]
	s_addc_u32 s31, s31, 0
	s_add_i32 s34, s53, s37
	global_load_lds_dwordx4 v[214:215], off
	v_lshl_add_u64 v[214:215], s[30:31], 0, v[138:139]
	s_mov_b32 m0, s34
	s_nop 0
	global_load_lds_dwordx4 v[214:215], off
	v_lshl_add_u64 v[214:215], s[30:31], 0, v[142:143]
	s_add_i32 m0, s34, 0x2000
	s_nop 0
	global_load_lds_dwordx4 v[214:215], off
	v_lshl_add_u64 v[214:215], v[218:219], 0, s[12:13]
	s_mov_b32 m0, s44
	s_nop 0
	global_load_lds_dwordx4 v[214:215], off
	v_lshl_add_u64 v[214:215], v[220:221], 0, s[12:13]
	s_mov_b32 m0, s45
	s_nop 0
	global_load_lds_dwordx4 v[214:215], off
	s_waitcnt vmcnt(8)
	s_waitcnt lgkmcnt(0)
	s_setprio 1
	s_barrier
	v_mfma_f32_16x16x32_bf16 v[56:59], v[128:131], v[176:179], v[56:59]
	v_mfma_f32_16x16x32_bf16 v[56:59], v[132:135], v[186:189], v[56:59]
	v_mfma_f32_16x16x32_bf16 v[60:63], v[152:155], v[176:179], v[60:63]
	v_mfma_f32_16x16x32_bf16 v[60:63], v[156:159], v[186:189], v[60:63]
	v_mfma_f32_16x16x32_bf16 v[40:43], v[128:131], v[190:193], v[40:43]
	v_mfma_f32_16x16x32_bf16 v[40:43], v[132:135], v[194:197], v[40:43]
	v_mfma_f32_16x16x32_bf16 v[44:47], v[152:155], v[190:193], v[44:47]
	v_mfma_f32_16x16x32_bf16 v[44:47], v[156:159], v[194:197], v[44:47]
	v_mfma_f32_16x16x32_bf16 v[24:27], v[128:131], v[198:201], v[24:27]
	v_mfma_f32_16x16x32_bf16 v[24:27], v[132:135], v[202:205], v[24:27]
	v_mfma_f32_16x16x32_bf16 v[28:31], v[152:155], v[198:201], v[28:31]
	v_mfma_f32_16x16x32_bf16 v[28:31], v[156:159], v[202:205], v[28:31]
	v_mfma_f32_16x16x32_bf16 v[8:11], v[128:131], v[206:209], v[8:11]
	v_mfma_f32_16x16x32_bf16 v[8:11], v[132:135], v[210:213], v[8:11]
	v_mfma_f32_16x16x32_bf16 v[12:15], v[152:155], v[206:209], v[12:15]
	v_mfma_f32_16x16x32_bf16 v[12:15], v[156:159], v[210:213], v[12:15]
	s_setprio 0
	s_setprio 1
	v_mfma_f32_16x16x32_bf16 v[48:51], v[160:163], v[176:179], v[48:51]
	v_mfma_f32_16x16x32_bf16 v[48:51], v[164:167], v[186:189], v[48:51]
	v_mfma_f32_16x16x32_bf16 v[52:55], v[168:171], v[176:179], v[52:55]
	v_mfma_f32_16x16x32_bf16 v[52:55], v[172:175], v[186:189], v[52:55]
	v_mfma_f32_16x16x32_bf16 v[32:35], v[160:163], v[190:193], v[32:35]
	v_mfma_f32_16x16x32_bf16 v[32:35], v[164:167], v[194:197], v[32:35]
	v_mfma_f32_16x16x32_bf16 v[36:39], v[168:171], v[190:193], v[36:39]
	v_mfma_f32_16x16x32_bf16 v[36:39], v[172:175], v[194:197], v[36:39]
	v_mfma_f32_16x16x32_bf16 v[16:19], v[160:163], v[198:201], v[16:19]
	v_mfma_f32_16x16x32_bf16 v[16:19], v[164:167], v[202:205], v[16:19]
	v_mfma_f32_16x16x32_bf16 v[20:23], v[168:171], v[198:201], v[20:23]
	v_mfma_f32_16x16x32_bf16 v[20:23], v[172:175], v[202:205], v[20:23]
	v_mfma_f32_16x16x32_bf16 v[4:7], v[160:163], v[206:209], v[4:7]
	v_mfma_f32_16x16x32_bf16 v[4:7], v[164:167], v[210:213], v[4:7]
	v_mfma_f32_16x16x32_bf16 v[0:3], v[168:171], v[206:209], v[0:3]
	v_mfma_f32_16x16x32_bf16 v[0:3], v[172:175], v[210:213], v[0:3]
	s_barrier
	s_setprio 0
	s_add_i32 s51, s51, 2
	s_add_u32 s28, s28, 0x100
	s_addc_u32 s29, s29, 0
	s_add_u32 s49, s49, 0x100
	s_addc_u32 s50, s50, 0
	s_cmpk_gt_u32 s51, 0x7d
	s_cbranch_scc0 .LBB0_1755
	s_and_b64 vcc, exec, s[14:15]
	s_cbranch_vccz .LBB0_1758
	s_barrier
